# v82 + accumulator-stationary MFMA order (both k-half MFMAs of an accumulator back to back, then operand-sharing order) in the 32-MFMA blocks
# speedup vs baseline: 1.0075x; 1.0071x over previous
; #define PG8_STAGE(bufoff, gbase, voff) do { _Pragma("unroll") for (int _i = 0; _i < 2; ++_i) \
;         __builtin_amdgcn_global_load_lds((const unsigned*)((const char*)(gbase) + (voff)[_i]), (PG8_LAS unsigned*)(lds + (bufoff) + ldsw + _i * 8192), 16, 0, 0); } while (0)
; #define PG8_LDA(dst, b, h) do { _Pragma("unroll") for (int m = 0; m < 4; ++m) _Pragma("unroll") for (int k = 0; k < 2; ++k) dst[m][k] = *(const PG8_LAS bf16x8*)(lds + PG8_SA(b, h) + aoff + m * 2048 + k * 1024); } while (0)
; #define PG8_LDB(dst, b, h) do { _Pragma("unroll") for (int n = 0; n < 2; ++n) _Pragma("unroll") for (int k = 0; k < 2; ++k) dst[n][k] = *(const PG8_LAS bf16x8*)(lds + PG8_SB(b, h) + boff + n * 2048 + k * 1024); } while (0)
; #define PG8_MMA(ai, bj, At, Bt) do { __builtin_amdgcn_s_setprio(1); _Pragma("unroll") for (int m = 0; m < 4; ++m) _Pragma("unroll") for (int n = 0; n < 2; ++n) _Pragma("unroll") for (int k = 0; k < 2; ++k) \
;         acc[ai][bj][m][n] = mma16<Epi::I8>(Bt[n][k], At[m][k], acc[ai][bj][m][n]); __builtin_amdgcn_s_setprio(0); } while (0)
; #define PG8_WAIT_V(n) asm volatile("s_waitcnt vmcnt(" #n ")" ::: "memory")
; #define PG8_WAIT_L(n) asm volatile("s_waitcnt lgkmcnt(" #n ")" ::: "memory")
; #define PG8_BAR __builtin_amdgcn_s_barrier()
; #define PG8_SCHED __builtin_amdgcn_sched_barrier(0)
; template <class Epi, class Sched, bool ALIGN_EPI = false, bool SP2 = false>
; __device__ __forceinline__ void gemm_phase(PG8_LAS unsigned char* lds, const Gemm g, const Sched& S, const Epi& E) {
;     ...
;             const char* a1 = cA + (size_t)(t + 1) * kstep;
;             const char* a2 = last ? nA : cA + (size_t)(t + 2) * kstep; const char* b2 = last ? nB : cB + (size_t)(t + 2) * kstep;
;             const char* a3 = a2 + kstep; const char* b3 = b2 + kstep;
;             if (last && has_next) S.a_ready(nxt);
;             if constexpr (SP2) {
;             PG8_LDB(B0, 0, 0); PG8_LDB(B1, 0, 1); PG8_SCHED; PG8_LDA(At, 0, 0); PG8_STAGE(PG8_SA(1, 1), a1 + hstep, voffA);
;             PG8_WAIT_V(8); PG8_WAIT_L(0); PG8_BAR; PG8_MMA(0, 0, At, B0); PG8_MMA(0, 1, At, B1); PG8_BAR; PG8_SCHED;
;             PG8_LDA(At, 0, 1); PG8_STAGE(PG8_SB(0, 0), b2, voffB); PG8_STAGE(PG8_SB(0, 1), b2 + hstep, voffB); PG8_STAGE(PG8_SA(0, 0), a2, voffA);
;             PG8_WAIT_V(8); PG8_WAIT_L(0); PG8_BAR; PG8_MMA(1, 0, At, B0); PG8_MMA(1, 1, At, B1); PG8_BAR; PG8_SCHED;
.Lpeel80:
	s_add_u32 s8, s0, 0x100
	s_addc_u32 s9, s1, 0
	s_add_i32 vcc_hi, 0, 0x10000
	s_cmp_eq_u32 vcc_lo, 12
	s_cselect_b32 s13, s66, s9
	s_cselect_b32 s12, s67, s8
	s_cselect_b32 s7, s82, s97
	s_cselect_b32 s6, s83, s96
	s_add_i32 s4, 0, 0x14000
	v_add_u32_e32 v38, vcc_hi, v242
	v_add_u32_e32 v158, s4, v242
	ds_read_b128 v[18:21], v38
	ds_read_b128 v[22:25], v38 offset:1024
	ds_read_b128 v[34:37], v38 offset:2048
	ds_read_b128 v[38:41], v38 offset:3072
	ds_read_b128 v[130:133], v158
	ds_read_b128 v[134:137], v158 offset:1024
	ds_read_b128 v[154:157], v158 offset:2048
	ds_read_b128 v[158:161], v158 offset:3072
	s_add_i32 m0, s11, 0xc000
	ds_read_b128 v[162:165], v243
	ds_read_b128 v[166:169], v243 offset:1024
	ds_read_b128 v[170:173], v243 offset:2048
	ds_read_b128 v[174:177], v243 offset:3072
	ds_read_b128 v[178:181], v243 offset:4096
	ds_read_b128 v[182:185], v243 offset:5120
	ds_read_b128 v[186:189], v243 offset:6144
	ds_read_b128 v[190:193], v243 offset:7168
	global_load_lds_dwordx4 v216, s[0:1]
	s_add_i32 m0, s11, 0xe000
	s_nop 0
	global_load_lds_dwordx4 v218, s[0:1]
	s_waitcnt vmcnt(8)
	s_waitcnt lgkmcnt(0)
	s_barrier
	s_waitcnt lgkmcnt(0)
	v_mfma_i32_16x16x64_i8 v[150:153], v[18:21], v[162:165], 0
	v_mfma_i32_16x16x64_i8 v[150:153], v[22:25], v[166:169], v[150:153]
	v_mfma_i32_16x16x64_i8 v[146:149], v[34:37], v[162:165], 0
	v_mfma_i32_16x16x64_i8 v[146:149], v[38:41], v[166:169], v[146:149]
	v_mfma_i32_16x16x64_i8 v[110:113], v[34:37], v[170:173], 0
	v_mfma_i32_16x16x64_i8 v[110:113], v[38:41], v[174:177], v[110:113]
	v_mfma_i32_16x16x64_i8 v[118:121], v[18:21], v[170:173], 0
	v_mfma_i32_16x16x64_i8 v[118:121], v[22:25], v[174:177], v[118:121]
	v_mfma_i32_16x16x64_i8 v[54:57], v[18:21], v[178:181], 0
	v_mfma_i32_16x16x64_i8 v[54:57], v[22:25], v[182:185], v[54:57]
	v_mfma_i32_16x16x64_i8 v[30:33], v[34:37], v[178:181], 0
	v_mfma_i32_16x16x64_i8 v[30:33], v[38:41], v[182:185], v[30:33]
	v_mfma_i32_16x16x64_i8 v[58:61], v[34:37], v[186:189], 0
	v_mfma_i32_16x16x64_i8 v[58:61], v[38:41], v[190:193], v[58:61]
	v_mfma_i32_16x16x64_i8 v[94:97], v[18:21], v[186:189], 0
	v_mfma_i32_16x16x64_i8 v[94:97], v[22:25], v[190:193], v[94:97]
	v_mfma_i32_16x16x64_i8 v[142:145], v[130:133], v[162:165], 0
	v_mfma_i32_16x16x64_i8 v[142:145], v[134:137], v[166:169], v[142:145]
	v_mfma_i32_16x16x64_i8 v[138:141], v[154:157], v[162:165], 0
	v_mfma_i32_16x16x64_i8 v[138:141], v[158:161], v[166:169], v[138:141]
	v_mfma_i32_16x16x64_i8 v[98:101], v[154:157], v[170:173], 0
	v_mfma_i32_16x16x64_i8 v[98:101], v[158:161], v[174:177], v[98:101]
	v_mfma_i32_16x16x64_i8 v[102:105], v[130:133], v[170:173], 0
	v_mfma_i32_16x16x64_i8 v[102:105], v[134:137], v[174:177], v[102:105]
	v_mfma_i32_16x16x64_i8 v[42:45], v[130:133], v[178:181], 0
	v_mfma_i32_16x16x64_i8 v[42:45], v[134:137], v[182:185], v[42:45]
	v_mfma_i32_16x16x64_i8 v[26:29], v[154:157], v[178:181], 0
	v_mfma_i32_16x16x64_i8 v[26:29], v[158:161], v[182:185], v[26:29]
	v_mfma_i32_16x16x64_i8 v[62:65], v[154:157], v[186:189], 0
	v_mfma_i32_16x16x64_i8 v[62:65], v[158:161], v[190:193], v[62:65]
	v_mfma_i32_16x16x64_i8 v[78:81], v[130:133], v[186:189], 0
	v_mfma_i32_16x16x64_i8 v[78:81], v[134:137], v[190:193], v[78:81]
	s_barrier
	s_add_i32 s0, vcc_hi, s69
	v_lshl_add_u64 v[198:199], s[6:7], 0, v[0:1]
	s_mov_b32 m0, s0
	ds_read_b128 v[162:165], v243 offset:16384
	ds_read_b128 v[166:169], v243 offset:17408
	ds_read_b128 v[170:173], v243 offset:18432
	ds_read_b128 v[174:177], v243 offset:19456
	ds_read_b128 v[178:181], v243 offset:20480
	ds_read_b128 v[182:185], v243 offset:21504
	ds_read_b128 v[186:189], v243 offset:22528
	ds_read_b128 v[190:193], v243 offset:23552
	global_load_lds_dwordx4 v[198:199], off
	s_add_i32 m0, s0, 0x2000
	s_add_u32 s0, s6, 0x40000
	v_lshl_add_u64 v[200:201], s[6:7], 0, v[214:215]
	s_addc_u32 s1, s7, 0
	s_add_i32 s4, s4, s69
	global_load_lds_dwordx4 v[200:201], off
	s_mov_b32 m0, s4
	v_lshl_add_u64 v[206:207], s[12:13], 0, v[210:211]
	global_load_lds_dwordx4 v0, s[0:1]
	s_add_i32 m0, s4, 0x2000
	v_lshl_add_u64 v[220:221], s[12:13], 0, v[212:213]
	global_load_lds_dwordx4 v214, s[0:1]
	s_mov_b32 m0, s11
	s_nop 0
	global_load_lds_dwordx4 v[206:207], off
	s_mov_b32 m0, s71
	s_nop 0
	global_load_lds_dwordx4 v[220:221], off
	s_waitcnt vmcnt(8)
	s_waitcnt lgkmcnt(0)
	s_barrier
	s_waitcnt lgkmcnt(0)
	v_mfma_i32_16x16x64_i8 v[106:109], v[18:21], v[162:165], 0
	v_mfma_i32_16x16x64_i8 v[106:109], v[22:25], v[166:169], v[106:109]
	v_mfma_i32_16x16x64_i8 v[46:49], v[34:37], v[162:165], 0
	v_mfma_i32_16x16x64_i8 v[46:49], v[38:41], v[166:169], v[46:49]
	v_mfma_i32_16x16x64_i8 v[6:9], v[34:37], v[170:173], 0
	v_mfma_i32_16x16x64_i8 v[6:9], v[38:41], v[174:177], v[6:9]
	v_mfma_i32_16x16x64_i8 v[14:17], v[18:21], v[170:173], 0
	v_mfma_i32_16x16x64_i8 v[14:17], v[22:25], v[174:177], v[14:17]
	v_mfma_i32_16x16x64_i8 v[90:93], v[18:21], v[178:181], 0
	v_mfma_i32_16x16x64_i8 v[90:93], v[22:25], v[182:185], v[90:93]
	v_mfma_i32_16x16x64_i8 v[86:89], v[34:37], v[178:181], 0
	v_mfma_i32_16x16x64_i8 v[86:89], v[38:41], v[182:185], v[86:89]
	v_mfma_i32_16x16x64_i8 v[18:21], v[18:21], v[186:189], 0
	v_mfma_i32_16x16x64_i8 v[18:21], v[22:25], v[190:193], v[18:21]
	v_mfma_i32_16x16x64_i8 v[22:25], v[34:37], v[186:189], 0
	v_mfma_i32_16x16x64_i8 v[22:25], v[38:41], v[190:193], v[22:25]
	v_mfma_i32_16x16x64_i8 v[38:41], v[154:157], v[162:165], 0
	v_mfma_i32_16x16x64_i8 v[38:41], v[158:161], v[166:169], v[38:41]
	v_mfma_i32_16x16x64_i8 v[2:5], v[154:157], v[170:173], 0
	v_mfma_i32_16x16x64_i8 v[2:5], v[158:161], v[174:177], v[2:5]
	v_mfma_i32_16x16x64_i8 v[10:13], v[130:133], v[170:173], 0
	v_mfma_i32_16x16x64_i8 v[10:13], v[134:137], v[174:177], v[10:13]
	v_mfma_i32_16x16x64_i8 v[50:53], v[130:133], v[178:181], 0
	v_mfma_i32_16x16x64_i8 v[82:85], v[134:137], v[182:185], v[50:53]
	v_mfma_i32_16x16x64_i8 v[34:37], v[130:133], v[162:165], 0
	v_mfma_i32_16x16x64_i8 v[34:37], v[134:137], v[166:169], v[34:37]
	v_mfma_i32_16x16x64_i8 v[50:53], v[154:157], v[178:181], 0
	v_mfma_i32_16x16x64_i8 v[74:77], v[158:161], v[182:185], v[50:53]
	v_mfma_i32_16x16x64_i8 v[50:53], v[130:133], v[186:189], 0
	v_mfma_i32_16x16x64_i8 v[122:125], v[134:137], v[190:193], v[50:53]
	v_mfma_i32_16x16x64_i8 v[50:53], v[154:157], v[186:189], 0
	v_mfma_i32_16x16x64_i8 v[70:73], v[158:161], v[190:193], v[50:53]
	s_barrier
; #define PG8_STAGE(bufoff, gbase, voff) do { _Pragma("unroll") for (int _i = 0; _i < 2; ++_i) \
;         __builtin_amdgcn_global_load_lds((const unsigned*)((const char*)(gbase) + (voff)[_i]), (PG8_LAS unsigned*)(lds + (bufoff) + ldsw + _i * 8192), 16, 0, 0); } while (0)
; #define PG8_LDA(dst, b, h) do { _Pragma("unroll") for (int m = 0; m < 4; ++m) _Pragma("unroll") for (int k = 0; k < 2; ++k) dst[m][k] = *(const PG8_LAS bf16x8*)(lds + PG8_SA(b, h) + aoff + m * 2048 + k * 1024); } while (0)
; #define PG8_LDB(dst, b, h) do { _Pragma("unroll") for (int n = 0; n < 2; ++n) _Pragma("unroll") for (int k = 0; k < 2; ++k) dst[n][k] = *(const PG8_LAS bf16x8*)(lds + PG8_SB(b, h) + boff + n * 2048 + k * 1024); } while (0)
; #define PG8_MMA(ai, bj, At, Bt) do { __builtin_amdgcn_s_setprio(1); _Pragma("unroll") for (int m = 0; m < 4; ++m) _Pragma("unroll") for (int n = 0; n < 2; ++n) _Pragma("unroll") for (int k = 0; k < 2; ++k) \
;         acc[ai][bj][m][n] = mma16<Epi::I8>(Bt[n][k], At[m][k], acc[ai][bj][m][n]); __builtin_amdgcn_s_setprio(0); } while (0)
; #define PG8_WAIT_V(n) asm volatile("s_waitcnt vmcnt(" #n ")" ::: "memory")
; #define PG8_WAIT_L(n) asm volatile("s_waitcnt lgkmcnt(" #n ")" ::: "memory")
; #define PG8_BAR __builtin_amdgcn_s_barrier()
; #define PG8_SCHED __builtin_amdgcn_sched_barrier(0)
; template <class Epi, class Sched, bool ALIGN_EPI = false, bool SP2 = false>
; __device__ __forceinline__ void gemm_phase(PG8_LAS unsigned char* lds, const Gemm g, const Sched& S, const Epi& E) {
;     ...
;             PG8_LDB(B0, 1, 0); PG8_LDB(B1, 1, 1); PG8_SCHED; PG8_LDA(At, 1, 0); PG8_STAGE(PG8_SA(0, 1), a2 + hstep, voffA);
;             PG8_WAIT_V(8); PG8_WAIT_L(0); PG8_BAR; PG8_MMA(0, 0, At, B0); PG8_MMA(0, 1, At, B1); PG8_BAR; PG8_SCHED;
;             PG8_LDA(At, 1, 1); PG8_STAGE(PG8_SB(1, 0), b3, voffB); PG8_STAGE(PG8_SB(1, 1), b3 + hstep, voffB); PG8_STAGE(PG8_SA(1, 0), a3, voffA);
;             PG8_WAIT_V(8); PG8_WAIT_L(0); PG8_BAR; PG8_MMA(1, 0, At, B0); PG8_MMA(1, 1, At, B1); PG8_BAR; PG8_SCHED;
	s_add_i32 s4, 0, 0x18000
	v_add_u32_e32 v126, s4, v242
	s_add_i32 s5, 0, 0x1c000
	ds_read_b128 v[50:53], v126
	ds_read_b128 v[66:69], v126 offset:1024
	ds_read_b128 v[114:117], v126 offset:2048
	ds_read_b128 v[130:133], v126 offset:3072
	v_add_u32_e32 v126, s5, v242
	ds_read_b128 v[134:137], v126
	ds_read_b128 v[154:157], v126 offset:1024
	ds_read_b128 v[158:161], v126 offset:2048
	ds_read_b128 v[162:165], v126 offset:3072
	s_add_u32 s0, s12, 0x40000
	s_addc_u32 s1, s13, 0
	s_mov_b32 m0, s80
	ds_read_b128 v[126:129], v243 offset:32768
	ds_read_b128 v[166:169], v243 offset:33792
	ds_read_b128 v[170:173], v243 offset:34816
	ds_read_b128 v[174:177], v243 offset:35840
	ds_read_b128 v[178:181], v243 offset:36864
	ds_read_b128 v[182:185], v243 offset:37888
	ds_read_b128 v[186:189], v243 offset:38912
	ds_read_b128 v[190:193], v243 offset:39936
	global_load_lds_dwordx4 v210, s[0:1]
	s_mov_b32 m0, s81
	s_nop 0
	global_load_lds_dwordx4 v212, s[0:1]
	s_waitcnt vmcnt(8)
	s_waitcnt lgkmcnt(0)
	s_barrier
	s_waitcnt lgkmcnt(0)
	v_mfma_i32_16x16x64_i8 v[150:153], v[50:53], v[126:129], v[150:153]
	v_mfma_i32_16x16x64_i8 v[150:153], v[66:69], v[166:169], v[150:153]
	v_mfma_i32_16x16x64_i8 v[146:149], v[114:117], v[126:129], v[146:149]
	v_mfma_i32_16x16x64_i8 v[146:149], v[130:133], v[166:169], v[146:149]
	v_mfma_i32_16x16x64_i8 v[110:113], v[114:117], v[170:173], v[110:113]
	v_mfma_i32_16x16x64_i8 v[110:113], v[130:133], v[174:177], v[110:113]
	v_mfma_i32_16x16x64_i8 v[118:121], v[50:53], v[170:173], v[118:121]
	v_mfma_i32_16x16x64_i8 v[118:121], v[66:69], v[174:177], v[118:121]
	v_mfma_i32_16x16x64_i8 v[54:57], v[50:53], v[178:181], v[54:57]
	v_mfma_i32_16x16x64_i8 v[54:57], v[66:69], v[182:185], v[54:57]
	v_mfma_i32_16x16x64_i8 v[30:33], v[114:117], v[178:181], v[30:33]
	v_mfma_i32_16x16x64_i8 v[30:33], v[130:133], v[182:185], v[30:33]
	v_mfma_i32_16x16x64_i8 v[58:61], v[114:117], v[186:189], v[58:61]
	v_mfma_i32_16x16x64_i8 v[58:61], v[130:133], v[190:193], v[58:61]
	v_mfma_i32_16x16x64_i8 v[94:97], v[50:53], v[186:189], v[94:97]
	v_mfma_i32_16x16x64_i8 v[94:97], v[66:69], v[190:193], v[94:97]
	v_mfma_i32_16x16x64_i8 v[142:145], v[134:137], v[126:129], v[142:145]
	v_mfma_i32_16x16x64_i8 v[142:145], v[154:157], v[166:169], v[142:145]
	v_mfma_i32_16x16x64_i8 v[126:129], v[158:161], v[126:129], v[138:141]
	v_mfma_i32_16x16x64_i8 v[138:141], v[162:165], v[166:169], v[126:129]
	v_mfma_i32_16x16x64_i8 v[98:101], v[158:161], v[170:173], v[98:101]
	v_mfma_i32_16x16x64_i8 v[98:101], v[162:165], v[174:177], v[98:101]
	v_mfma_i32_16x16x64_i8 v[102:105], v[134:137], v[170:173], v[102:105]
	v_mfma_i32_16x16x64_i8 v[102:105], v[154:157], v[174:177], v[102:105]
	v_mfma_i32_16x16x64_i8 v[42:45], v[134:137], v[178:181], v[42:45]
	v_mfma_i32_16x16x64_i8 v[42:45], v[154:157], v[182:185], v[42:45]
	v_mfma_i32_16x16x64_i8 v[26:29], v[158:161], v[178:181], v[26:29]
	v_mfma_i32_16x16x64_i8 v[26:29], v[162:165], v[182:185], v[26:29]
	v_mfma_i32_16x16x64_i8 v[62:65], v[158:161], v[186:189], v[62:65]
	v_mfma_i32_16x16x64_i8 v[62:65], v[162:165], v[190:193], v[62:65]
	v_mfma_i32_16x16x64_i8 v[78:81], v[134:137], v[186:189], v[78:81]
	v_mfma_i32_16x16x64_i8 v[78:81], v[154:157], v[190:193], v[78:81]
	s_barrier
	s_add_i32 s0, s4, s69
	v_lshl_add_u64 v[126:127], v[198:199], 0, s[92:93]
	s_mov_b32 m0, s0
	ds_read_b128 v[166:169], v243 offset:49152
	ds_read_b128 v[170:173], v243 offset:50176
	ds_read_b128 v[174:177], v243 offset:51200
	ds_read_b128 v[178:181], v243 offset:52224
	ds_read_b128 v[182:185], v243 offset:53248
	ds_read_b128 v[186:189], v243 offset:54272
	ds_read_b128 v[190:193], v243 offset:55296
	ds_read_b128 v[194:197], v243 offset:56320
	global_load_lds_dwordx4 v[126:127], off
	s_add_i32 m0, s0, 0x2000
	s_add_u32 s0, s6, 0x40080
	v_lshl_add_u64 v[126:127], v[200:201], 0, s[92:93]
	s_addc_u32 s1, s7, 0
	s_add_i32 s4, s5, s69
	global_load_lds_dwordx4 v[126:127], off
	s_mov_b32 m0, s4
	s_nop 0
	global_load_lds_dwordx4 v0, s[0:1]
	s_add_i32 m0, s4, 0x2000
	s_nop 0
	global_load_lds_dwordx4 v214, s[0:1]
	v_lshl_add_u64 v[126:127], v[206:207], 0, s[92:93]
	s_mov_b32 m0, s84
	s_nop 0
	global_load_lds_dwordx4 v[126:127], off
	v_lshl_add_u64 v[126:127], v[220:221], 0, s[92:93]
	s_mov_b32 m0, s85
	s_nop 0
	global_load_lds_dwordx4 v[126:127], off
	s_waitcnt vmcnt(8)
	s_waitcnt lgkmcnt(0)
	s_barrier
	s_waitcnt lgkmcnt(0)
	v_mfma_i32_16x16x64_i8 v[18:21], v[50:53], v[190:193], v[18:21]
	v_mfma_i32_16x16x64_i8 v[126:129], v[66:69], v[194:197], v[18:21]
	v_mfma_i32_16x16x64_i8 v[106:109], v[50:53], v[166:169], v[106:109]
	v_mfma_i32_16x16x64_i8 v[106:109], v[66:69], v[170:173], v[106:109]
	v_mfma_i32_16x16x64_i8 v[46:49], v[114:117], v[166:169], v[46:49]
	v_mfma_i32_16x16x64_i8 v[46:49], v[130:133], v[170:173], v[46:49]
	v_mfma_i32_16x16x64_i8 v[6:9], v[114:117], v[174:177], v[6:9]
	v_mfma_i32_16x16x64_i8 v[6:9], v[130:133], v[178:181], v[6:9]
	v_mfma_i32_16x16x64_i8 v[14:17], v[50:53], v[174:177], v[14:17]
	v_mfma_i32_16x16x64_i8 v[14:17], v[66:69], v[178:181], v[14:17]
	v_mfma_i32_16x16x64_i8 v[90:93], v[50:53], v[182:185], v[90:93]
	v_mfma_i32_16x16x64_i8 v[90:93], v[66:69], v[186:189], v[90:93]
	v_mfma_i32_16x16x64_i8 v[86:89], v[114:117], v[182:185], v[86:89]
	v_mfma_i32_16x16x64_i8 v[86:89], v[130:133], v[186:189], v[86:89]
	v_mfma_i32_16x16x64_i8 v[18:21], v[114:117], v[190:193], v[22:25]
	v_mfma_i32_16x16x64_i8 v[66:69], v[130:133], v[194:197], v[18:21]
	v_mfma_i32_16x16x64_i8 v[18:21], v[134:137], v[166:169], v[34:37]
	v_mfma_i32_16x16x64_i8 v[114:117], v[154:157], v[170:173], v[18:21]
	v_mfma_i32_16x16x64_i8 v[10:13], v[134:137], v[174:177], v[10:13]
	v_mfma_i32_16x16x64_i8 v[10:13], v[154:157], v[178:181], v[10:13]
	v_mfma_i32_16x16x64_i8 v[2:5], v[158:161], v[174:177], v[2:5]
	v_mfma_i32_16x16x64_i8 v[2:5], v[162:165], v[178:181], v[2:5]
	v_mfma_i32_16x16x64_i8 v[18:21], v[158:161], v[166:169], v[38:41]
	v_mfma_i32_16x16x64_i8 v[50:53], v[162:165], v[170:173], v[18:21]
	v_mfma_i32_16x16x64_i8 v[18:21], v[134:137], v[182:185], v[82:85]
	v_mfma_i32_16x16x64_i8 v[82:85], v[154:157], v[186:189], v[18:21]
	v_mfma_i32_16x16x64_i8 v[18:21], v[158:161], v[182:185], v[74:77]
	v_mfma_i32_16x16x64_i8 v[74:77], v[162:165], v[186:189], v[18:21]
	v_mfma_i32_16x16x64_i8 v[18:21], v[134:137], v[190:193], v[122:125]
	v_mfma_i32_16x16x64_i8 v[122:125], v[154:157], v[194:197], v[18:21]
	v_mfma_i32_16x16x64_i8 v[18:21], v[158:161], v[190:193], v[70:73]
	v_mfma_i32_16x16x64_i8 v[70:73], v[162:165], v[194:197], v[18:21]
	s_barrier
	s_add_i32 vcc_lo, vcc_lo, 2
	s_add_u32 s96, s96, 0x100
	s_addc_u32 s97, s97, 0
	s_cmp_gt_u32 vcc_lo, 13
	s_mov_b64 s[0:1], s[8:9]
	s_cbranch_scc0 .LBB0_80
	s_branch .Lpeelx80
; #define PG8_STAGE(bufoff, gbase, voff) do { _Pragma("unroll") for (int _i = 0; _i < 2; ++_i) \
;         __builtin_amdgcn_global_load_lds((const unsigned*)((const char*)(gbase) + (voff)[_i]), (PG8_LAS unsigned*)(lds + (bufoff) + ldsw + _i * 8192), 16, 0, 0); } while (0)
; #define PG8_LDA(dst, b, h) do { _Pragma("unroll") for (int m = 0; m < 4; ++m) _Pragma("unroll") for (int k = 0; k < 2; ++k) dst[m][k] = *(const PG8_LAS bf16x8*)(lds + PG8_SA(b, h) + aoff + m * 2048 + k * 1024); } while (0)
; #define PG8_LDB(dst, b, h) do { _Pragma("unroll") for (int n = 0; n < 2; ++n) _Pragma("unroll") for (int k = 0; k < 2; ++k) dst[n][k] = *(const PG8_LAS bf16x8*)(lds + PG8_SB(b, h) + boff + n * 2048 + k * 1024); } while (0)
; #define PG8_MMA(ai, bj, At, Bt) do { __builtin_amdgcn_s_setprio(1); _Pragma("unroll") for (int m = 0; m < 4; ++m) _Pragma("unroll") for (int n = 0; n < 2; ++n) _Pragma("unroll") for (int k = 0; k < 2; ++k) \
;         acc[ai][bj][m][n] = mma16<Epi::I8>(Bt[n][k], At[m][k], acc[ai][bj][m][n]); __builtin_amdgcn_s_setprio(0); } while (0)
; #define PG8_WAIT_V(n) asm volatile("s_waitcnt vmcnt(" #n ")" ::: "memory")
; #define PG8_WAIT_L(n) asm volatile("s_waitcnt lgkmcnt(" #n ")" ::: "memory")
; #define PG8_BAR __builtin_amdgcn_s_barrier()
; #define PG8_SCHED __builtin_amdgcn_sched_barrier(0)
; template <class Epi, class Sched, bool ALIGN_EPI = false, bool SP2 = false>
; __device__ __forceinline__ void gemm_phase(PG8_LAS unsigned char* lds, const Gemm g, const Sched& S, const Epi& E) {
;     ...
;             const char* a1 = cA + (size_t)(t + 1) * kstep;
;             const char* a2 = last ? nA : cA + (size_t)(t + 2) * kstep; const char* b2 = last ? nB : cB + (size_t)(t + 2) * kstep;
;             const char* a3 = a2 + kstep; const char* b3 = b2 + kstep;
;             if (last && has_next) S.a_ready(nxt);
;             if constexpr (SP2) {
;             PG8_LDB(B0, 0, 0); PG8_LDB(B1, 0, 1); PG8_SCHED; PG8_LDA(At, 0, 0); PG8_STAGE(PG8_SA(1, 1), a1 + hstep, voffA);
;             PG8_WAIT_V(8); PG8_WAIT_L(0); PG8_BAR; PG8_MMA(0, 0, At, B0); PG8_MMA(0, 1, At, B1); PG8_BAR; PG8_SCHED;
;             PG8_LDA(At, 0, 1); PG8_STAGE(PG8_SB(0, 0), b2, voffB); PG8_STAGE(PG8_SB(0, 1), b2 + hstep, voffB); PG8_STAGE(PG8_SA(0, 0), a2, voffA);
;             PG8_WAIT_V(8); PG8_WAIT_L(0); PG8_BAR; PG8_MMA(1, 0, At, B0); PG8_MMA(1, 1, At, B1); PG8_BAR; PG8_SCHED;
.LBB0_80:
	s_add_u32 s8, s0, 0x100
	s_addc_u32 s9, s1, 0
	s_add_i32 vcc_hi, 0, 0x10000
	s_cmp_eq_u32 vcc_lo, 12
	s_cselect_b32 s13, s66, s9
	s_cselect_b32 s12, s67, s8
	s_cselect_b32 s7, s82, s97
	s_cselect_b32 s6, s83, s96
	s_add_i32 s4, 0, 0x14000
	v_add_u32_e32 v38, vcc_hi, v242
	v_add_u32_e32 v158, s4, v242
	ds_read_b128 v[18:21], v38
	ds_read_b128 v[22:25], v38 offset:1024
	ds_read_b128 v[34:37], v38 offset:2048
	ds_read_b128 v[38:41], v38 offset:3072
	ds_read_b128 v[130:133], v158
	ds_read_b128 v[134:137], v158 offset:1024
	ds_read_b128 v[154:157], v158 offset:2048
	ds_read_b128 v[158:161], v158 offset:3072
	s_add_i32 m0, s11, 0xc000
	ds_read_b128 v[162:165], v243
	ds_read_b128 v[166:169], v243 offset:1024
	ds_read_b128 v[170:173], v243 offset:2048
	ds_read_b128 v[174:177], v243 offset:3072
	ds_read_b128 v[178:181], v243 offset:4096
	ds_read_b128 v[182:185], v243 offset:5120
	ds_read_b128 v[186:189], v243 offset:6144
	ds_read_b128 v[190:193], v243 offset:7168
	global_load_lds_dwordx4 v216, s[0:1]
	s_add_i32 m0, s11, 0xe000
	s_nop 0
	global_load_lds_dwordx4 v218, s[0:1]
	s_waitcnt vmcnt(8)
	s_waitcnt lgkmcnt(0)
	s_barrier
	s_waitcnt lgkmcnt(0)
	v_mfma_i32_16x16x64_i8 v[150:153], v[18:21], v[162:165], v[150:153]
	v_mfma_i32_16x16x64_i8 v[150:153], v[22:25], v[166:169], v[150:153]
	v_mfma_i32_16x16x64_i8 v[146:149], v[34:37], v[162:165], v[146:149]
	v_mfma_i32_16x16x64_i8 v[146:149], v[38:41], v[166:169], v[146:149]
	v_mfma_i32_16x16x64_i8 v[110:113], v[34:37], v[170:173], v[110:113]
	v_mfma_i32_16x16x64_i8 v[110:113], v[38:41], v[174:177], v[110:113]
	v_mfma_i32_16x16x64_i8 v[118:121], v[18:21], v[170:173], v[118:121]
	v_mfma_i32_16x16x64_i8 v[118:121], v[22:25], v[174:177], v[118:121]
	v_mfma_i32_16x16x64_i8 v[54:57], v[18:21], v[178:181], v[54:57]
	v_mfma_i32_16x16x64_i8 v[54:57], v[22:25], v[182:185], v[54:57]
	v_mfma_i32_16x16x64_i8 v[30:33], v[34:37], v[178:181], v[30:33]
	v_mfma_i32_16x16x64_i8 v[30:33], v[38:41], v[182:185], v[30:33]
	v_mfma_i32_16x16x64_i8 v[58:61], v[34:37], v[186:189], v[58:61]
	v_mfma_i32_16x16x64_i8 v[58:61], v[38:41], v[190:193], v[58:61]
	v_mfma_i32_16x16x64_i8 v[94:97], v[18:21], v[186:189], v[94:97]
	v_mfma_i32_16x16x64_i8 v[94:97], v[22:25], v[190:193], v[94:97]
	v_mfma_i32_16x16x64_i8 v[142:145], v[130:133], v[162:165], v[142:145]
	v_mfma_i32_16x16x64_i8 v[142:145], v[134:137], v[166:169], v[142:145]
	v_mfma_i32_16x16x64_i8 v[138:141], v[154:157], v[162:165], v[138:141]
	v_mfma_i32_16x16x64_i8 v[138:141], v[158:161], v[166:169], v[138:141]
	v_mfma_i32_16x16x64_i8 v[98:101], v[154:157], v[170:173], v[98:101]
	v_mfma_i32_16x16x64_i8 v[98:101], v[158:161], v[174:177], v[98:101]
	v_mfma_i32_16x16x64_i8 v[102:105], v[130:133], v[170:173], v[102:105]
	v_mfma_i32_16x16x64_i8 v[102:105], v[134:137], v[174:177], v[102:105]
	v_mfma_i32_16x16x64_i8 v[42:45], v[130:133], v[178:181], v[42:45]
	v_mfma_i32_16x16x64_i8 v[42:45], v[134:137], v[182:185], v[42:45]
	v_mfma_i32_16x16x64_i8 v[26:29], v[154:157], v[178:181], v[26:29]
	v_mfma_i32_16x16x64_i8 v[26:29], v[158:161], v[182:185], v[26:29]
	v_mfma_i32_16x16x64_i8 v[62:65], v[154:157], v[186:189], v[62:65]
	v_mfma_i32_16x16x64_i8 v[62:65], v[158:161], v[190:193], v[62:65]
	v_mfma_i32_16x16x64_i8 v[78:81], v[130:133], v[186:189], v[78:81]
	v_mfma_i32_16x16x64_i8 v[78:81], v[134:137], v[190:193], v[78:81]
	s_barrier
	s_add_i32 s0, vcc_hi, s69
	v_lshl_add_u64 v[198:199], s[6:7], 0, v[0:1]
	s_mov_b32 m0, s0
	ds_read_b128 v[162:165], v243 offset:16384
	ds_read_b128 v[166:169], v243 offset:17408
	ds_read_b128 v[170:173], v243 offset:18432
	ds_read_b128 v[174:177], v243 offset:19456
	ds_read_b128 v[178:181], v243 offset:20480
	ds_read_b128 v[182:185], v243 offset:21504
	ds_read_b128 v[186:189], v243 offset:22528
	ds_read_b128 v[190:193], v243 offset:23552
	global_load_lds_dwordx4 v[198:199], off
	s_add_i32 m0, s0, 0x2000
	s_add_u32 s0, s6, 0x40000
	v_lshl_add_u64 v[200:201], s[6:7], 0, v[214:215]
	s_addc_u32 s1, s7, 0
	s_add_i32 s4, s4, s69
	global_load_lds_dwordx4 v[200:201], off
	s_mov_b32 m0, s4
	v_lshl_add_u64 v[206:207], s[12:13], 0, v[210:211]
	global_load_lds_dwordx4 v0, s[0:1]
	s_add_i32 m0, s4, 0x2000
	v_lshl_add_u64 v[220:221], s[12:13], 0, v[212:213]
	global_load_lds_dwordx4 v214, s[0:1]
	s_mov_b32 m0, s11
	s_nop 0
	global_load_lds_dwordx4 v[206:207], off
	s_mov_b32 m0, s71
	s_nop 0
	global_load_lds_dwordx4 v[220:221], off
	s_waitcnt vmcnt(8)
	s_waitcnt lgkmcnt(0)
	s_barrier
	s_waitcnt lgkmcnt(0)
	v_mfma_i32_16x16x64_i8 v[106:109], v[18:21], v[162:165], v[106:109]
	v_mfma_i32_16x16x64_i8 v[106:109], v[22:25], v[166:169], v[106:109]
	v_mfma_i32_16x16x64_i8 v[46:49], v[34:37], v[162:165], v[46:49]
	v_mfma_i32_16x16x64_i8 v[46:49], v[38:41], v[166:169], v[46:49]
	v_mfma_i32_16x16x64_i8 v[6:9], v[34:37], v[170:173], v[6:9]
	v_mfma_i32_16x16x64_i8 v[6:9], v[38:41], v[174:177], v[6:9]
	v_mfma_i32_16x16x64_i8 v[14:17], v[18:21], v[170:173], v[14:17]
	v_mfma_i32_16x16x64_i8 v[14:17], v[22:25], v[174:177], v[14:17]
	v_mfma_i32_16x16x64_i8 v[90:93], v[18:21], v[178:181], v[90:93]
	v_mfma_i32_16x16x64_i8 v[90:93], v[22:25], v[182:185], v[90:93]
	v_mfma_i32_16x16x64_i8 v[86:89], v[34:37], v[178:181], v[86:89]
	v_mfma_i32_16x16x64_i8 v[86:89], v[38:41], v[182:185], v[86:89]
	v_mfma_i32_16x16x64_i8 v[18:21], v[18:21], v[186:189], v[126:129]
	v_mfma_i32_16x16x64_i8 v[18:21], v[22:25], v[190:193], v[18:21]
	v_mfma_i32_16x16x64_i8 v[22:25], v[34:37], v[186:189], v[66:69]
	v_mfma_i32_16x16x64_i8 v[22:25], v[38:41], v[190:193], v[22:25]
	v_mfma_i32_16x16x64_i8 v[38:41], v[154:157], v[162:165], v[50:53]
	v_mfma_i32_16x16x64_i8 v[38:41], v[158:161], v[166:169], v[38:41]
	v_mfma_i32_16x16x64_i8 v[2:5], v[154:157], v[170:173], v[2:5]
	v_mfma_i32_16x16x64_i8 v[2:5], v[158:161], v[174:177], v[2:5]
	v_mfma_i32_16x16x64_i8 v[10:13], v[130:133], v[170:173], v[10:13]
	v_mfma_i32_16x16x64_i8 v[10:13], v[134:137], v[174:177], v[10:13]
	v_mfma_i32_16x16x64_i8 v[50:53], v[130:133], v[178:181], v[82:85]
	v_mfma_i32_16x16x64_i8 v[82:85], v[134:137], v[182:185], v[50:53]
	v_mfma_i32_16x16x64_i8 v[34:37], v[130:133], v[162:165], v[114:117]
	v_mfma_i32_16x16x64_i8 v[34:37], v[134:137], v[166:169], v[34:37]
	v_mfma_i32_16x16x64_i8 v[50:53], v[154:157], v[178:181], v[74:77]
	v_mfma_i32_16x16x64_i8 v[74:77], v[158:161], v[182:185], v[50:53]
	v_mfma_i32_16x16x64_i8 v[50:53], v[130:133], v[186:189], v[122:125]
	v_mfma_i32_16x16x64_i8 v[122:125], v[134:137], v[190:193], v[50:53]
	v_mfma_i32_16x16x64_i8 v[50:53], v[154:157], v[186:189], v[70:73]
	v_mfma_i32_16x16x64_i8 v[70:73], v[158:161], v[190:193], v[50:53]
	s_barrier
; #define PG8_STAGE(bufoff, gbase, voff) do { _Pragma("unroll") for (int _i = 0; _i < 2; ++_i) \
;         __builtin_amdgcn_global_load_lds((const unsigned*)((const char*)(gbase) + (voff)[_i]), (PG8_LAS unsigned*)(lds + (bufoff) + ldsw + _i * 8192), 16, 0, 0); } while (0)
; #define PG8_LDA(dst, b, h) do { _Pragma("unroll") for (int m = 0; m < 4; ++m) _Pragma("unroll") for (int k = 0; k < 2; ++k) dst[m][k] = *(const PG8_LAS bf16x8*)(lds + PG8_SA(b, h) + aoff + m * 2048 + k * 1024); } while (0)
; #define PG8_LDB(dst, b, h) do { _Pragma("unroll") for (int n = 0; n < 2; ++n) _Pragma("unroll") for (int k = 0; k < 2; ++k) dst[n][k] = *(const PG8_LAS bf16x8*)(lds + PG8_SB(b, h) + boff + n * 2048 + k * 1024); } while (0)
; #define PG8_MMA(ai, bj, At, Bt) do { __builtin_amdgcn_s_setprio(1); _Pragma("unroll") for (int m = 0; m < 4; ++m) _Pragma("unroll") for (int n = 0; n < 2; ++n) _Pragma("unroll") for (int k = 0; k < 2; ++k) \
;         acc[ai][bj][m][n] = mma16<Epi::I8>(Bt[n][k], At[m][k], acc[ai][bj][m][n]); __builtin_amdgcn_s_setprio(0); } while (0)
; #define PG8_WAIT_V(n) asm volatile("s_waitcnt vmcnt(" #n ")" ::: "memory")
; #define PG8_WAIT_L(n) asm volatile("s_waitcnt lgkmcnt(" #n ")" ::: "memory")
; #define PG8_BAR __builtin_amdgcn_s_barrier()
; #define PG8_SCHED __builtin_amdgcn_sched_barrier(0)
; template <class Epi, class Sched, bool ALIGN_EPI = false, bool SP2 = false>
; __device__ __forceinline__ void gemm_phase(PG8_LAS unsigned char* lds, const Gemm g, const Sched& S, const Epi& E) {
;     ...
;             PG8_LDB(B0, 1, 0); PG8_LDB(B1, 1, 1); PG8_SCHED; PG8_LDA(At, 1, 0); PG8_STAGE(PG8_SA(0, 1), a2 + hstep, voffA);
;             PG8_WAIT_V(8); PG8_WAIT_L(0); PG8_BAR; PG8_MMA(0, 0, At, B0); PG8_MMA(0, 1, At, B1); PG8_BAR; PG8_SCHED;
;             PG8_LDA(At, 1, 1); PG8_STAGE(PG8_SB(1, 0), b3, voffB); PG8_STAGE(PG8_SB(1, 1), b3 + hstep, voffB); PG8_STAGE(PG8_SA(1, 0), a3, voffA);
;             PG8_WAIT_V(8); PG8_WAIT_L(0); PG8_BAR; PG8_MMA(1, 0, At, B0); PG8_MMA(1, 1, At, B1); PG8_BAR; PG8_SCHED;
	s_add_i32 s4, 0, 0x18000
	v_add_u32_e32 v126, s4, v242
	s_add_i32 s5, 0, 0x1c000
	ds_read_b128 v[50:53], v126
	ds_read_b128 v[66:69], v126 offset:1024
	ds_read_b128 v[114:117], v126 offset:2048
	ds_read_b128 v[130:133], v126 offset:3072
	v_add_u32_e32 v126, s5, v242
	ds_read_b128 v[134:137], v126
	ds_read_b128 v[154:157], v126 offset:1024
	ds_read_b128 v[158:161], v126 offset:2048
	ds_read_b128 v[162:165], v126 offset:3072
	s_add_u32 s0, s12, 0x40000
	s_addc_u32 s1, s13, 0
	s_mov_b32 m0, s80
	ds_read_b128 v[126:129], v243 offset:32768
	ds_read_b128 v[166:169], v243 offset:33792
	ds_read_b128 v[170:173], v243 offset:34816
	ds_read_b128 v[174:177], v243 offset:35840
	ds_read_b128 v[178:181], v243 offset:36864
	ds_read_b128 v[182:185], v243 offset:37888
	ds_read_b128 v[186:189], v243 offset:38912
	ds_read_b128 v[190:193], v243 offset:39936
	global_load_lds_dwordx4 v210, s[0:1]
	s_mov_b32 m0, s81
	s_nop 0
	global_load_lds_dwordx4 v212, s[0:1]
	s_waitcnt vmcnt(8)
	s_waitcnt lgkmcnt(0)
	s_barrier
	s_waitcnt lgkmcnt(0)
	v_mfma_i32_16x16x64_i8 v[150:153], v[50:53], v[126:129], v[150:153]
	v_mfma_i32_16x16x64_i8 v[150:153], v[66:69], v[166:169], v[150:153]
	v_mfma_i32_16x16x64_i8 v[146:149], v[114:117], v[126:129], v[146:149]
	v_mfma_i32_16x16x64_i8 v[146:149], v[130:133], v[166:169], v[146:149]
	v_mfma_i32_16x16x64_i8 v[110:113], v[114:117], v[170:173], v[110:113]
	v_mfma_i32_16x16x64_i8 v[110:113], v[130:133], v[174:177], v[110:113]
	v_mfma_i32_16x16x64_i8 v[118:121], v[50:53], v[170:173], v[118:121]
	v_mfma_i32_16x16x64_i8 v[118:121], v[66:69], v[174:177], v[118:121]
	v_mfma_i32_16x16x64_i8 v[54:57], v[50:53], v[178:181], v[54:57]
	v_mfma_i32_16x16x64_i8 v[54:57], v[66:69], v[182:185], v[54:57]
	v_mfma_i32_16x16x64_i8 v[30:33], v[114:117], v[178:181], v[30:33]
	v_mfma_i32_16x16x64_i8 v[30:33], v[130:133], v[182:185], v[30:33]
	v_mfma_i32_16x16x64_i8 v[58:61], v[114:117], v[186:189], v[58:61]
	v_mfma_i32_16x16x64_i8 v[58:61], v[130:133], v[190:193], v[58:61]
	v_mfma_i32_16x16x64_i8 v[94:97], v[50:53], v[186:189], v[94:97]
	v_mfma_i32_16x16x64_i8 v[94:97], v[66:69], v[190:193], v[94:97]
	v_mfma_i32_16x16x64_i8 v[142:145], v[134:137], v[126:129], v[142:145]
	v_mfma_i32_16x16x64_i8 v[142:145], v[154:157], v[166:169], v[142:145]
	v_mfma_i32_16x16x64_i8 v[126:129], v[158:161], v[126:129], v[138:141]
	v_mfma_i32_16x16x64_i8 v[138:141], v[162:165], v[166:169], v[126:129]
	v_mfma_i32_16x16x64_i8 v[98:101], v[158:161], v[170:173], v[98:101]
	v_mfma_i32_16x16x64_i8 v[98:101], v[162:165], v[174:177], v[98:101]
	v_mfma_i32_16x16x64_i8 v[102:105], v[134:137], v[170:173], v[102:105]
	v_mfma_i32_16x16x64_i8 v[102:105], v[154:157], v[174:177], v[102:105]
	v_mfma_i32_16x16x64_i8 v[42:45], v[134:137], v[178:181], v[42:45]
	v_mfma_i32_16x16x64_i8 v[42:45], v[154:157], v[182:185], v[42:45]
	v_mfma_i32_16x16x64_i8 v[26:29], v[158:161], v[178:181], v[26:29]
	v_mfma_i32_16x16x64_i8 v[26:29], v[162:165], v[182:185], v[26:29]
	v_mfma_i32_16x16x64_i8 v[62:65], v[158:161], v[186:189], v[62:65]
	v_mfma_i32_16x16x64_i8 v[62:65], v[162:165], v[190:193], v[62:65]
	v_mfma_i32_16x16x64_i8 v[78:81], v[134:137], v[186:189], v[78:81]
	v_mfma_i32_16x16x64_i8 v[78:81], v[154:157], v[190:193], v[78:81]
	s_barrier
	s_add_i32 s0, s4, s69
	v_lshl_add_u64 v[126:127], v[198:199], 0, s[92:93]
	s_mov_b32 m0, s0
	ds_read_b128 v[166:169], v243 offset:49152
	ds_read_b128 v[170:173], v243 offset:50176
	ds_read_b128 v[174:177], v243 offset:51200
	ds_read_b128 v[178:181], v243 offset:52224
	ds_read_b128 v[182:185], v243 offset:53248
	ds_read_b128 v[186:189], v243 offset:54272
	ds_read_b128 v[190:193], v243 offset:55296
	ds_read_b128 v[194:197], v243 offset:56320
	global_load_lds_dwordx4 v[126:127], off
	s_add_i32 m0, s0, 0x2000
	s_add_u32 s0, s6, 0x40080
	v_lshl_add_u64 v[126:127], v[200:201], 0, s[92:93]
	s_addc_u32 s1, s7, 0
	s_add_i32 s4, s5, s69
	global_load_lds_dwordx4 v[126:127], off
	s_mov_b32 m0, s4
	s_nop 0
	global_load_lds_dwordx4 v0, s[0:1]
	s_add_i32 m0, s4, 0x2000
	s_nop 0
	global_load_lds_dwordx4 v214, s[0:1]
	v_lshl_add_u64 v[126:127], v[206:207], 0, s[92:93]
	s_mov_b32 m0, s84
	s_nop 0
	global_load_lds_dwordx4 v[126:127], off
	v_lshl_add_u64 v[126:127], v[220:221], 0, s[92:93]
	s_mov_b32 m0, s85
	s_nop 0
	global_load_lds_dwordx4 v[126:127], off
	s_waitcnt vmcnt(8)
	s_waitcnt lgkmcnt(0)
	s_barrier
	s_waitcnt lgkmcnt(0)
	v_mfma_i32_16x16x64_i8 v[18:21], v[50:53], v[190:193], v[18:21]
	v_mfma_i32_16x16x64_i8 v[126:129], v[66:69], v[194:197], v[18:21]
	v_mfma_i32_16x16x64_i8 v[106:109], v[50:53], v[166:169], v[106:109]
	v_mfma_i32_16x16x64_i8 v[106:109], v[66:69], v[170:173], v[106:109]
	v_mfma_i32_16x16x64_i8 v[46:49], v[114:117], v[166:169], v[46:49]
	v_mfma_i32_16x16x64_i8 v[46:49], v[130:133], v[170:173], v[46:49]
	v_mfma_i32_16x16x64_i8 v[6:9], v[114:117], v[174:177], v[6:9]
	v_mfma_i32_16x16x64_i8 v[6:9], v[130:133], v[178:181], v[6:9]
	v_mfma_i32_16x16x64_i8 v[14:17], v[50:53], v[174:177], v[14:17]
	v_mfma_i32_16x16x64_i8 v[14:17], v[66:69], v[178:181], v[14:17]
	v_mfma_i32_16x16x64_i8 v[90:93], v[50:53], v[182:185], v[90:93]
	v_mfma_i32_16x16x64_i8 v[90:93], v[66:69], v[186:189], v[90:93]
	v_mfma_i32_16x16x64_i8 v[86:89], v[114:117], v[182:185], v[86:89]
	v_mfma_i32_16x16x64_i8 v[86:89], v[130:133], v[186:189], v[86:89]
	v_mfma_i32_16x16x64_i8 v[18:21], v[114:117], v[190:193], v[22:25]
	v_mfma_i32_16x16x64_i8 v[66:69], v[130:133], v[194:197], v[18:21]
	v_mfma_i32_16x16x64_i8 v[18:21], v[134:137], v[166:169], v[34:37]
	v_mfma_i32_16x16x64_i8 v[114:117], v[154:157], v[170:173], v[18:21]
	v_mfma_i32_16x16x64_i8 v[10:13], v[134:137], v[174:177], v[10:13]
	v_mfma_i32_16x16x64_i8 v[10:13], v[154:157], v[178:181], v[10:13]
	v_mfma_i32_16x16x64_i8 v[2:5], v[158:161], v[174:177], v[2:5]
	v_mfma_i32_16x16x64_i8 v[2:5], v[162:165], v[178:181], v[2:5]
	v_mfma_i32_16x16x64_i8 v[18:21], v[158:161], v[166:169], v[38:41]
	v_mfma_i32_16x16x64_i8 v[50:53], v[162:165], v[170:173], v[18:21]
	v_mfma_i32_16x16x64_i8 v[18:21], v[134:137], v[182:185], v[82:85]
	v_mfma_i32_16x16x64_i8 v[82:85], v[154:157], v[186:189], v[18:21]
	v_mfma_i32_16x16x64_i8 v[18:21], v[158:161], v[182:185], v[74:77]
	v_mfma_i32_16x16x64_i8 v[74:77], v[162:165], v[186:189], v[18:21]
	v_mfma_i32_16x16x64_i8 v[18:21], v[134:137], v[190:193], v[122:125]
	v_mfma_i32_16x16x64_i8 v[122:125], v[154:157], v[194:197], v[18:21]
	v_mfma_i32_16x16x64_i8 v[18:21], v[158:161], v[190:193], v[70:73]
	v_mfma_i32_16x16x64_i8 v[70:73], v[162:165], v[194:197], v[18:21]
	s_barrier
	s_add_i32 vcc_lo, vcc_lo, 2
	s_add_u32 s96, s96, 0x100
	s_addc_u32 s97, s97, 0
	s_cmp_gt_u32 vcc_lo, 13
	s_mov_b64 s[0:1], s[8:9]
	s_cbranch_scc0 .LBB0_80

; #define PG8_STAGE(bufoff, gbase, voff) do { _Pragma("unroll") for (int _i = 0; _i < 2; ++_i) \
;         __builtin_amdgcn_global_load_lds((const unsigned*)((const char*)(gbase) + (voff)[_i]), (PG8_LAS unsigned*)(lds + (bufoff) + ldsw + _i * 8192), 16, 0, 0); } while (0)
; #define PG8_LDA(dst, b, h) do { _Pragma("unroll") for (int m = 0; m < 4; ++m) _Pragma("unroll") for (int k = 0; k < 2; ++k) dst[m][k] = *(const PG8_LAS bf16x8*)(lds + PG8_SA(b, h) + aoff + m * 2048 + k * 1024); } while (0)
; #define PG8_LDB(dst, b, h) do { _Pragma("unroll") for (int n = 0; n < 2; ++n) _Pragma("unroll") for (int k = 0; k < 2; ++k) dst[n][k] = *(const PG8_LAS bf16x8*)(lds + PG8_SB(b, h) + boff + n * 2048 + k * 1024); } while (0)
; #define PG8_MMA(ai, bj, At, Bt) do { __builtin_amdgcn_s_setprio(1); _Pragma("unroll") for (int m = 0; m < 4; ++m) _Pragma("unroll") for (int n = 0; n < 2; ++n) _Pragma("unroll") for (int k = 0; k < 2; ++k) \
;         acc[ai][bj][m][n] = mma16<Epi::I8>(Bt[n][k], At[m][k], acc[ai][bj][m][n]); __builtin_amdgcn_s_setprio(0); } while (0)
; #define PG8_WAIT_V(n) asm volatile("s_waitcnt vmcnt(" #n ")" ::: "memory")
; #define PG8_WAIT_L(n) asm volatile("s_waitcnt lgkmcnt(" #n ")" ::: "memory")
; #define PG8_BAR __builtin_amdgcn_s_barrier()
; #define PG8_SCHED __builtin_amdgcn_sched_barrier(0)
; template <class Epi, class Sched, bool ALIGN_EPI = false, bool SP2 = false>
; __device__ __forceinline__ void gemm_phase(PG8_LAS unsigned char* lds, const Gemm g, const Sched& S, const Epi& E) {
;     ...
;             const char* a1 = cA + (size_t)(t + 1) * kstep;
;             const char* a2 = last ? nA : cA + (size_t)(t + 2) * kstep; const char* b2 = last ? nB : cB + (size_t)(t + 2) * kstep;
;             const char* a3 = a2 + kstep; const char* b3 = b2 + kstep;
;             if (last && has_next) S.a_ready(nxt);
;             if constexpr (SP2) {
;             PG8_LDB(B0, 0, 0); PG8_LDB(B1, 0, 1); PG8_SCHED; PG8_LDA(At, 0, 0); PG8_STAGE(PG8_SA(1, 1), a1 + hstep, voffA);
;             PG8_WAIT_V(8); PG8_WAIT_L(0); PG8_BAR; PG8_MMA(0, 0, At, B0); PG8_MMA(0, 1, At, B1); PG8_BAR; PG8_SCHED;
;             PG8_LDA(At, 0, 1); PG8_STAGE(PG8_SB(0, 0), b2, voffB); PG8_STAGE(PG8_SB(0, 1), b2 + hstep, voffB); PG8_STAGE(PG8_SA(0, 0), a2, voffA);
.Lpeel175:
	s_add_i32 vcc_lo, s8, 2
	s_add_u32 s4, s6, s98
	s_addc_u32 s5, s7, 0
	s_add_i32 vcc_hi, 0, 0x10000
	s_cmp_eq_u32 s13, s8
	s_cselect_b32 s9, s1, s5
	s_cselect_b32 s8, s0, s4
	s_cselect_b32 s5, s97, s85
	s_cselect_b32 s4, s96, s67
	s_add_i32 s84, 0, 0x14000
	v_add_u32_e32 v122, vcc_hi, v248
	v_add_u32_e32 v154, s84, v248
	ds_read_b128 v[98:101], v122
	ds_read_b128 v[102:105], v122 offset:1024
	ds_read_b128 v[114:117], v122 offset:2048
	ds_read_b128 v[122:125], v122 offset:3072
	ds_read_b128 v[130:133], v154
	ds_read_b128 v[138:141], v154 offset:1024
	ds_read_b128 v[146:149], v154 offset:2048
	ds_read_b128 v[154:157], v154 offset:3072
	v_lshl_add_u64 v[206:207], s[6:7], 0, v[200:201]
	s_add_i32 m0, s81, 0xc000
	ds_read_b128 v[162:165], v249
	ds_read_b128 v[166:169], v249 offset:1024
	ds_read_b128 v[170:173], v249 offset:2048
	ds_read_b128 v[174:177], v249 offset:3072
	ds_read_b128 v[178:181], v249 offset:4096
	ds_read_b128 v[182:185], v249 offset:5120
	ds_read_b128 v[186:189], v249 offset:6144
	ds_read_b128 v[190:193], v249 offset:7168
	global_load_lds_dwordx4 v[206:207], off
	v_lshl_add_u64 v[206:207], s[6:7], 0, v[210:211]
	s_add_i32 m0, s81, 0xe000
	s_nop 0
	global_load_lds_dwordx4 v[206:207], off
	s_waitcnt vmcnt(8)
	s_waitcnt lgkmcnt(0)
	s_barrier
	s_waitcnt lgkmcnt(0)
	v_mfma_f32_16x16x32_bf16 v[158:161], v[98:101], v[162:165], 0
	v_mfma_f32_16x16x32_bf16 v[158:161], v[102:105], v[166:169], v[158:161]
	v_mfma_f32_16x16x32_bf16 v[150:153], v[114:117], v[162:165], 0
	v_mfma_f32_16x16x32_bf16 v[150:153], v[122:125], v[166:169], v[150:153]
	v_mfma_f32_16x16x32_bf16 v[118:121], v[114:117], v[170:173], 0
	v_mfma_f32_16x16x32_bf16 v[118:121], v[122:125], v[174:177], v[118:121]
	v_mfma_f32_16x16x32_bf16 v[126:129], v[98:101], v[170:173], 0
	v_mfma_f32_16x16x32_bf16 v[126:129], v[102:105], v[174:177], v[126:129]
	v_mfma_f32_16x16x32_bf16 v[94:97], v[98:101], v[178:181], 0
	v_mfma_f32_16x16x32_bf16 v[94:97], v[102:105], v[182:185], v[94:97]
	v_mfma_f32_16x16x32_bf16 v[90:93], v[114:117], v[178:181], 0
	v_mfma_f32_16x16x32_bf16 v[90:93], v[122:125], v[182:185], v[90:93]
	v_mfma_f32_16x16x32_bf16 v[74:77], v[114:117], v[186:189], 0
	v_mfma_f32_16x16x32_bf16 v[74:77], v[122:125], v[190:193], v[74:77]
	v_mfma_f32_16x16x32_bf16 v[78:81], v[98:101], v[186:189], 0
	v_mfma_f32_16x16x32_bf16 v[78:81], v[102:105], v[190:193], v[78:81]
	v_mfma_f32_16x16x32_bf16 v[142:145], v[130:133], v[162:165], 0
	v_mfma_f32_16x16x32_bf16 v[142:145], v[138:141], v[166:169], v[142:145]
	v_mfma_f32_16x16x32_bf16 v[134:137], v[146:149], v[162:165], 0
	v_mfma_f32_16x16x32_bf16 v[134:137], v[154:157], v[166:169], v[134:137]
	v_mfma_f32_16x16x32_bf16 v[106:109], v[146:149], v[170:173], 0
	v_mfma_f32_16x16x32_bf16 v[106:109], v[154:157], v[174:177], v[106:109]
	v_mfma_f32_16x16x32_bf16 v[110:113], v[130:133], v[170:173], 0
	v_mfma_f32_16x16x32_bf16 v[110:113], v[138:141], v[174:177], v[110:113]
	v_mfma_f32_16x16x32_bf16 v[86:89], v[130:133], v[178:181], 0
	v_mfma_f32_16x16x32_bf16 v[86:89], v[138:141], v[182:185], v[86:89]
	v_mfma_f32_16x16x32_bf16 v[82:85], v[146:149], v[178:181], 0
	v_mfma_f32_16x16x32_bf16 v[82:85], v[154:157], v[182:185], v[82:85]
	v_mfma_f32_16x16x32_bf16 v[66:69], v[146:149], v[186:189], 0
	v_mfma_f32_16x16x32_bf16 v[66:69], v[154:157], v[190:193], v[66:69]
	v_mfma_f32_16x16x32_bf16 v[70:73], v[130:133], v[186:189], 0
	v_mfma_f32_16x16x32_bf16 v[70:73], v[138:141], v[190:193], v[70:73]
	s_barrier
	s_add_i32 vcc_hi, vcc_hi, s80
	v_lshl_add_u64 v[206:207], s[4:5], 0, v[0:1]
	s_mov_b32 m0, vcc_hi
	ds_read_b128 v[162:165], v249 offset:16384
	ds_read_b128 v[166:169], v249 offset:17408
	ds_read_b128 v[170:173], v249 offset:18432
	ds_read_b128 v[174:177], v249 offset:19456
	ds_read_b128 v[178:181], v249 offset:20480
	ds_read_b128 v[182:185], v249 offset:21504
	ds_read_b128 v[186:189], v249 offset:22528
	ds_read_b128 v[190:193], v249 offset:23552
	global_load_lds_dwordx4 v[206:207], off
	s_add_i32 m0, vcc_hi, 0x2000
	v_lshl_add_u64 v[212:213], s[4:5], 0, v[198:199]
	s_add_u32 s4, s4, s100
	s_addc_u32 s5, s5, 0
	s_add_i32 s84, s84, s80
	global_load_lds_dwordx4 v[212:213], off
	v_lshl_add_u64 v[214:215], s[4:5], 0, v[0:1]
	s_mov_b32 m0, s84
	v_lshl_add_u64 v[216:217], s[4:5], 0, v[198:199]
	global_load_lds_dwordx4 v[214:215], off
	s_add_i32 m0, s84, 0x2000
	v_lshl_add_u64 v[218:219], s[8:9], 0, v[194:195]
	global_load_lds_dwordx4 v[216:217], off
	s_mov_b32 m0, s81
	v_lshl_add_u64 v[220:221], s[8:9], 0, v[196:197]
	global_load_lds_dwordx4 v[218:219], off
	s_mov_b32 m0, s70
	s_nop 0
	global_load_lds_dwordx4 v[220:221], off
	s_waitcnt vmcnt(8)
	s_waitcnt lgkmcnt(0)
	s_barrier
; #define PG8_STAGE(bufoff, gbase, voff) do { _Pragma("unroll") for (int _i = 0; _i < 2; ++_i) \
;         __builtin_amdgcn_global_load_lds((const unsigned*)((const char*)(gbase) + (voff)[_i]), (PG8_LAS unsigned*)(lds + (bufoff) + ldsw + _i * 8192), 16, 0, 0); } while (0)
; #define PG8_LDA(dst, b, h) do { _Pragma("unroll") for (int m = 0; m < 4; ++m) _Pragma("unroll") for (int k = 0; k < 2; ++k) dst[m][k] = *(const PG8_LAS bf16x8*)(lds + PG8_SA(b, h) + aoff + m * 2048 + k * 1024); } while (0)
; #define PG8_LDB(dst, b, h) do { _Pragma("unroll") for (int n = 0; n < 2; ++n) _Pragma("unroll") for (int k = 0; k < 2; ++k) dst[n][k] = *(const PG8_LAS bf16x8*)(lds + PG8_SB(b, h) + boff + n * 2048 + k * 1024); } while (0)
; #define PG8_MMA(ai, bj, At, Bt) do { __builtin_amdgcn_s_setprio(1); _Pragma("unroll") for (int m = 0; m < 4; ++m) _Pragma("unroll") for (int n = 0; n < 2; ++n) _Pragma("unroll") for (int k = 0; k < 2; ++k) \
;         acc[ai][bj][m][n] = mma16<Epi::I8>(Bt[n][k], At[m][k], acc[ai][bj][m][n]); __builtin_amdgcn_s_setprio(0); } while (0)
; #define PG8_WAIT_V(n) asm volatile("s_waitcnt vmcnt(" #n ")" ::: "memory")
; #define PG8_WAIT_L(n) asm volatile("s_waitcnt lgkmcnt(" #n ")" ::: "memory")
; #define PG8_BAR __builtin_amdgcn_s_barrier()
; #define PG8_SCHED __builtin_amdgcn_sched_barrier(0)
; template <class Epi, class Sched, bool ALIGN_EPI = false, bool SP2 = false>
; __device__ __forceinline__ void gemm_phase(PG8_LAS unsigned char* lds, const Gemm g, const Sched& S, const Epi& E) {
;     ...
;             PG8_WAIT_V(8); PG8_WAIT_L(0); PG8_BAR; PG8_MMA(1, 0, At, B0); PG8_MMA(1, 1, At, B1); PG8_BAR; PG8_SCHED;
;             PG8_LDB(B0, 1, 0); PG8_LDB(B1, 1, 1); PG8_SCHED; PG8_LDA(At, 1, 0); PG8_STAGE(PG8_SA(0, 1), a2 + hstep, voffA);
;             PG8_WAIT_V(8); PG8_WAIT_L(0); PG8_BAR; PG8_MMA(0, 0, At, B0); PG8_MMA(0, 1, At, B1); PG8_BAR; PG8_SCHED;
	s_waitcnt lgkmcnt(0)
	v_mfma_f32_16x16x32_bf16 v[62:65], v[98:101], v[162:165], 0
	v_mfma_f32_16x16x32_bf16 v[62:65], v[102:105], v[166:169], v[62:65]
	v_mfma_f32_16x16x32_bf16 v[58:61], v[114:117], v[162:165], 0
	v_mfma_f32_16x16x32_bf16 v[58:61], v[122:125], v[166:169], v[58:61]
	v_mfma_f32_16x16x32_bf16 v[42:45], v[114:117], v[170:173], 0
	v_mfma_f32_16x16x32_bf16 v[42:45], v[122:125], v[174:177], v[42:45]
	v_mfma_f32_16x16x32_bf16 v[46:49], v[98:101], v[170:173], 0
	v_mfma_f32_16x16x32_bf16 v[46:49], v[102:105], v[174:177], v[46:49]
	v_mfma_f32_16x16x32_bf16 v[30:33], v[98:101], v[178:181], 0
	v_mfma_f32_16x16x32_bf16 v[30:33], v[102:105], v[182:185], v[30:33]
	v_mfma_f32_16x16x32_bf16 v[26:29], v[114:117], v[178:181], 0
	v_mfma_f32_16x16x32_bf16 v[26:29], v[122:125], v[182:185], v[26:29]
	v_mfma_f32_16x16x32_bf16 v[10:13], v[114:117], v[186:189], 0
	v_mfma_f32_16x16x32_bf16 v[10:13], v[122:125], v[190:193], v[10:13]
	v_mfma_f32_16x16x32_bf16 v[14:17], v[98:101], v[186:189], 0
	v_mfma_f32_16x16x32_bf16 v[14:17], v[102:105], v[190:193], v[14:17]
	v_mfma_f32_16x16x32_bf16 v[54:57], v[130:133], v[162:165], 0
	v_mfma_f32_16x16x32_bf16 v[54:57], v[138:141], v[166:169], v[54:57]
	v_mfma_f32_16x16x32_bf16 v[50:53], v[146:149], v[162:165], 0
	v_mfma_f32_16x16x32_bf16 v[50:53], v[154:157], v[166:169], v[50:53]
	v_mfma_f32_16x16x32_bf16 v[34:37], v[146:149], v[170:173], 0
	v_mfma_f32_16x16x32_bf16 v[34:37], v[154:157], v[174:177], v[34:37]
	v_mfma_f32_16x16x32_bf16 v[38:41], v[130:133], v[170:173], 0
	v_mfma_f32_16x16x32_bf16 v[38:41], v[138:141], v[174:177], v[38:41]
	v_mfma_f32_16x16x32_bf16 v[22:25], v[130:133], v[178:181], 0
	v_mfma_f32_16x16x32_bf16 v[22:25], v[138:141], v[182:185], v[22:25]
	v_mfma_f32_16x16x32_bf16 v[18:21], v[146:149], v[178:181], 0
	v_mfma_f32_16x16x32_bf16 v[18:21], v[154:157], v[182:185], v[18:21]
	v_mfma_f32_16x16x32_bf16 v[2:5], v[146:149], v[186:189], 0
	v_mfma_f32_16x16x32_bf16 v[2:5], v[154:157], v[190:193], v[2:5]
	v_mfma_f32_16x16x32_bf16 v[6:9], v[130:133], v[186:189], 0
	v_mfma_f32_16x16x32_bf16 v[6:9], v[138:141], v[190:193], v[6:9]
	s_barrier
	s_add_i32 s84, 0, 0x18000
	s_add_i32 vcc_hi, 0, 0x1c000
	v_add_u32_e32 v122, s84, v248
	v_add_u32_e32 v154, vcc_hi, v248
	ds_read_b128 v[98:101], v122
	ds_read_b128 v[102:105], v122 offset:1024
	ds_read_b128 v[114:117], v122 offset:2048
	ds_read_b128 v[122:125], v122 offset:3072
	ds_read_b128 v[130:133], v154
	ds_read_b128 v[138:141], v154 offset:1024
	ds_read_b128 v[146:149], v154 offset:2048
	ds_read_b128 v[154:157], v154 offset:3072
	s_add_u32 s4, s8, s100
	s_addc_u32 s5, s9, 0
	s_mov_b32 m0, s71
	v_lshl_add_u64 v[222:223], s[4:5], 0, v[194:195]
	ds_read_b128 v[162:165], v249 offset:32768
	ds_read_b128 v[166:169], v249 offset:33792
	ds_read_b128 v[170:173], v249 offset:34816
	ds_read_b128 v[174:177], v249 offset:35840
	ds_read_b128 v[178:181], v249 offset:36864
	ds_read_b128 v[182:185], v249 offset:37888
	ds_read_b128 v[186:189], v249 offset:38912
	ds_read_b128 v[190:193], v249 offset:39936
	global_load_lds_dwordx4 v[222:223], off
	v_lshl_add_u64 v[222:223], s[4:5], 0, v[196:197]
	s_mov_b32 m0, s12
	s_nop 0
	global_load_lds_dwordx4 v[222:223], off
	s_waitcnt vmcnt(8)
	s_waitcnt lgkmcnt(0)
	s_barrier
	s_waitcnt lgkmcnt(0)
	v_mfma_f32_16x16x32_bf16 v[158:161], v[98:101], v[162:165], v[158:161]
	v_mfma_f32_16x16x32_bf16 v[158:161], v[102:105], v[166:169], v[158:161]
	v_mfma_f32_16x16x32_bf16 v[150:153], v[114:117], v[162:165], v[150:153]
	v_mfma_f32_16x16x32_bf16 v[150:153], v[122:125], v[166:169], v[150:153]
	v_mfma_f32_16x16x32_bf16 v[118:121], v[114:117], v[170:173], v[118:121]
	v_mfma_f32_16x16x32_bf16 v[118:121], v[122:125], v[174:177], v[118:121]
	v_mfma_f32_16x16x32_bf16 v[126:129], v[98:101], v[170:173], v[126:129]
	v_mfma_f32_16x16x32_bf16 v[126:129], v[102:105], v[174:177], v[126:129]
	v_mfma_f32_16x16x32_bf16 v[94:97], v[98:101], v[178:181], v[94:97]
	v_mfma_f32_16x16x32_bf16 v[94:97], v[102:105], v[182:185], v[94:97]
	v_mfma_f32_16x16x32_bf16 v[90:93], v[114:117], v[178:181], v[90:93]
	v_mfma_f32_16x16x32_bf16 v[90:93], v[122:125], v[182:185], v[90:93]
	v_mfma_f32_16x16x32_bf16 v[74:77], v[114:117], v[186:189], v[74:77]
	v_mfma_f32_16x16x32_bf16 v[74:77], v[122:125], v[190:193], v[74:77]
	v_mfma_f32_16x16x32_bf16 v[78:81], v[98:101], v[186:189], v[78:81]
	v_mfma_f32_16x16x32_bf16 v[78:81], v[102:105], v[190:193], v[78:81]
	v_mfma_f32_16x16x32_bf16 v[142:145], v[130:133], v[162:165], v[142:145]
	v_mfma_f32_16x16x32_bf16 v[142:145], v[138:141], v[166:169], v[142:145]
	v_mfma_f32_16x16x32_bf16 v[134:137], v[146:149], v[162:165], v[134:137]
	v_mfma_f32_16x16x32_bf16 v[134:137], v[154:157], v[166:169], v[134:137]
	v_mfma_f32_16x16x32_bf16 v[106:109], v[146:149], v[170:173], v[106:109]
	v_mfma_f32_16x16x32_bf16 v[106:109], v[154:157], v[174:177], v[106:109]
	v_mfma_f32_16x16x32_bf16 v[110:113], v[130:133], v[170:173], v[110:113]
	v_mfma_f32_16x16x32_bf16 v[110:113], v[138:141], v[174:177], v[110:113]
	v_mfma_f32_16x16x32_bf16 v[86:89], v[130:133], v[178:181], v[86:89]
	v_mfma_f32_16x16x32_bf16 v[86:89], v[138:141], v[182:185], v[86:89]
	v_mfma_f32_16x16x32_bf16 v[82:85], v[146:149], v[178:181], v[82:85]
	v_mfma_f32_16x16x32_bf16 v[82:85], v[154:157], v[182:185], v[82:85]
	v_mfma_f32_16x16x32_bf16 v[66:69], v[146:149], v[186:189], v[66:69]
	v_mfma_f32_16x16x32_bf16 v[66:69], v[154:157], v[190:193], v[66:69]
	v_mfma_f32_16x16x32_bf16 v[70:73], v[130:133], v[186:189], v[70:73]
	v_mfma_f32_16x16x32_bf16 v[70:73], v[138:141], v[190:193], v[70:73]
	s_barrier
; #define PG8_STAGE(bufoff, gbase, voff) do { _Pragma("unroll") for (int _i = 0; _i < 2; ++_i) \
;         __builtin_amdgcn_global_load_lds((const unsigned*)((const char*)(gbase) + (voff)[_i]), (PG8_LAS unsigned*)(lds + (bufoff) + ldsw + _i * 8192), 16, 0, 0); } while (0)
; #define PG8_LDA(dst, b, h) do { _Pragma("unroll") for (int m = 0; m < 4; ++m) _Pragma("unroll") for (int k = 0; k < 2; ++k) dst[m][k] = *(const PG8_LAS bf16x8*)(lds + PG8_SA(b, h) + aoff + m * 2048 + k * 1024); } while (0)
; #define PG8_LDB(dst, b, h) do { _Pragma("unroll") for (int n = 0; n < 2; ++n) _Pragma("unroll") for (int k = 0; k < 2; ++k) dst[n][k] = *(const PG8_LAS bf16x8*)(lds + PG8_SB(b, h) + boff + n * 2048 + k * 1024); } while (0)
; #define PG8_MMA(ai, bj, At, Bt) do { __builtin_amdgcn_s_setprio(1); _Pragma("unroll") for (int m = 0; m < 4; ++m) _Pragma("unroll") for (int n = 0; n < 2; ++n) _Pragma("unroll") for (int k = 0; k < 2; ++k) \
;         acc[ai][bj][m][n] = mma16<Epi::I8>(Bt[n][k], At[m][k], acc[ai][bj][m][n]); __builtin_amdgcn_s_setprio(0); } while (0)
; #define PG8_WAIT_V(n) asm volatile("s_waitcnt vmcnt(" #n ")" ::: "memory")
; #define PG8_WAIT_L(n) asm volatile("s_waitcnt lgkmcnt(" #n ")" ::: "memory")
; #define PG8_BAR __builtin_amdgcn_s_barrier()
; #define PG8_SCHED __builtin_amdgcn_sched_barrier(0)
; template <class Epi, class Sched, bool ALIGN_EPI = false, bool SP2 = false>
; __device__ __forceinline__ void gemm_phase(PG8_LAS unsigned char* lds, const Gemm g, const Sched& S, const Epi& E) {
;     ...
;             const char* a1 = cA + (size_t)(t + 1) * kstep;
;             const char* a2 = last ? nA : cA + (size_t)(t + 2) * kstep; const char* b2 = last ? nB : cB + (size_t)(t + 2) * kstep;
;             const char* a3 = a2 + kstep; const char* b3 = b2 + kstep;
;             if (last && has_next) S.a_ready(nxt);
;             if constexpr (SP2) {
;             PG8_LDB(B0, 0, 0); PG8_LDB(B1, 0, 1); PG8_SCHED; PG8_LDA(At, 0, 0); PG8_STAGE(PG8_SA(1, 1), a1 + hstep, voffA);
;     ...
;             PG8_LDA(At, 1, 1); PG8_STAGE(PG8_SB(1, 0), b3, voffB); PG8_STAGE(PG8_SB(1, 1), b3 + hstep, voffB); PG8_STAGE(PG8_SA(1, 0), a3, voffA);
;             PG8_WAIT_V(8); PG8_WAIT_L(0); PG8_BAR; PG8_MMA(1, 0, At, B0); PG8_MMA(1, 1, At, B1); PG8_BAR; PG8_SCHED;
	s_add_i32 s4, s84, s80
	v_lshl_add_u64 v[206:207], v[206:207], 0, s[98:99]
	s_mov_b32 m0, s4
	ds_read_b128 v[162:165], v249 offset:49152
	ds_read_b128 v[166:169], v249 offset:50176
	ds_read_b128 v[170:173], v249 offset:51200
	ds_read_b128 v[174:177], v249 offset:52224
	ds_read_b128 v[178:181], v249 offset:53248
	ds_read_b128 v[182:185], v249 offset:54272
	ds_read_b128 v[186:189], v249 offset:55296
	ds_read_b128 v[190:193], v249 offset:56320
	global_load_lds_dwordx4 v[206:207], off
	v_lshl_add_u64 v[206:207], v[212:213], 0, s[98:99]
	s_add_i32 m0, s4, 0x2000
	s_add_i32 s4, vcc_hi, s80
	global_load_lds_dwordx4 v[206:207], off
	v_lshl_add_u64 v[206:207], v[214:215], 0, s[98:99]
	s_mov_b32 m0, s4
	s_nop 0
	global_load_lds_dwordx4 v[206:207], off
	v_lshl_add_u64 v[206:207], v[216:217], 0, s[98:99]
	s_add_i32 m0, s4, 0x2000
	s_nop 0
	global_load_lds_dwordx4 v[206:207], off
	v_lshl_add_u64 v[206:207], v[218:219], 0, s[98:99]
	s_mov_b32 m0, s10
	s_nop 0
	global_load_lds_dwordx4 v[206:207], off
	v_lshl_add_u64 v[206:207], v[220:221], 0, s[98:99]
	s_mov_b32 m0, s11
	s_nop 0
	global_load_lds_dwordx4 v[206:207], off
	s_waitcnt vmcnt(8)
	s_waitcnt lgkmcnt(0)
	s_barrier
	s_waitcnt lgkmcnt(0)
	v_mfma_f32_16x16x32_bf16 v[62:65], v[98:101], v[162:165], v[62:65]
	v_mfma_f32_16x16x32_bf16 v[62:65], v[102:105], v[166:169], v[62:65]
	v_mfma_f32_16x16x32_bf16 v[58:61], v[114:117], v[162:165], v[58:61]
	v_mfma_f32_16x16x32_bf16 v[58:61], v[122:125], v[166:169], v[58:61]
	v_mfma_f32_16x16x32_bf16 v[42:45], v[114:117], v[170:173], v[42:45]
	v_mfma_f32_16x16x32_bf16 v[42:45], v[122:125], v[174:177], v[42:45]
	v_mfma_f32_16x16x32_bf16 v[46:49], v[98:101], v[170:173], v[46:49]
	v_mfma_f32_16x16x32_bf16 v[46:49], v[102:105], v[174:177], v[46:49]
	v_mfma_f32_16x16x32_bf16 v[30:33], v[98:101], v[178:181], v[30:33]
	v_mfma_f32_16x16x32_bf16 v[30:33], v[102:105], v[182:185], v[30:33]
	v_mfma_f32_16x16x32_bf16 v[26:29], v[114:117], v[178:181], v[26:29]
	v_mfma_f32_16x16x32_bf16 v[26:29], v[122:125], v[182:185], v[26:29]
	v_mfma_f32_16x16x32_bf16 v[10:13], v[114:117], v[186:189], v[10:13]
	v_mfma_f32_16x16x32_bf16 v[10:13], v[122:125], v[190:193], v[10:13]
	v_mfma_f32_16x16x32_bf16 v[14:17], v[98:101], v[186:189], v[14:17]
	v_mfma_f32_16x16x32_bf16 v[14:17], v[102:105], v[190:193], v[14:17]
	v_mfma_f32_16x16x32_bf16 v[54:57], v[130:133], v[162:165], v[54:57]
	v_mfma_f32_16x16x32_bf16 v[54:57], v[138:141], v[166:169], v[54:57]
	v_mfma_f32_16x16x32_bf16 v[50:53], v[146:149], v[162:165], v[50:53]
	v_mfma_f32_16x16x32_bf16 v[50:53], v[154:157], v[166:169], v[50:53]
	v_mfma_f32_16x16x32_bf16 v[34:37], v[146:149], v[170:173], v[34:37]
	v_mfma_f32_16x16x32_bf16 v[34:37], v[154:157], v[174:177], v[34:37]
	v_mfma_f32_16x16x32_bf16 v[38:41], v[130:133], v[170:173], v[38:41]
	v_mfma_f32_16x16x32_bf16 v[38:41], v[138:141], v[174:177], v[38:41]
	v_mfma_f32_16x16x32_bf16 v[22:25], v[130:133], v[178:181], v[22:25]
	v_mfma_f32_16x16x32_bf16 v[22:25], v[138:141], v[182:185], v[22:25]
	v_mfma_f32_16x16x32_bf16 v[18:21], v[146:149], v[178:181], v[18:21]
	v_mfma_f32_16x16x32_bf16 v[18:21], v[154:157], v[182:185], v[18:21]
	v_mfma_f32_16x16x32_bf16 v[2:5], v[146:149], v[186:189], v[2:5]
	v_mfma_f32_16x16x32_bf16 v[2:5], v[154:157], v[190:193], v[2:5]
	v_mfma_f32_16x16x32_bf16 v[6:9], v[130:133], v[186:189], v[6:9]
	v_mfma_f32_16x16x32_bf16 v[6:9], v[138:141], v[190:193], v[6:9]
	s_barrier
	s_add_u32 s6, s6, s98
	s_addc_u32 s7, s7, 0
	s_add_u32 s6, s6, s98
	s_addc_u32 s7, s7, 0
	s_add_u32 s67, s67, s98
	s_addc_u32 s85, s85, 0
	s_add_u32 s67, s67, s98
	s_addc_u32 s85, s85, 0
	s_cmp_ge_u32 vcc_lo, s69
	s_mov_b32 s8, vcc_lo
	s_cbranch_scc0 .LBB0_175
	s_branch .Lpeelx175
.LBB0_175:
	s_add_i32 vcc_lo, s8, 2
	s_add_u32 s4, s6, s98
	s_addc_u32 s5, s7, 0
	s_add_i32 vcc_hi, 0, 0x10000
	s_cmp_eq_u32 s13, s8
	s_cselect_b32 s9, s1, s5
	s_cselect_b32 s8, s0, s4
	s_cselect_b32 s5, s97, s85
	s_cselect_b32 s4, s96, s67
	s_add_i32 s84, 0, 0x14000
	v_add_u32_e32 v122, vcc_hi, v248
	v_add_u32_e32 v154, s84, v248
	ds_read_b128 v[98:101], v122
	ds_read_b128 v[102:105], v122 offset:1024
	ds_read_b128 v[114:117], v122 offset:2048
	ds_read_b128 v[122:125], v122 offset:3072
	ds_read_b128 v[130:133], v154
	ds_read_b128 v[138:141], v154 offset:1024
	ds_read_b128 v[146:149], v154 offset:2048
	ds_read_b128 v[154:157], v154 offset:3072
	v_lshl_add_u64 v[206:207], s[6:7], 0, v[200:201]
	s_add_i32 m0, s81, 0xc000
	ds_read_b128 v[162:165], v249
	ds_read_b128 v[166:169], v249 offset:1024
	ds_read_b128 v[170:173], v249 offset:2048
	ds_read_b128 v[174:177], v249 offset:3072
	ds_read_b128 v[178:181], v249 offset:4096
	ds_read_b128 v[182:185], v249 offset:5120
	ds_read_b128 v[186:189], v249 offset:6144
	ds_read_b128 v[190:193], v249 offset:7168
	global_load_lds_dwordx4 v[206:207], off
	v_lshl_add_u64 v[206:207], s[6:7], 0, v[210:211]
	s_add_i32 m0, s81, 0xe000
	s_nop 0
	global_load_lds_dwordx4 v[206:207], off
	s_waitcnt vmcnt(8)
	s_waitcnt lgkmcnt(0)
	s_barrier
; #define PG8_STAGE(bufoff, gbase, voff) do { _Pragma("unroll") for (int _i = 0; _i < 2; ++_i) \
;         __builtin_amdgcn_global_load_lds((const unsigned*)((const char*)(gbase) + (voff)[_i]), (PG8_LAS unsigned*)(lds + (bufoff) + ldsw + _i * 8192), 16, 0, 0); } while (0)
; #define PG8_LDA(dst, b, h) do { _Pragma("unroll") for (int m = 0; m < 4; ++m) _Pragma("unroll") for (int k = 0; k < 2; ++k) dst[m][k] = *(const PG8_LAS bf16x8*)(lds + PG8_SA(b, h) + aoff + m * 2048 + k * 1024); } while (0)
; #define PG8_MMA(ai, bj, At, Bt) do { __builtin_amdgcn_s_setprio(1); _Pragma("unroll") for (int m = 0; m < 4; ++m) _Pragma("unroll") for (int n = 0; n < 2; ++n) _Pragma("unroll") for (int k = 0; k < 2; ++k) \
;         acc[ai][bj][m][n] = mma16<Epi::I8>(Bt[n][k], At[m][k], acc[ai][bj][m][n]); __builtin_amdgcn_s_setprio(0); } while (0)
; #define PG8_WAIT_V(n) asm volatile("s_waitcnt vmcnt(" #n ")" ::: "memory")
; #define PG8_WAIT_L(n) asm volatile("s_waitcnt lgkmcnt(" #n ")" ::: "memory")
; #define PG8_BAR __builtin_amdgcn_s_barrier()
; #define PG8_SCHED __builtin_amdgcn_sched_barrier(0)
; template <class Epi, class Sched, bool ALIGN_EPI = false, bool SP2 = false>
; __device__ __forceinline__ void gemm_phase(PG8_LAS unsigned char* lds, const Gemm g, const Sched& S, const Epi& E) {
;     ...
;             PG8_WAIT_V(8); PG8_WAIT_L(0); PG8_BAR; PG8_MMA(0, 0, At, B0); PG8_MMA(0, 1, At, B1); PG8_BAR; PG8_SCHED;
;             PG8_LDA(At, 0, 1); PG8_STAGE(PG8_SB(0, 0), b2, voffB); PG8_STAGE(PG8_SB(0, 1), b2 + hstep, voffB); PG8_STAGE(PG8_SA(0, 0), a2, voffA);
;             PG8_WAIT_V(8); PG8_WAIT_L(0); PG8_BAR; PG8_MMA(1, 0, At, B0); PG8_MMA(1, 1, At, B1); PG8_BAR; PG8_SCHED;
	s_waitcnt lgkmcnt(0)
	v_mfma_f32_16x16x32_bf16 v[158:161], v[98:101], v[162:165], v[158:161]
	v_mfma_f32_16x16x32_bf16 v[158:161], v[102:105], v[166:169], v[158:161]
	v_mfma_f32_16x16x32_bf16 v[150:153], v[114:117], v[162:165], v[150:153]
	v_mfma_f32_16x16x32_bf16 v[150:153], v[122:125], v[166:169], v[150:153]
	v_mfma_f32_16x16x32_bf16 v[118:121], v[114:117], v[170:173], v[118:121]
	v_mfma_f32_16x16x32_bf16 v[118:121], v[122:125], v[174:177], v[118:121]
	v_mfma_f32_16x16x32_bf16 v[126:129], v[98:101], v[170:173], v[126:129]
	v_mfma_f32_16x16x32_bf16 v[126:129], v[102:105], v[174:177], v[126:129]
	v_mfma_f32_16x16x32_bf16 v[94:97], v[98:101], v[178:181], v[94:97]
	v_mfma_f32_16x16x32_bf16 v[94:97], v[102:105], v[182:185], v[94:97]
	v_mfma_f32_16x16x32_bf16 v[90:93], v[114:117], v[178:181], v[90:93]
	v_mfma_f32_16x16x32_bf16 v[90:93], v[122:125], v[182:185], v[90:93]
	v_mfma_f32_16x16x32_bf16 v[74:77], v[114:117], v[186:189], v[74:77]
	v_mfma_f32_16x16x32_bf16 v[74:77], v[122:125], v[190:193], v[74:77]
	v_mfma_f32_16x16x32_bf16 v[78:81], v[98:101], v[186:189], v[78:81]
	v_mfma_f32_16x16x32_bf16 v[78:81], v[102:105], v[190:193], v[78:81]
	v_mfma_f32_16x16x32_bf16 v[142:145], v[130:133], v[162:165], v[142:145]
	v_mfma_f32_16x16x32_bf16 v[142:145], v[138:141], v[166:169], v[142:145]
	v_mfma_f32_16x16x32_bf16 v[134:137], v[146:149], v[162:165], v[134:137]
	v_mfma_f32_16x16x32_bf16 v[134:137], v[154:157], v[166:169], v[134:137]
	v_mfma_f32_16x16x32_bf16 v[106:109], v[146:149], v[170:173], v[106:109]
	v_mfma_f32_16x16x32_bf16 v[106:109], v[154:157], v[174:177], v[106:109]
	v_mfma_f32_16x16x32_bf16 v[110:113], v[130:133], v[170:173], v[110:113]
	v_mfma_f32_16x16x32_bf16 v[110:113], v[138:141], v[174:177], v[110:113]
	v_mfma_f32_16x16x32_bf16 v[86:89], v[130:133], v[178:181], v[86:89]
	v_mfma_f32_16x16x32_bf16 v[86:89], v[138:141], v[182:185], v[86:89]
	v_mfma_f32_16x16x32_bf16 v[82:85], v[146:149], v[178:181], v[82:85]
	v_mfma_f32_16x16x32_bf16 v[82:85], v[154:157], v[182:185], v[82:85]
	v_mfma_f32_16x16x32_bf16 v[66:69], v[146:149], v[186:189], v[66:69]
	v_mfma_f32_16x16x32_bf16 v[66:69], v[154:157], v[190:193], v[66:69]
	v_mfma_f32_16x16x32_bf16 v[70:73], v[130:133], v[186:189], v[70:73]
	v_mfma_f32_16x16x32_bf16 v[70:73], v[138:141], v[190:193], v[70:73]
	s_barrier
	s_add_i32 vcc_hi, vcc_hi, s80
	v_lshl_add_u64 v[206:207], s[4:5], 0, v[0:1]
	s_mov_b32 m0, vcc_hi
	ds_read_b128 v[162:165], v249 offset:16384
	ds_read_b128 v[166:169], v249 offset:17408
	ds_read_b128 v[170:173], v249 offset:18432
	ds_read_b128 v[174:177], v249 offset:19456
	ds_read_b128 v[178:181], v249 offset:20480
	ds_read_b128 v[182:185], v249 offset:21504
	ds_read_b128 v[186:189], v249 offset:22528
	ds_read_b128 v[190:193], v249 offset:23552
	global_load_lds_dwordx4 v[206:207], off
	s_add_i32 m0, vcc_hi, 0x2000
	v_lshl_add_u64 v[212:213], s[4:5], 0, v[198:199]
	s_add_u32 s4, s4, s100
	s_addc_u32 s5, s5, 0
	s_add_i32 s84, s84, s80
	global_load_lds_dwordx4 v[212:213], off
	v_lshl_add_u64 v[214:215], s[4:5], 0, v[0:1]
	s_mov_b32 m0, s84
	v_lshl_add_u64 v[216:217], s[4:5], 0, v[198:199]
	global_load_lds_dwordx4 v[214:215], off
	s_add_i32 m0, s84, 0x2000
	v_lshl_add_u64 v[218:219], s[8:9], 0, v[194:195]
	global_load_lds_dwordx4 v[216:217], off
	s_mov_b32 m0, s81
	v_lshl_add_u64 v[220:221], s[8:9], 0, v[196:197]
	global_load_lds_dwordx4 v[218:219], off
	s_mov_b32 m0, s70
	s_nop 0
	global_load_lds_dwordx4 v[220:221], off
	s_waitcnt vmcnt(8)
	s_waitcnt lgkmcnt(0)
	s_barrier
	s_waitcnt lgkmcnt(0)
	v_mfma_f32_16x16x32_bf16 v[62:65], v[98:101], v[162:165], v[62:65]
	v_mfma_f32_16x16x32_bf16 v[62:65], v[102:105], v[166:169], v[62:65]
	v_mfma_f32_16x16x32_bf16 v[58:61], v[114:117], v[162:165], v[58:61]
	v_mfma_f32_16x16x32_bf16 v[58:61], v[122:125], v[166:169], v[58:61]
	v_mfma_f32_16x16x32_bf16 v[42:45], v[114:117], v[170:173], v[42:45]
	v_mfma_f32_16x16x32_bf16 v[42:45], v[122:125], v[174:177], v[42:45]
	v_mfma_f32_16x16x32_bf16 v[46:49], v[98:101], v[170:173], v[46:49]
	v_mfma_f32_16x16x32_bf16 v[46:49], v[102:105], v[174:177], v[46:49]
	v_mfma_f32_16x16x32_bf16 v[30:33], v[98:101], v[178:181], v[30:33]
	v_mfma_f32_16x16x32_bf16 v[30:33], v[102:105], v[182:185], v[30:33]
	v_mfma_f32_16x16x32_bf16 v[26:29], v[114:117], v[178:181], v[26:29]
	v_mfma_f32_16x16x32_bf16 v[26:29], v[122:125], v[182:185], v[26:29]
	v_mfma_f32_16x16x32_bf16 v[10:13], v[114:117], v[186:189], v[10:13]
	v_mfma_f32_16x16x32_bf16 v[10:13], v[122:125], v[190:193], v[10:13]
	v_mfma_f32_16x16x32_bf16 v[14:17], v[98:101], v[186:189], v[14:17]
	v_mfma_f32_16x16x32_bf16 v[14:17], v[102:105], v[190:193], v[14:17]
	v_mfma_f32_16x16x32_bf16 v[54:57], v[130:133], v[162:165], v[54:57]
	v_mfma_f32_16x16x32_bf16 v[54:57], v[138:141], v[166:169], v[54:57]
	v_mfma_f32_16x16x32_bf16 v[50:53], v[146:149], v[162:165], v[50:53]
	v_mfma_f32_16x16x32_bf16 v[50:53], v[154:157], v[166:169], v[50:53]
	v_mfma_f32_16x16x32_bf16 v[34:37], v[146:149], v[170:173], v[34:37]
	v_mfma_f32_16x16x32_bf16 v[34:37], v[154:157], v[174:177], v[34:37]
	v_mfma_f32_16x16x32_bf16 v[38:41], v[130:133], v[170:173], v[38:41]
	v_mfma_f32_16x16x32_bf16 v[38:41], v[138:141], v[174:177], v[38:41]
	v_mfma_f32_16x16x32_bf16 v[22:25], v[130:133], v[178:181], v[22:25]
	v_mfma_f32_16x16x32_bf16 v[22:25], v[138:141], v[182:185], v[22:25]
	v_mfma_f32_16x16x32_bf16 v[18:21], v[146:149], v[178:181], v[18:21]
	v_mfma_f32_16x16x32_bf16 v[18:21], v[154:157], v[182:185], v[18:21]
	v_mfma_f32_16x16x32_bf16 v[2:5], v[146:149], v[186:189], v[2:5]
	v_mfma_f32_16x16x32_bf16 v[2:5], v[154:157], v[190:193], v[2:5]
	v_mfma_f32_16x16x32_bf16 v[6:9], v[130:133], v[186:189], v[6:9]
	v_mfma_f32_16x16x32_bf16 v[6:9], v[138:141], v[190:193], v[6:9]
	s_barrier
; #define PG8_STAGE(bufoff, gbase, voff) do { _Pragma("unroll") for (int _i = 0; _i < 2; ++_i) \
;         __builtin_amdgcn_global_load_lds((const unsigned*)((const char*)(gbase) + (voff)[_i]), (PG8_LAS unsigned*)(lds + (bufoff) + ldsw + _i * 8192), 16, 0, 0); } while (0)
; #define PG8_LDA(dst, b, h) do { _Pragma("unroll") for (int m = 0; m < 4; ++m) _Pragma("unroll") for (int k = 0; k < 2; ++k) dst[m][k] = *(const PG8_LAS bf16x8*)(lds + PG8_SA(b, h) + aoff + m * 2048 + k * 1024); } while (0)
; #define PG8_LDB(dst, b, h) do { _Pragma("unroll") for (int n = 0; n < 2; ++n) _Pragma("unroll") for (int k = 0; k < 2; ++k) dst[n][k] = *(const PG8_LAS bf16x8*)(lds + PG8_SB(b, h) + boff + n * 2048 + k * 1024); } while (0)
; #define PG8_MMA(ai, bj, At, Bt) do { __builtin_amdgcn_s_setprio(1); _Pragma("unroll") for (int m = 0; m < 4; ++m) _Pragma("unroll") for (int n = 0; n < 2; ++n) _Pragma("unroll") for (int k = 0; k < 2; ++k) \
;         acc[ai][bj][m][n] = mma16<Epi::I8>(Bt[n][k], At[m][k], acc[ai][bj][m][n]); __builtin_amdgcn_s_setprio(0); } while (0)
; #define PG8_WAIT_V(n) asm volatile("s_waitcnt vmcnt(" #n ")" ::: "memory")
; #define PG8_WAIT_L(n) asm volatile("s_waitcnt lgkmcnt(" #n ")" ::: "memory")
; #define PG8_BAR __builtin_amdgcn_s_barrier()
; #define PG8_SCHED __builtin_amdgcn_sched_barrier(0)
; template <class Epi, class Sched, bool ALIGN_EPI = false, bool SP2 = false>
; __device__ __forceinline__ void gemm_phase(PG8_LAS unsigned char* lds, const Gemm g, const Sched& S, const Epi& E) {
;     ...
;             PG8_LDB(B0, 1, 0); PG8_LDB(B1, 1, 1); PG8_SCHED; PG8_LDA(At, 1, 0); PG8_STAGE(PG8_SA(0, 1), a2 + hstep, voffA);
;             PG8_WAIT_V(8); PG8_WAIT_L(0); PG8_BAR; PG8_MMA(0, 0, At, B0); PG8_MMA(0, 1, At, B1); PG8_BAR; PG8_SCHED;
	s_add_i32 s84, 0, 0x18000
	s_add_i32 vcc_hi, 0, 0x1c000
	v_add_u32_e32 v122, s84, v248
	v_add_u32_e32 v154, vcc_hi, v248
	ds_read_b128 v[98:101], v122
	ds_read_b128 v[102:105], v122 offset:1024
	ds_read_b128 v[114:117], v122 offset:2048
	ds_read_b128 v[122:125], v122 offset:3072
	ds_read_b128 v[130:133], v154
	ds_read_b128 v[138:141], v154 offset:1024
	ds_read_b128 v[146:149], v154 offset:2048
	ds_read_b128 v[154:157], v154 offset:3072
	s_add_u32 s4, s8, s100
	s_addc_u32 s5, s9, 0
	s_mov_b32 m0, s71
	v_lshl_add_u64 v[222:223], s[4:5], 0, v[194:195]
	ds_read_b128 v[162:165], v249 offset:32768
	ds_read_b128 v[166:169], v249 offset:33792
	ds_read_b128 v[170:173], v249 offset:34816
	ds_read_b128 v[174:177], v249 offset:35840
	ds_read_b128 v[178:181], v249 offset:36864
	ds_read_b128 v[182:185], v249 offset:37888
	ds_read_b128 v[186:189], v249 offset:38912
	ds_read_b128 v[190:193], v249 offset:39936
	global_load_lds_dwordx4 v[222:223], off
	v_lshl_add_u64 v[222:223], s[4:5], 0, v[196:197]
	s_mov_b32 m0, s12
	s_nop 0
	global_load_lds_dwordx4 v[222:223], off
	s_waitcnt vmcnt(8)
	s_waitcnt lgkmcnt(0)
	s_barrier
	s_waitcnt lgkmcnt(0)
	v_mfma_f32_16x16x32_bf16 v[158:161], v[98:101], v[162:165], v[158:161]
	v_mfma_f32_16x16x32_bf16 v[158:161], v[102:105], v[166:169], v[158:161]
	v_mfma_f32_16x16x32_bf16 v[150:153], v[114:117], v[162:165], v[150:153]
	v_mfma_f32_16x16x32_bf16 v[150:153], v[122:125], v[166:169], v[150:153]
	v_mfma_f32_16x16x32_bf16 v[118:121], v[114:117], v[170:173], v[118:121]
	v_mfma_f32_16x16x32_bf16 v[118:121], v[122:125], v[174:177], v[118:121]
	v_mfma_f32_16x16x32_bf16 v[126:129], v[98:101], v[170:173], v[126:129]
	v_mfma_f32_16x16x32_bf16 v[126:129], v[102:105], v[174:177], v[126:129]
	v_mfma_f32_16x16x32_bf16 v[94:97], v[98:101], v[178:181], v[94:97]
	v_mfma_f32_16x16x32_bf16 v[94:97], v[102:105], v[182:185], v[94:97]
	v_mfma_f32_16x16x32_bf16 v[90:93], v[114:117], v[178:181], v[90:93]
	v_mfma_f32_16x16x32_bf16 v[90:93], v[122:125], v[182:185], v[90:93]
	v_mfma_f32_16x16x32_bf16 v[74:77], v[114:117], v[186:189], v[74:77]
	v_mfma_f32_16x16x32_bf16 v[74:77], v[122:125], v[190:193], v[74:77]
	v_mfma_f32_16x16x32_bf16 v[78:81], v[98:101], v[186:189], v[78:81]
	v_mfma_f32_16x16x32_bf16 v[78:81], v[102:105], v[190:193], v[78:81]
	v_mfma_f32_16x16x32_bf16 v[142:145], v[130:133], v[162:165], v[142:145]
	v_mfma_f32_16x16x32_bf16 v[142:145], v[138:141], v[166:169], v[142:145]
	v_mfma_f32_16x16x32_bf16 v[134:137], v[146:149], v[162:165], v[134:137]
	v_mfma_f32_16x16x32_bf16 v[134:137], v[154:157], v[166:169], v[134:137]
	v_mfma_f32_16x16x32_bf16 v[106:109], v[146:149], v[170:173], v[106:109]
	v_mfma_f32_16x16x32_bf16 v[106:109], v[154:157], v[174:177], v[106:109]
	v_mfma_f32_16x16x32_bf16 v[110:113], v[130:133], v[170:173], v[110:113]
	v_mfma_f32_16x16x32_bf16 v[110:113], v[138:141], v[174:177], v[110:113]
	v_mfma_f32_16x16x32_bf16 v[86:89], v[130:133], v[178:181], v[86:89]
	v_mfma_f32_16x16x32_bf16 v[86:89], v[138:141], v[182:185], v[86:89]
	v_mfma_f32_16x16x32_bf16 v[82:85], v[146:149], v[178:181], v[82:85]
	v_mfma_f32_16x16x32_bf16 v[82:85], v[154:157], v[182:185], v[82:85]
	v_mfma_f32_16x16x32_bf16 v[66:69], v[146:149], v[186:189], v[66:69]
	v_mfma_f32_16x16x32_bf16 v[66:69], v[154:157], v[190:193], v[66:69]
	v_mfma_f32_16x16x32_bf16 v[70:73], v[130:133], v[186:189], v[70:73]
	v_mfma_f32_16x16x32_bf16 v[70:73], v[138:141], v[190:193], v[70:73]
	s_barrier
; #define PG8_STAGE(bufoff, gbase, voff) do { _Pragma("unroll") for (int _i = 0; _i < 2; ++_i) \
;         __builtin_amdgcn_global_load_lds((const unsigned*)((const char*)(gbase) + (voff)[_i]), (PG8_LAS unsigned*)(lds + (bufoff) + ldsw + _i * 8192), 16, 0, 0); } while (0)
; #define PG8_LDA(dst, b, h) do { _Pragma("unroll") for (int m = 0; m < 4; ++m) _Pragma("unroll") for (int k = 0; k < 2; ++k) dst[m][k] = *(const PG8_LAS bf16x8*)(lds + PG8_SA(b, h) + aoff + m * 2048 + k * 1024); } while (0)
; #define PG8_MMA(ai, bj, At, Bt) do { __builtin_amdgcn_s_setprio(1); _Pragma("unroll") for (int m = 0; m < 4; ++m) _Pragma("unroll") for (int n = 0; n < 2; ++n) _Pragma("unroll") for (int k = 0; k < 2; ++k) \
;         acc[ai][bj][m][n] = mma16<Epi::I8>(Bt[n][k], At[m][k], acc[ai][bj][m][n]); __builtin_amdgcn_s_setprio(0); } while (0)
; #define PG8_WAIT_V(n) asm volatile("s_waitcnt vmcnt(" #n ")" ::: "memory")
; #define PG8_WAIT_L(n) asm volatile("s_waitcnt lgkmcnt(" #n ")" ::: "memory")
; #define PG8_BAR __builtin_amdgcn_s_barrier()
; #define PG8_SCHED __builtin_amdgcn_sched_barrier(0)
; template <class Epi, class Sched, bool ALIGN_EPI = false, bool SP2 = false>
; __device__ __forceinline__ void gemm_phase(PG8_LAS unsigned char* lds, const Gemm g, const Sched& S, const Epi& E) {
;     ...
;             PG8_LDA(At, 1, 1); PG8_STAGE(PG8_SB(1, 0), b3, voffB); PG8_STAGE(PG8_SB(1, 1), b3 + hstep, voffB); PG8_STAGE(PG8_SA(1, 0), a3, voffA);
;             PG8_WAIT_V(8); PG8_WAIT_L(0); PG8_BAR; PG8_MMA(1, 0, At, B0); PG8_MMA(1, 1, At, B1); PG8_BAR; PG8_SCHED;
	s_add_i32 s4, s84, s80
	v_lshl_add_u64 v[206:207], v[206:207], 0, s[98:99]
	s_mov_b32 m0, s4
	ds_read_b128 v[162:165], v249 offset:49152
	ds_read_b128 v[166:169], v249 offset:50176
	ds_read_b128 v[170:173], v249 offset:51200
	ds_read_b128 v[174:177], v249 offset:52224
	ds_read_b128 v[178:181], v249 offset:53248
	ds_read_b128 v[182:185], v249 offset:54272
	ds_read_b128 v[186:189], v249 offset:55296
	ds_read_b128 v[190:193], v249 offset:56320
	global_load_lds_dwordx4 v[206:207], off
	v_lshl_add_u64 v[206:207], v[212:213], 0, s[98:99]
	s_add_i32 m0, s4, 0x2000
	s_add_i32 s4, vcc_hi, s80
	global_load_lds_dwordx4 v[206:207], off
	v_lshl_add_u64 v[206:207], v[214:215], 0, s[98:99]
	s_mov_b32 m0, s4
	s_nop 0
	global_load_lds_dwordx4 v[206:207], off
	v_lshl_add_u64 v[206:207], v[216:217], 0, s[98:99]
	s_add_i32 m0, s4, 0x2000
	s_nop 0
	global_load_lds_dwordx4 v[206:207], off
	v_lshl_add_u64 v[206:207], v[218:219], 0, s[98:99]
	s_mov_b32 m0, s10
	s_nop 0
	global_load_lds_dwordx4 v[206:207], off
	v_lshl_add_u64 v[206:207], v[220:221], 0, s[98:99]
	s_mov_b32 m0, s11
	s_nop 0
	global_load_lds_dwordx4 v[206:207], off
	s_waitcnt vmcnt(8)
	s_waitcnt lgkmcnt(0)
	s_barrier
	s_waitcnt lgkmcnt(0)
	v_mfma_f32_16x16x32_bf16 v[62:65], v[98:101], v[162:165], v[62:65]
	v_mfma_f32_16x16x32_bf16 v[62:65], v[102:105], v[166:169], v[62:65]
	v_mfma_f32_16x16x32_bf16 v[58:61], v[114:117], v[162:165], v[58:61]
	v_mfma_f32_16x16x32_bf16 v[58:61], v[122:125], v[166:169], v[58:61]
	v_mfma_f32_16x16x32_bf16 v[42:45], v[114:117], v[170:173], v[42:45]
	v_mfma_f32_16x16x32_bf16 v[42:45], v[122:125], v[174:177], v[42:45]
	v_mfma_f32_16x16x32_bf16 v[46:49], v[98:101], v[170:173], v[46:49]
	v_mfma_f32_16x16x32_bf16 v[46:49], v[102:105], v[174:177], v[46:49]
	v_mfma_f32_16x16x32_bf16 v[30:33], v[98:101], v[178:181], v[30:33]
	v_mfma_f32_16x16x32_bf16 v[30:33], v[102:105], v[182:185], v[30:33]
	v_mfma_f32_16x16x32_bf16 v[26:29], v[114:117], v[178:181], v[26:29]
	v_mfma_f32_16x16x32_bf16 v[26:29], v[122:125], v[182:185], v[26:29]
	v_mfma_f32_16x16x32_bf16 v[10:13], v[114:117], v[186:189], v[10:13]
	v_mfma_f32_16x16x32_bf16 v[10:13], v[122:125], v[190:193], v[10:13]
	v_mfma_f32_16x16x32_bf16 v[14:17], v[98:101], v[186:189], v[14:17]
	v_mfma_f32_16x16x32_bf16 v[14:17], v[102:105], v[190:193], v[14:17]
	v_mfma_f32_16x16x32_bf16 v[54:57], v[130:133], v[162:165], v[54:57]
	v_mfma_f32_16x16x32_bf16 v[54:57], v[138:141], v[166:169], v[54:57]
	v_mfma_f32_16x16x32_bf16 v[50:53], v[146:149], v[162:165], v[50:53]
	v_mfma_f32_16x16x32_bf16 v[50:53], v[154:157], v[166:169], v[50:53]
	v_mfma_f32_16x16x32_bf16 v[34:37], v[146:149], v[170:173], v[34:37]
	v_mfma_f32_16x16x32_bf16 v[34:37], v[154:157], v[174:177], v[34:37]
	v_mfma_f32_16x16x32_bf16 v[38:41], v[130:133], v[170:173], v[38:41]
	v_mfma_f32_16x16x32_bf16 v[38:41], v[138:141], v[174:177], v[38:41]
	v_mfma_f32_16x16x32_bf16 v[22:25], v[130:133], v[178:181], v[22:25]
	v_mfma_f32_16x16x32_bf16 v[22:25], v[138:141], v[182:185], v[22:25]
	v_mfma_f32_16x16x32_bf16 v[18:21], v[146:149], v[178:181], v[18:21]
	v_mfma_f32_16x16x32_bf16 v[18:21], v[154:157], v[182:185], v[18:21]
	v_mfma_f32_16x16x32_bf16 v[2:5], v[146:149], v[186:189], v[2:5]
	v_mfma_f32_16x16x32_bf16 v[2:5], v[154:157], v[190:193], v[2:5]
	v_mfma_f32_16x16x32_bf16 v[6:9], v[130:133], v[186:189], v[6:9]
	v_mfma_f32_16x16x32_bf16 v[6:9], v[138:141], v[190:193], v[6:9]
	s_barrier
	s_add_u32 s6, s6, s98
	s_addc_u32 s7, s7, 0
	s_add_u32 s6, s6, s98
	s_addc_u32 s7, s7, 0
	s_add_u32 s67, s67, s98
	s_addc_u32 s85, s85, 0
	s_add_u32 s67, s67, s98
	s_addc_u32 s85, s85, 0
	s_cmp_ge_u32 vcc_lo, s69
	s_mov_b32 s8, vcc_lo
	s_cbranch_scc0 .LBB0_175

; #define PG8_STAGE(bufoff, gbase, voff) do { _Pragma("unroll") for (int _i = 0; _i < 2; ++_i) \
;         __builtin_amdgcn_global_load_lds((const unsigned*)((const char*)(gbase) + (voff)[_i]), (PG8_LAS unsigned*)(lds + (bufoff) + ldsw + _i * 8192), 16, 0, 0); } while (0)
; #define PG8_LDA(dst, b, h) do { _Pragma("unroll") for (int m = 0; m < 4; ++m) _Pragma("unroll") for (int k = 0; k < 2; ++k) dst[m][k] = *(const PG8_LAS bf16x8*)(lds + PG8_SA(b, h) + aoff + m * 2048 + k * 1024); } while (0)
; #define PG8_LDB(dst, b, h) do { _Pragma("unroll") for (int n = 0; n < 2; ++n) _Pragma("unroll") for (int k = 0; k < 2; ++k) dst[n][k] = *(const PG8_LAS bf16x8*)(lds + PG8_SB(b, h) + boff + n * 2048 + k * 1024); } while (0)
; #define PG8_MMA(ai, bj, At, Bt) do { __builtin_amdgcn_s_setprio(1); _Pragma("unroll") for (int m = 0; m < 4; ++m) _Pragma("unroll") for (int n = 0; n < 2; ++n) _Pragma("unroll") for (int k = 0; k < 2; ++k) \
;         acc[ai][bj][m][n] = mma16<Epi::I8>(Bt[n][k], At[m][k], acc[ai][bj][m][n]); __builtin_amdgcn_s_setprio(0); } while (0)
; #define PG8_WAIT_V(n) asm volatile("s_waitcnt vmcnt(" #n ")" ::: "memory")
; #define PG8_WAIT_L(n) asm volatile("s_waitcnt lgkmcnt(" #n ")" ::: "memory")
; #define PG8_BAR __builtin_amdgcn_s_barrier()
; #define PG8_SCHED __builtin_amdgcn_sched_barrier(0)
; template <class Epi, class Sched, bool ALIGN_EPI = false, bool SP2 = false>
; __device__ __forceinline__ void gemm_phase(PG8_LAS unsigned char* lds, const Gemm g, const Sched& S, const Epi& E) {
;     ...
;             const char* a1 = cA + (size_t)(t + 1) * kstep;
;             const char* a2 = last ? nA : cA + (size_t)(t + 2) * kstep; const char* b2 = last ? nB : cB + (size_t)(t + 2) * kstep;
;             const char* a3 = a2 + kstep; const char* b3 = b2 + kstep;
;             if (last && has_next) S.a_ready(nxt);
;             if constexpr (SP2) {
;             PG8_LDB(B0, 0, 0); PG8_LDB(B1, 0, 1); PG8_SCHED; PG8_LDA(At, 0, 0); PG8_STAGE(PG8_SA(1, 1), a1 + hstep, voffA);
;             PG8_WAIT_V(8); PG8_WAIT_L(0); PG8_BAR; PG8_MMA(0, 0, At, B0); PG8_MMA(0, 1, At, B1); PG8_BAR; PG8_SCHED;
;             PG8_LDA(At, 0, 1); PG8_STAGE(PG8_SB(0, 0), b2, voffB); PG8_STAGE(PG8_SB(0, 1), b2 + hstep, voffB); PG8_STAGE(PG8_SA(0, 0), a2, voffA);
;             PG8_WAIT_V(8); PG8_WAIT_L(0); PG8_BAR; PG8_MMA(1, 0, At, B0); PG8_MMA(1, 1, At, B1); PG8_BAR; PG8_SCHED;
.Lpeel291:
	s_add_u32 s84, s8, 0x100
	s_addc_u32 s85, s9, 0
	s_add_i32 s66, 0, 0x10000
	s_cmp_eq_u32 s10, 12
	s_cselect_b32 vcc_hi, s5, s85
	s_cselect_b32 vcc_lo, s7, s84
	s_cselect_b32 s97, s11, s68
	s_cselect_b32 s96, s67, s69
	s_add_i32 s70, 0, 0x14000
	v_add_u32_e32 v110, s66, v175
	v_add_u32_e32 v168, s70, v175
	s_waitcnt vmcnt(0)
	ds_read_b128 v[66:69], v110
	ds_read_b128 v[70:73], v110 offset:1024
	ds_read_b128 v[106:109], v110 offset:2048
	ds_read_b128 v[110:113], v110 offset:3072
	ds_read_b128 v[114:117], v168
	ds_read_b128 v[118:121], v168 offset:1024
	ds_read_b128 v[126:129], v168 offset:2048
	ds_read_b128 v[178:181], v168 offset:3072
	v_lshl_add_u64 v[168:169], s[8:9], 0, v[164:165]
	s_add_i32 m0, s1, 0xc000
	ds_read_b128 v[182:185], v177
	ds_read_b128 v[186:189], v177 offset:1024
	ds_read_b128 v[190:193], v177 offset:2048
	ds_read_b128 v[194:197], v177 offset:3072
	ds_read_b128 v[198:201], v177 offset:4096
	ds_read_b128 v[210:213], v177 offset:5120
	ds_read_b128 v[214:217], v177 offset:6144
	ds_read_b128 v[218:221], v177 offset:7168
	global_load_lds_dwordx4 v[168:169], off
	v_lshl_add_u64 v[168:169], s[8:9], 0, v[166:167]
	s_add_i32 m0, s1, 0xe000
	s_nop 0
	global_load_lds_dwordx4 v[168:169], off
	s_waitcnt vmcnt(8)
	s_waitcnt lgkmcnt(0)
	s_barrier
	s_waitcnt lgkmcnt(0)
	v_mfma_i32_16x16x64_i8 v[154:157], v[66:69], v[182:185], 0
	v_mfma_i32_16x16x64_i8 v[154:157], v[70:73], v[186:189], v[154:157]
	v_mfma_i32_16x16x64_i8 v[146:149], v[106:109], v[182:185], 0
	v_mfma_i32_16x16x64_i8 v[146:149], v[110:113], v[186:189], v[146:149]
	v_mfma_i32_16x16x64_i8 v[138:141], v[106:109], v[190:193], 0
	v_mfma_i32_16x16x64_i8 v[138:141], v[110:113], v[194:197], v[138:141]
	v_mfma_i32_16x16x64_i8 v[150:153], v[66:69], v[190:193], 0
	v_mfma_i32_16x16x64_i8 v[150:153], v[70:73], v[194:197], v[150:153]
	v_mfma_i32_16x16x64_i8 v[142:145], v[66:69], v[198:201], 0
	v_mfma_i32_16x16x64_i8 v[142:145], v[70:73], v[210:213], v[142:145]
	v_mfma_i32_16x16x64_i8 v[130:133], v[106:109], v[198:201], 0
	v_mfma_i32_16x16x64_i8 v[130:133], v[110:113], v[210:213], v[130:133]
	v_mfma_i32_16x16x64_i8 v[122:125], v[106:109], v[214:217], 0
	v_mfma_i32_16x16x64_i8 v[122:125], v[110:113], v[218:221], v[122:125]
	v_mfma_i32_16x16x64_i8 v[134:137], v[66:69], v[214:217], 0
	v_mfma_i32_16x16x64_i8 v[134:137], v[70:73], v[218:221], v[134:137]
	v_mfma_i32_16x16x64_i8 v[102:105], v[114:117], v[182:185], 0
	v_mfma_i32_16x16x64_i8 v[102:105], v[118:121], v[186:189], v[102:105]
	v_mfma_i32_16x16x64_i8 v[94:97], v[126:129], v[182:185], 0
	v_mfma_i32_16x16x64_i8 v[94:97], v[178:181], v[186:189], v[94:97]
	v_mfma_i32_16x16x64_i8 v[86:89], v[126:129], v[190:193], 0
	v_mfma_i32_16x16x64_i8 v[86:89], v[178:181], v[194:197], v[86:89]
	v_mfma_i32_16x16x64_i8 v[98:101], v[114:117], v[190:193], 0
	v_mfma_i32_16x16x64_i8 v[98:101], v[118:121], v[194:197], v[98:101]
	v_mfma_i32_16x16x64_i8 v[90:93], v[114:117], v[198:201], 0
	v_mfma_i32_16x16x64_i8 v[90:93], v[118:121], v[210:213], v[90:93]
	v_mfma_i32_16x16x64_i8 v[78:81], v[126:129], v[198:201], 0
	v_mfma_i32_16x16x64_i8 v[78:81], v[178:181], v[210:213], v[78:81]
	v_mfma_i32_16x16x64_i8 v[74:77], v[126:129], v[214:217], 0
	v_mfma_i32_16x16x64_i8 v[74:77], v[178:181], v[218:221], v[74:77]
	v_mfma_i32_16x16x64_i8 v[82:85], v[114:117], v[214:217], 0
	v_mfma_i32_16x16x64_i8 v[82:85], v[118:121], v[218:221], v[82:85]
	s_barrier
	s_add_i32 s8, s66, s81
	v_lshl_add_u64 v[168:169], s[96:97], 0, v[0:1]
	s_mov_b32 m0, s8
	ds_read_b128 v[182:185], v177 offset:16384
	ds_read_b128 v[186:189], v177 offset:17408
	ds_read_b128 v[190:193], v177 offset:18432
	ds_read_b128 v[194:197], v177 offset:19456
	ds_read_b128 v[198:201], v177 offset:20480
	ds_read_b128 v[210:213], v177 offset:21504
	ds_read_b128 v[214:217], v177 offset:22528
	ds_read_b128 v[218:221], v177 offset:23552
	global_load_lds_dwordx4 v[168:169], off
	s_add_i32 m0, s8, 0x2000
	s_add_u32 s8, s96, 0x40000
	v_lshl_add_u64 v[206:207], s[96:97], 0, v[158:159]
	s_addc_u32 s9, s97, 0
	s_add_i32 s66, s70, s81
	global_load_lds_dwordx4 v[206:207], off
	v_lshl_add_u64 v[222:223], s[8:9], 0, v[0:1]
	s_mov_b32 m0, s66
	v_lshl_add_u64 v[224:225], vcc, 0, v[160:161]
	global_load_lds_dwordx4 v[222:223], off
	v_lshl_add_u64 v[222:223], s[8:9], 0, v[158:159]
	s_add_i32 m0, s66, 0x2000
	s_nop 0
	global_load_lds_dwordx4 v[222:223], off
	v_lshl_add_u64 v[222:223], vcc, 0, v[162:163]
	s_mov_b32 m0, s1
	s_nop 0
	global_load_lds_dwordx4 v[222:223], off
	s_mov_b32 m0, s58
	s_nop 0
	global_load_lds_dwordx4 v[224:225], off
	s_waitcnt vmcnt(8)
	s_waitcnt lgkmcnt(0)
	s_barrier
	s_waitcnt lgkmcnt(0)
	v_mfma_i32_16x16x64_i8 v[62:65], v[66:69], v[182:185], 0
	v_mfma_i32_16x16x64_i8 v[62:65], v[70:73], v[186:189], v[62:65]
	v_mfma_i32_16x16x64_i8 v[54:57], v[106:109], v[182:185], 0
	v_mfma_i32_16x16x64_i8 v[54:57], v[110:113], v[186:189], v[54:57]
	v_mfma_i32_16x16x64_i8 v[46:49], v[106:109], v[190:193], 0
	v_mfma_i32_16x16x64_i8 v[46:49], v[110:113], v[194:197], v[46:49]
	v_mfma_i32_16x16x64_i8 v[58:61], v[66:69], v[190:193], 0
	v_mfma_i32_16x16x64_i8 v[58:61], v[70:73], v[194:197], v[58:61]
	v_mfma_i32_16x16x64_i8 v[50:53], v[66:69], v[198:201], 0
	v_mfma_i32_16x16x64_i8 v[50:53], v[70:73], v[210:213], v[50:53]
	v_mfma_i32_16x16x64_i8 v[38:41], v[106:109], v[198:201], 0
	v_mfma_i32_16x16x64_i8 v[38:41], v[110:113], v[210:213], v[38:41]
	v_mfma_i32_16x16x64_i8 v[34:37], v[106:109], v[214:217], 0
	v_mfma_i32_16x16x64_i8 v[34:37], v[110:113], v[218:221], v[34:37]
	v_mfma_i32_16x16x64_i8 v[42:45], v[66:69], v[214:217], 0
	v_mfma_i32_16x16x64_i8 v[42:45], v[70:73], v[218:221], v[42:45]
	v_mfma_i32_16x16x64_i8 v[30:33], v[114:117], v[182:185], 0
	v_mfma_i32_16x16x64_i8 v[30:33], v[118:121], v[186:189], v[30:33]
	v_mfma_i32_16x16x64_i8 v[22:25], v[126:129], v[182:185], 0
	v_mfma_i32_16x16x64_i8 v[22:25], v[178:181], v[186:189], v[22:25]
	v_mfma_i32_16x16x64_i8 v[14:17], v[126:129], v[190:193], 0
	v_mfma_i32_16x16x64_i8 v[14:17], v[178:181], v[194:197], v[14:17]
	v_mfma_i32_16x16x64_i8 v[26:29], v[114:117], v[190:193], 0
	v_mfma_i32_16x16x64_i8 v[26:29], v[118:121], v[194:197], v[26:29]
	v_mfma_i32_16x16x64_i8 v[18:21], v[114:117], v[198:201], 0
	v_mfma_i32_16x16x64_i8 v[18:21], v[118:121], v[210:213], v[18:21]
	v_mfma_i32_16x16x64_i8 v[6:9], v[126:129], v[198:201], 0
	v_mfma_i32_16x16x64_i8 v[6:9], v[178:181], v[210:213], v[6:9]
	v_mfma_i32_16x16x64_i8 v[2:5], v[126:129], v[214:217], 0
	v_mfma_i32_16x16x64_i8 v[2:5], v[178:181], v[218:221], v[2:5]
	v_mfma_i32_16x16x64_i8 v[10:13], v[114:117], v[214:217], 0
	v_mfma_i32_16x16x64_i8 v[10:13], v[118:121], v[218:221], v[10:13]
	s_barrier
; #define PG8_STAGE(bufoff, gbase, voff) do { _Pragma("unroll") for (int _i = 0; _i < 2; ++_i) \
;         __builtin_amdgcn_global_load_lds((const unsigned*)((const char*)(gbase) + (voff)[_i]), (PG8_LAS unsigned*)(lds + (bufoff) + ldsw + _i * 8192), 16, 0, 0); } while (0)
; #define PG8_LDA(dst, b, h) do { _Pragma("unroll") for (int m = 0; m < 4; ++m) _Pragma("unroll") for (int k = 0; k < 2; ++k) dst[m][k] = *(const PG8_LAS bf16x8*)(lds + PG8_SA(b, h) + aoff + m * 2048 + k * 1024); } while (0)
; #define PG8_LDB(dst, b, h) do { _Pragma("unroll") for (int n = 0; n < 2; ++n) _Pragma("unroll") for (int k = 0; k < 2; ++k) dst[n][k] = *(const PG8_LAS bf16x8*)(lds + PG8_SB(b, h) + boff + n * 2048 + k * 1024); } while (0)
; #define PG8_MMA(ai, bj, At, Bt) do { __builtin_amdgcn_s_setprio(1); _Pragma("unroll") for (int m = 0; m < 4; ++m) _Pragma("unroll") for (int n = 0; n < 2; ++n) _Pragma("unroll") for (int k = 0; k < 2; ++k) \
;         acc[ai][bj][m][n] = mma16<Epi::I8>(Bt[n][k], At[m][k], acc[ai][bj][m][n]); __builtin_amdgcn_s_setprio(0); } while (0)
; #define PG8_WAIT_V(n) asm volatile("s_waitcnt vmcnt(" #n ")" ::: "memory")
; #define PG8_WAIT_L(n) asm volatile("s_waitcnt lgkmcnt(" #n ")" ::: "memory")
; #define PG8_BAR __builtin_amdgcn_s_barrier()
; template <class Epi, class Sched, bool ALIGN_EPI = false, bool SP2 = false>
; __device__ __forceinline__ void gemm_phase(PG8_LAS unsigned char* lds, const Gemm g, const Sched& S, const Epi& E) {
;     ...
;         for (int t = 0; t < nt; t += 2) {
;             const bool last = (t == nt - 2);
;             const char* a1 = cA + (size_t)(t + 1) * kstep;
;             const char* a2 = last ? nA : cA + (size_t)(t + 2) * kstep; const char* b2 = last ? nB : cB + (size_t)(t + 2) * kstep;
;             const char* a3 = a2 + kstep; const char* b3 = b2 + kstep;
;             if (last && has_next) S.a_ready(nxt);
;     ...
;             PG8_LDB(B0, 1, 0); PG8_LDB(B1, 1, 1); PG8_SCHED; PG8_LDA(At, 1, 0); PG8_STAGE(PG8_SA(0, 1), a2 + hstep, voffA);
;             PG8_WAIT_V(8); PG8_WAIT_L(0); PG8_BAR; PG8_MMA(0, 0, At, B0); PG8_MMA(0, 1, At, B1); PG8_BAR; PG8_SCHED;
;             PG8_LDA(At, 1, 1); PG8_STAGE(PG8_SB(1, 0), b3, voffB); PG8_STAGE(PG8_SB(1, 1), b3 + hstep, voffB); PG8_STAGE(PG8_SA(1, 0), a3, voffA);
;             PG8_WAIT_V(8); PG8_WAIT_L(0); PG8_BAR; PG8_MMA(1, 0, At, B0); PG8_MMA(1, 1, At, B1); PG8_BAR; PG8_SCHED;
	s_add_i32 s66, 0, 0x18000
	s_add_i32 s70, 0, 0x1c000
	v_add_u32_e32 v110, s66, v175
	v_add_u32_e32 v170, s70, v175
	ds_read_b128 v[66:69], v110
	ds_read_b128 v[70:73], v110 offset:1024
	ds_read_b128 v[106:109], v110 offset:2048
	ds_read_b128 v[110:113], v110 offset:3072
	ds_read_b128 v[114:117], v170
	ds_read_b128 v[118:121], v170 offset:1024
	ds_read_b128 v[126:129], v170 offset:2048
	ds_read_b128 v[178:181], v170 offset:3072
	s_add_u32 s8, vcc_lo, 0x40000
	s_addc_u32 s9, vcc_hi, 0
	s_mov_b32 m0, s80
	v_lshl_add_u64 v[226:227], s[8:9], 0, v[162:163]
	ds_read_b128 v[182:185], v177 offset:32768
	ds_read_b128 v[186:189], v177 offset:33792
	ds_read_b128 v[190:193], v177 offset:34816
	ds_read_b128 v[194:197], v177 offset:35840
	ds_read_b128 v[198:201], v177 offset:36864
	ds_read_b128 v[210:213], v177 offset:37888
	ds_read_b128 v[214:217], v177 offset:38912
	ds_read_b128 v[218:221], v177 offset:39936
	global_load_lds_dwordx4 v[226:227], off
	v_lshl_add_u64 v[226:227], s[8:9], 0, v[160:161]
	s_mov_b32 m0, s0
	s_nop 0
	global_load_lds_dwordx4 v[226:227], off
	s_waitcnt vmcnt(8)
	s_waitcnt lgkmcnt(0)
	s_barrier
	s_waitcnt lgkmcnt(0)
	v_mfma_i32_16x16x64_i8 v[154:157], v[66:69], v[182:185], v[154:157]
	v_mfma_i32_16x16x64_i8 v[154:157], v[70:73], v[186:189], v[154:157]
	v_mfma_i32_16x16x64_i8 v[146:149], v[106:109], v[182:185], v[146:149]
	v_mfma_i32_16x16x64_i8 v[146:149], v[110:113], v[186:189], v[146:149]
	v_mfma_i32_16x16x64_i8 v[138:141], v[106:109], v[190:193], v[138:141]
	v_mfma_i32_16x16x64_i8 v[138:141], v[110:113], v[194:197], v[138:141]
	v_mfma_i32_16x16x64_i8 v[150:153], v[66:69], v[190:193], v[150:153]
	v_mfma_i32_16x16x64_i8 v[150:153], v[70:73], v[194:197], v[150:153]
	v_mfma_i32_16x16x64_i8 v[142:145], v[66:69], v[198:201], v[142:145]
	v_mfma_i32_16x16x64_i8 v[142:145], v[70:73], v[210:213], v[142:145]
	v_mfma_i32_16x16x64_i8 v[130:133], v[106:109], v[198:201], v[130:133]
	v_mfma_i32_16x16x64_i8 v[130:133], v[110:113], v[210:213], v[130:133]
	v_mfma_i32_16x16x64_i8 v[122:125], v[106:109], v[214:217], v[122:125]
	v_mfma_i32_16x16x64_i8 v[122:125], v[110:113], v[218:221], v[122:125]
	v_mfma_i32_16x16x64_i8 v[134:137], v[66:69], v[214:217], v[134:137]
	v_mfma_i32_16x16x64_i8 v[134:137], v[70:73], v[218:221], v[134:137]
	v_mfma_i32_16x16x64_i8 v[102:105], v[114:117], v[182:185], v[102:105]
	v_mfma_i32_16x16x64_i8 v[102:105], v[118:121], v[186:189], v[102:105]
	v_mfma_i32_16x16x64_i8 v[94:97], v[126:129], v[182:185], v[94:97]
	v_mfma_i32_16x16x64_i8 v[94:97], v[178:181], v[186:189], v[94:97]
	v_mfma_i32_16x16x64_i8 v[86:89], v[126:129], v[190:193], v[86:89]
	v_mfma_i32_16x16x64_i8 v[86:89], v[178:181], v[194:197], v[86:89]
	v_mfma_i32_16x16x64_i8 v[98:101], v[114:117], v[190:193], v[98:101]
	v_mfma_i32_16x16x64_i8 v[98:101], v[118:121], v[194:197], v[98:101]
	v_mfma_i32_16x16x64_i8 v[90:93], v[114:117], v[198:201], v[90:93]
	v_mfma_i32_16x16x64_i8 v[90:93], v[118:121], v[210:213], v[90:93]
	v_mfma_i32_16x16x64_i8 v[78:81], v[126:129], v[198:201], v[78:81]
	v_mfma_i32_16x16x64_i8 v[78:81], v[178:181], v[210:213], v[78:81]
	v_mfma_i32_16x16x64_i8 v[74:77], v[126:129], v[214:217], v[74:77]
	v_mfma_i32_16x16x64_i8 v[74:77], v[178:181], v[218:221], v[74:77]
	v_mfma_i32_16x16x64_i8 v[82:85], v[114:117], v[214:217], v[82:85]
	v_mfma_i32_16x16x64_i8 v[82:85], v[118:121], v[218:221], v[82:85]
	s_barrier
	s_add_i32 s8, s66, s81
	v_lshl_add_u64 v[168:169], v[168:169], 0, s[92:93]
	s_mov_b32 m0, s8
	ds_read_b128 v[182:185], v177 offset:49152
	ds_read_b128 v[186:189], v177 offset:50176
	ds_read_b128 v[190:193], v177 offset:51200
	ds_read_b128 v[194:197], v177 offset:52224
	ds_read_b128 v[198:201], v177 offset:53248
	ds_read_b128 v[210:213], v177 offset:54272
	ds_read_b128 v[214:217], v177 offset:55296
	ds_read_b128 v[218:221], v177 offset:56320
	global_load_lds_dwordx4 v[168:169], off
	s_add_i32 m0, s8, 0x2000
	s_add_u32 s8, s96, 0x40080
	v_lshl_add_u64 v[168:169], v[206:207], 0, s[92:93]
	s_addc_u32 s9, s97, 0
	s_add_i32 s66, s70, s81
	global_load_lds_dwordx4 v[168:169], off
	v_lshl_add_u64 v[168:169], s[8:9], 0, v[0:1]
	s_mov_b32 m0, s66
	s_nop 0
	global_load_lds_dwordx4 v[168:169], off
	v_lshl_add_u64 v[168:169], s[8:9], 0, v[158:159]
	s_add_i32 m0, s66, 0x2000
	s_nop 0
	global_load_lds_dwordx4 v[168:169], off
	v_lshl_add_u64 v[168:169], v[222:223], 0, s[92:93]
	s_mov_b32 m0, s13
	s_nop 0
	global_load_lds_dwordx4 v[168:169], off
	v_lshl_add_u64 v[168:169], v[224:225], 0, s[92:93]
	s_mov_b32 m0, s12
	s_nop 0
	global_load_lds_dwordx4 v[168:169], off
	s_waitcnt vmcnt(8)
	s_waitcnt lgkmcnt(0)
	s_barrier
	s_waitcnt lgkmcnt(0)
	v_mfma_i32_16x16x64_i8 v[62:65], v[66:69], v[182:185], v[62:65]
	v_mfma_i32_16x16x64_i8 v[62:65], v[70:73], v[186:189], v[62:65]
	v_mfma_i32_16x16x64_i8 v[54:57], v[106:109], v[182:185], v[54:57]
	v_mfma_i32_16x16x64_i8 v[54:57], v[110:113], v[186:189], v[54:57]
	v_mfma_i32_16x16x64_i8 v[46:49], v[106:109], v[190:193], v[46:49]
	v_mfma_i32_16x16x64_i8 v[46:49], v[110:113], v[194:197], v[46:49]
	v_mfma_i32_16x16x64_i8 v[58:61], v[66:69], v[190:193], v[58:61]
	v_mfma_i32_16x16x64_i8 v[58:61], v[70:73], v[194:197], v[58:61]
	v_mfma_i32_16x16x64_i8 v[50:53], v[66:69], v[198:201], v[50:53]
	v_mfma_i32_16x16x64_i8 v[50:53], v[70:73], v[210:213], v[50:53]
	v_mfma_i32_16x16x64_i8 v[38:41], v[106:109], v[198:201], v[38:41]
	v_mfma_i32_16x16x64_i8 v[38:41], v[110:113], v[210:213], v[38:41]
	v_mfma_i32_16x16x64_i8 v[34:37], v[106:109], v[214:217], v[34:37]
	v_mfma_i32_16x16x64_i8 v[34:37], v[110:113], v[218:221], v[34:37]
	v_mfma_i32_16x16x64_i8 v[42:45], v[66:69], v[214:217], v[42:45]
	v_mfma_i32_16x16x64_i8 v[42:45], v[70:73], v[218:221], v[42:45]
	v_mfma_i32_16x16x64_i8 v[30:33], v[114:117], v[182:185], v[30:33]
	v_mfma_i32_16x16x64_i8 v[30:33], v[118:121], v[186:189], v[30:33]
	v_mfma_i32_16x16x64_i8 v[22:25], v[126:129], v[182:185], v[22:25]
	v_mfma_i32_16x16x64_i8 v[22:25], v[178:181], v[186:189], v[22:25]
	v_mfma_i32_16x16x64_i8 v[14:17], v[126:129], v[190:193], v[14:17]
	v_mfma_i32_16x16x64_i8 v[14:17], v[178:181], v[194:197], v[14:17]
	v_mfma_i32_16x16x64_i8 v[26:29], v[114:117], v[190:193], v[26:29]
	v_mfma_i32_16x16x64_i8 v[26:29], v[118:121], v[194:197], v[26:29]
	v_mfma_i32_16x16x64_i8 v[18:21], v[114:117], v[198:201], v[18:21]
	v_mfma_i32_16x16x64_i8 v[18:21], v[118:121], v[210:213], v[18:21]
	v_mfma_i32_16x16x64_i8 v[6:9], v[126:129], v[198:201], v[6:9]
	v_mfma_i32_16x16x64_i8 v[6:9], v[178:181], v[210:213], v[6:9]
	v_mfma_i32_16x16x64_i8 v[2:5], v[126:129], v[214:217], v[2:5]
	v_mfma_i32_16x16x64_i8 v[2:5], v[178:181], v[218:221], v[2:5]
	v_mfma_i32_16x16x64_i8 v[10:13], v[114:117], v[214:217], v[10:13]
	v_mfma_i32_16x16x64_i8 v[10:13], v[118:121], v[218:221], v[10:13]
	s_barrier
	s_add_i32 s10, s10, 2
	s_add_u32 s69, s69, 0x100
	s_addc_u32 s68, s68, 0
	s_cmp_gt_u32 s10, 13
	s_mov_b64 s[8:9], s[84:85]
	s_cbranch_scc0 .LBB0_291
	s_branch .Lpeelx291
; #define PG8_STAGE(bufoff, gbase, voff) do { _Pragma("unroll") for (int _i = 0; _i < 2; ++_i) \
;         __builtin_amdgcn_global_load_lds((const unsigned*)((const char*)(gbase) + (voff)[_i]), (PG8_LAS unsigned*)(lds + (bufoff) + ldsw + _i * 8192), 16, 0, 0); } while (0)
; #define PG8_LDA(dst, b, h) do { _Pragma("unroll") for (int m = 0; m < 4; ++m) _Pragma("unroll") for (int k = 0; k < 2; ++k) dst[m][k] = *(const PG8_LAS bf16x8*)(lds + PG8_SA(b, h) + aoff + m * 2048 + k * 1024); } while (0)
; #define PG8_LDB(dst, b, h) do { _Pragma("unroll") for (int n = 0; n < 2; ++n) _Pragma("unroll") for (int k = 0; k < 2; ++k) dst[n][k] = *(const PG8_LAS bf16x8*)(lds + PG8_SB(b, h) + boff + n * 2048 + k * 1024); } while (0)
; #define PG8_MMA(ai, bj, At, Bt) do { __builtin_amdgcn_s_setprio(1); _Pragma("unroll") for (int m = 0; m < 4; ++m) _Pragma("unroll") for (int n = 0; n < 2; ++n) _Pragma("unroll") for (int k = 0; k < 2; ++k) \
;         acc[ai][bj][m][n] = mma16<Epi::I8>(Bt[n][k], At[m][k], acc[ai][bj][m][n]); __builtin_amdgcn_s_setprio(0); } while (0)
; #define PG8_WAIT_V(n) asm volatile("s_waitcnt vmcnt(" #n ")" ::: "memory")
; template <class Epi, class Sched, bool ALIGN_EPI = false, bool SP2 = false>
; __device__ __forceinline__ void gemm_phase(PG8_LAS unsigned char* lds, const Gemm g, const Sched& S, const Epi& E) {
;     ...
;         const bool has_next = S.next(ui + 1, nxt);
;         const char* nA = has_next ? (const char*)g.A + (size_t)nxt.pm * tstep : cA; const char* nB = has_next ? (const char*)g.Bt + (size_t)nxt.pn * tstep : cB;
;         for (int t = 0; t < nt; t += 2) {
;             const bool last = (t == nt - 2);
;             const char* a1 = cA + (size_t)(t + 1) * kstep;
;             const char* a2 = last ? nA : cA + (size_t)(t + 2) * kstep; const char* b2 = last ? nB : cB + (size_t)(t + 2) * kstep;
;             const char* a3 = a2 + kstep; const char* b3 = b2 + kstep;
;             if (last && has_next) S.a_ready(nxt);
;             if constexpr (SP2) {
;             PG8_LDB(B0, 0, 0); PG8_LDB(B1, 0, 1); PG8_SCHED; PG8_LDA(At, 0, 0); PG8_STAGE(PG8_SA(1, 1), a1 + hstep, voffA);
;             PG8_WAIT_V(8); PG8_WAIT_L(0); PG8_BAR; PG8_MMA(0, 0, At, B0); PG8_MMA(0, 1, At, B1); PG8_BAR; PG8_SCHED;
;             PG8_LDA(At, 0, 1); PG8_STAGE(PG8_SB(0, 0), b2, voffB); PG8_STAGE(PG8_SB(0, 1), b2 + hstep, voffB); PG8_STAGE(PG8_SA(0, 0), a2, voffA);
.LBB0_291:
	s_add_u32 s84, s8, 0x100
	s_addc_u32 s85, s9, 0
	s_add_i32 s66, 0, 0x10000
	s_cmp_eq_u32 s10, 12
	s_cselect_b32 vcc_hi, s5, s85
	s_cselect_b32 vcc_lo, s7, s84
	s_cselect_b32 s97, s11, s68
	s_cselect_b32 s96, s67, s69
	s_add_i32 s70, 0, 0x14000
	v_add_u32_e32 v110, s66, v175
	v_add_u32_e32 v168, s70, v175
	s_waitcnt vmcnt(0)
	ds_read_b128 v[66:69], v110
	ds_read_b128 v[70:73], v110 offset:1024
	ds_read_b128 v[106:109], v110 offset:2048
	ds_read_b128 v[110:113], v110 offset:3072
	ds_read_b128 v[114:117], v168
	ds_read_b128 v[118:121], v168 offset:1024
	ds_read_b128 v[126:129], v168 offset:2048
	ds_read_b128 v[178:181], v168 offset:3072
	v_lshl_add_u64 v[168:169], s[8:9], 0, v[164:165]
	s_add_i32 m0, s1, 0xc000
	ds_read_b128 v[182:185], v177
	ds_read_b128 v[186:189], v177 offset:1024
	ds_read_b128 v[190:193], v177 offset:2048
	ds_read_b128 v[194:197], v177 offset:3072
	ds_read_b128 v[198:201], v177 offset:4096
	ds_read_b128 v[210:213], v177 offset:5120
	ds_read_b128 v[214:217], v177 offset:6144
	ds_read_b128 v[218:221], v177 offset:7168
	global_load_lds_dwordx4 v[168:169], off
	v_lshl_add_u64 v[168:169], s[8:9], 0, v[166:167]
	s_add_i32 m0, s1, 0xe000
	s_nop 0
	global_load_lds_dwordx4 v[168:169], off
	s_waitcnt vmcnt(8)
	s_waitcnt lgkmcnt(0)
	s_barrier
	s_waitcnt lgkmcnt(0)
	v_mfma_i32_16x16x64_i8 v[154:157], v[66:69], v[182:185], v[154:157]
	v_mfma_i32_16x16x64_i8 v[154:157], v[70:73], v[186:189], v[154:157]
	v_mfma_i32_16x16x64_i8 v[146:149], v[106:109], v[182:185], v[146:149]
	v_mfma_i32_16x16x64_i8 v[146:149], v[110:113], v[186:189], v[146:149]
	v_mfma_i32_16x16x64_i8 v[138:141], v[106:109], v[190:193], v[138:141]
	v_mfma_i32_16x16x64_i8 v[138:141], v[110:113], v[194:197], v[138:141]
	v_mfma_i32_16x16x64_i8 v[150:153], v[66:69], v[190:193], v[150:153]
	v_mfma_i32_16x16x64_i8 v[150:153], v[70:73], v[194:197], v[150:153]
	v_mfma_i32_16x16x64_i8 v[142:145], v[66:69], v[198:201], v[142:145]
	v_mfma_i32_16x16x64_i8 v[142:145], v[70:73], v[210:213], v[142:145]
	v_mfma_i32_16x16x64_i8 v[130:133], v[106:109], v[198:201], v[130:133]
	v_mfma_i32_16x16x64_i8 v[130:133], v[110:113], v[210:213], v[130:133]
	v_mfma_i32_16x16x64_i8 v[122:125], v[106:109], v[214:217], v[122:125]
	v_mfma_i32_16x16x64_i8 v[122:125], v[110:113], v[218:221], v[122:125]
	v_mfma_i32_16x16x64_i8 v[134:137], v[66:69], v[214:217], v[134:137]
	v_mfma_i32_16x16x64_i8 v[134:137], v[70:73], v[218:221], v[134:137]
	v_mfma_i32_16x16x64_i8 v[102:105], v[114:117], v[182:185], v[102:105]
	v_mfma_i32_16x16x64_i8 v[102:105], v[118:121], v[186:189], v[102:105]
	v_mfma_i32_16x16x64_i8 v[94:97], v[126:129], v[182:185], v[94:97]
	v_mfma_i32_16x16x64_i8 v[94:97], v[178:181], v[186:189], v[94:97]
	v_mfma_i32_16x16x64_i8 v[86:89], v[126:129], v[190:193], v[86:89]
	v_mfma_i32_16x16x64_i8 v[86:89], v[178:181], v[194:197], v[86:89]
	v_mfma_i32_16x16x64_i8 v[98:101], v[114:117], v[190:193], v[98:101]
	v_mfma_i32_16x16x64_i8 v[98:101], v[118:121], v[194:197], v[98:101]
	v_mfma_i32_16x16x64_i8 v[90:93], v[114:117], v[198:201], v[90:93]
	v_mfma_i32_16x16x64_i8 v[90:93], v[118:121], v[210:213], v[90:93]
	v_mfma_i32_16x16x64_i8 v[78:81], v[126:129], v[198:201], v[78:81]
	v_mfma_i32_16x16x64_i8 v[78:81], v[178:181], v[210:213], v[78:81]
	v_mfma_i32_16x16x64_i8 v[74:77], v[126:129], v[214:217], v[74:77]
	v_mfma_i32_16x16x64_i8 v[74:77], v[178:181], v[218:221], v[74:77]
	v_mfma_i32_16x16x64_i8 v[82:85], v[114:117], v[214:217], v[82:85]
	v_mfma_i32_16x16x64_i8 v[82:85], v[118:121], v[218:221], v[82:85]
	s_barrier
	s_add_i32 s8, s66, s81
	v_lshl_add_u64 v[168:169], s[96:97], 0, v[0:1]
	s_mov_b32 m0, s8
	ds_read_b128 v[182:185], v177 offset:16384
	ds_read_b128 v[186:189], v177 offset:17408
	ds_read_b128 v[190:193], v177 offset:18432
	ds_read_b128 v[194:197], v177 offset:19456
	ds_read_b128 v[198:201], v177 offset:20480
	ds_read_b128 v[210:213], v177 offset:21504
	ds_read_b128 v[214:217], v177 offset:22528
	ds_read_b128 v[218:221], v177 offset:23552
	global_load_lds_dwordx4 v[168:169], off
	s_add_i32 m0, s8, 0x2000
	s_add_u32 s8, s96, 0x40000
	v_lshl_add_u64 v[206:207], s[96:97], 0, v[158:159]
	s_addc_u32 s9, s97, 0
	s_add_i32 s66, s70, s81
	global_load_lds_dwordx4 v[206:207], off
	v_lshl_add_u64 v[222:223], s[8:9], 0, v[0:1]
	s_mov_b32 m0, s66
	v_lshl_add_u64 v[224:225], vcc, 0, v[160:161]
	global_load_lds_dwordx4 v[222:223], off
	v_lshl_add_u64 v[222:223], s[8:9], 0, v[158:159]
	s_add_i32 m0, s66, 0x2000
	s_nop 0
	global_load_lds_dwordx4 v[222:223], off
	v_lshl_add_u64 v[222:223], vcc, 0, v[162:163]
	s_mov_b32 m0, s1
	s_nop 0
	global_load_lds_dwordx4 v[222:223], off
	s_mov_b32 m0, s58
	s_nop 0
	global_load_lds_dwordx4 v[224:225], off
	s_waitcnt vmcnt(8)
	s_waitcnt lgkmcnt(0)
	s_barrier
; #define PG8_STAGE(bufoff, gbase, voff) do { _Pragma("unroll") for (int _i = 0; _i < 2; ++_i) \
;         __builtin_amdgcn_global_load_lds((const unsigned*)((const char*)(gbase) + (voff)[_i]), (PG8_LAS unsigned*)(lds + (bufoff) + ldsw + _i * 8192), 16, 0, 0); } while (0)
; #define PG8_LDA(dst, b, h) do { _Pragma("unroll") for (int m = 0; m < 4; ++m) _Pragma("unroll") for (int k = 0; k < 2; ++k) dst[m][k] = *(const PG8_LAS bf16x8*)(lds + PG8_SA(b, h) + aoff + m * 2048 + k * 1024); } while (0)
; #define PG8_LDB(dst, b, h) do { _Pragma("unroll") for (int n = 0; n < 2; ++n) _Pragma("unroll") for (int k = 0; k < 2; ++k) dst[n][k] = *(const PG8_LAS bf16x8*)(lds + PG8_SB(b, h) + boff + n * 2048 + k * 1024); } while (0)
; #define PG8_MMA(ai, bj, At, Bt) do { __builtin_amdgcn_s_setprio(1); _Pragma("unroll") for (int m = 0; m < 4; ++m) _Pragma("unroll") for (int n = 0; n < 2; ++n) _Pragma("unroll") for (int k = 0; k < 2; ++k) \
;         acc[ai][bj][m][n] = mma16<Epi::I8>(Bt[n][k], At[m][k], acc[ai][bj][m][n]); __builtin_amdgcn_s_setprio(0); } while (0)
; #define PG8_WAIT_V(n) asm volatile("s_waitcnt vmcnt(" #n ")" ::: "memory")
; #define PG8_WAIT_L(n) asm volatile("s_waitcnt lgkmcnt(" #n ")" ::: "memory")
; #define PG8_BAR __builtin_amdgcn_s_barrier()
; #define PG8_SCHED __builtin_amdgcn_sched_barrier(0)
; template <class Epi, class Sched, bool ALIGN_EPI = false, bool SP2 = false>
; __device__ __forceinline__ void gemm_phase(PG8_LAS unsigned char* lds, const Gemm g, const Sched& S, const Epi& E) {
;     ...
;             PG8_WAIT_V(8); PG8_WAIT_L(0); PG8_BAR; PG8_MMA(1, 0, At, B0); PG8_MMA(1, 1, At, B1); PG8_BAR; PG8_SCHED;
;             PG8_LDB(B0, 1, 0); PG8_LDB(B1, 1, 1); PG8_SCHED; PG8_LDA(At, 1, 0); PG8_STAGE(PG8_SA(0, 1), a2 + hstep, voffA);
;             PG8_WAIT_V(8); PG8_WAIT_L(0); PG8_BAR; PG8_MMA(0, 0, At, B0); PG8_MMA(0, 1, At, B1); PG8_BAR; PG8_SCHED;
	s_waitcnt lgkmcnt(0)
	v_mfma_i32_16x16x64_i8 v[62:65], v[66:69], v[182:185], v[62:65]
	v_mfma_i32_16x16x64_i8 v[62:65], v[70:73], v[186:189], v[62:65]
	v_mfma_i32_16x16x64_i8 v[54:57], v[106:109], v[182:185], v[54:57]
	v_mfma_i32_16x16x64_i8 v[54:57], v[110:113], v[186:189], v[54:57]
	v_mfma_i32_16x16x64_i8 v[46:49], v[106:109], v[190:193], v[46:49]
	v_mfma_i32_16x16x64_i8 v[46:49], v[110:113], v[194:197], v[46:49]
	v_mfma_i32_16x16x64_i8 v[58:61], v[66:69], v[190:193], v[58:61]
	v_mfma_i32_16x16x64_i8 v[58:61], v[70:73], v[194:197], v[58:61]
	v_mfma_i32_16x16x64_i8 v[50:53], v[66:69], v[198:201], v[50:53]
	v_mfma_i32_16x16x64_i8 v[50:53], v[70:73], v[210:213], v[50:53]
	v_mfma_i32_16x16x64_i8 v[38:41], v[106:109], v[198:201], v[38:41]
	v_mfma_i32_16x16x64_i8 v[38:41], v[110:113], v[210:213], v[38:41]
	v_mfma_i32_16x16x64_i8 v[34:37], v[106:109], v[214:217], v[34:37]
	v_mfma_i32_16x16x64_i8 v[34:37], v[110:113], v[218:221], v[34:37]
	v_mfma_i32_16x16x64_i8 v[42:45], v[66:69], v[214:217], v[42:45]
	v_mfma_i32_16x16x64_i8 v[42:45], v[70:73], v[218:221], v[42:45]
	v_mfma_i32_16x16x64_i8 v[30:33], v[114:117], v[182:185], v[30:33]
	v_mfma_i32_16x16x64_i8 v[30:33], v[118:121], v[186:189], v[30:33]
	v_mfma_i32_16x16x64_i8 v[22:25], v[126:129], v[182:185], v[22:25]
	v_mfma_i32_16x16x64_i8 v[22:25], v[178:181], v[186:189], v[22:25]
	v_mfma_i32_16x16x64_i8 v[14:17], v[126:129], v[190:193], v[14:17]
	v_mfma_i32_16x16x64_i8 v[14:17], v[178:181], v[194:197], v[14:17]
	v_mfma_i32_16x16x64_i8 v[26:29], v[114:117], v[190:193], v[26:29]
	v_mfma_i32_16x16x64_i8 v[26:29], v[118:121], v[194:197], v[26:29]
	v_mfma_i32_16x16x64_i8 v[18:21], v[114:117], v[198:201], v[18:21]
	v_mfma_i32_16x16x64_i8 v[18:21], v[118:121], v[210:213], v[18:21]
	v_mfma_i32_16x16x64_i8 v[6:9], v[126:129], v[198:201], v[6:9]
	v_mfma_i32_16x16x64_i8 v[6:9], v[178:181], v[210:213], v[6:9]
	v_mfma_i32_16x16x64_i8 v[2:5], v[126:129], v[214:217], v[2:5]
	v_mfma_i32_16x16x64_i8 v[2:5], v[178:181], v[218:221], v[2:5]
	v_mfma_i32_16x16x64_i8 v[10:13], v[114:117], v[214:217], v[10:13]
	v_mfma_i32_16x16x64_i8 v[10:13], v[118:121], v[218:221], v[10:13]
	s_barrier
	s_add_i32 s66, 0, 0x18000
	s_add_i32 s70, 0, 0x1c000
	v_add_u32_e32 v110, s66, v175
	v_add_u32_e32 v170, s70, v175
	ds_read_b128 v[66:69], v110
	ds_read_b128 v[70:73], v110 offset:1024
	ds_read_b128 v[106:109], v110 offset:2048
	ds_read_b128 v[110:113], v110 offset:3072
	ds_read_b128 v[114:117], v170
	ds_read_b128 v[118:121], v170 offset:1024
	ds_read_b128 v[126:129], v170 offset:2048
	ds_read_b128 v[178:181], v170 offset:3072
	s_add_u32 s8, vcc_lo, 0x40000
	s_addc_u32 s9, vcc_hi, 0
	s_mov_b32 m0, s80
	v_lshl_add_u64 v[226:227], s[8:9], 0, v[162:163]
	ds_read_b128 v[182:185], v177 offset:32768
	ds_read_b128 v[186:189], v177 offset:33792
	ds_read_b128 v[190:193], v177 offset:34816
	ds_read_b128 v[194:197], v177 offset:35840
	ds_read_b128 v[198:201], v177 offset:36864
	ds_read_b128 v[210:213], v177 offset:37888
	ds_read_b128 v[214:217], v177 offset:38912
	ds_read_b128 v[218:221], v177 offset:39936
	global_load_lds_dwordx4 v[226:227], off
	v_lshl_add_u64 v[226:227], s[8:9], 0, v[160:161]
	s_mov_b32 m0, s0
	s_nop 0
	global_load_lds_dwordx4 v[226:227], off
	s_waitcnt vmcnt(8)
	s_waitcnt lgkmcnt(0)
	s_barrier
	s_waitcnt lgkmcnt(0)
	v_mfma_i32_16x16x64_i8 v[154:157], v[66:69], v[182:185], v[154:157]
	v_mfma_i32_16x16x64_i8 v[154:157], v[70:73], v[186:189], v[154:157]
	v_mfma_i32_16x16x64_i8 v[146:149], v[106:109], v[182:185], v[146:149]
	v_mfma_i32_16x16x64_i8 v[146:149], v[110:113], v[186:189], v[146:149]
	v_mfma_i32_16x16x64_i8 v[138:141], v[106:109], v[190:193], v[138:141]
	v_mfma_i32_16x16x64_i8 v[138:141], v[110:113], v[194:197], v[138:141]
	v_mfma_i32_16x16x64_i8 v[150:153], v[66:69], v[190:193], v[150:153]
	v_mfma_i32_16x16x64_i8 v[150:153], v[70:73], v[194:197], v[150:153]
	v_mfma_i32_16x16x64_i8 v[142:145], v[66:69], v[198:201], v[142:145]
	v_mfma_i32_16x16x64_i8 v[142:145], v[70:73], v[210:213], v[142:145]
	v_mfma_i32_16x16x64_i8 v[130:133], v[106:109], v[198:201], v[130:133]
	v_mfma_i32_16x16x64_i8 v[130:133], v[110:113], v[210:213], v[130:133]
	v_mfma_i32_16x16x64_i8 v[122:125], v[106:109], v[214:217], v[122:125]
	v_mfma_i32_16x16x64_i8 v[122:125], v[110:113], v[218:221], v[122:125]
	v_mfma_i32_16x16x64_i8 v[134:137], v[66:69], v[214:217], v[134:137]
	v_mfma_i32_16x16x64_i8 v[134:137], v[70:73], v[218:221], v[134:137]
	v_mfma_i32_16x16x64_i8 v[102:105], v[114:117], v[182:185], v[102:105]
	v_mfma_i32_16x16x64_i8 v[102:105], v[118:121], v[186:189], v[102:105]
	v_mfma_i32_16x16x64_i8 v[94:97], v[126:129], v[182:185], v[94:97]
	v_mfma_i32_16x16x64_i8 v[94:97], v[178:181], v[186:189], v[94:97]
	v_mfma_i32_16x16x64_i8 v[86:89], v[126:129], v[190:193], v[86:89]
	v_mfma_i32_16x16x64_i8 v[86:89], v[178:181], v[194:197], v[86:89]
	v_mfma_i32_16x16x64_i8 v[98:101], v[114:117], v[190:193], v[98:101]
	v_mfma_i32_16x16x64_i8 v[98:101], v[118:121], v[194:197], v[98:101]
	v_mfma_i32_16x16x64_i8 v[90:93], v[114:117], v[198:201], v[90:93]
	v_mfma_i32_16x16x64_i8 v[90:93], v[118:121], v[210:213], v[90:93]
	v_mfma_i32_16x16x64_i8 v[78:81], v[126:129], v[198:201], v[78:81]
	v_mfma_i32_16x16x64_i8 v[78:81], v[178:181], v[210:213], v[78:81]
	v_mfma_i32_16x16x64_i8 v[74:77], v[126:129], v[214:217], v[74:77]
	v_mfma_i32_16x16x64_i8 v[74:77], v[178:181], v[218:221], v[74:77]
	v_mfma_i32_16x16x64_i8 v[82:85], v[114:117], v[214:217], v[82:85]
	v_mfma_i32_16x16x64_i8 v[82:85], v[118:121], v[218:221], v[82:85]
	s_barrier
; #define PG8_STAGE(bufoff, gbase, voff) do { _Pragma("unroll") for (int _i = 0; _i < 2; ++_i) \
;         __builtin_amdgcn_global_load_lds((const unsigned*)((const char*)(gbase) + (voff)[_i]), (PG8_LAS unsigned*)(lds + (bufoff) + ldsw + _i * 8192), 16, 0, 0); } while (0)
; #define PG8_LDA(dst, b, h) do { _Pragma("unroll") for (int m = 0; m < 4; ++m) _Pragma("unroll") for (int k = 0; k < 2; ++k) dst[m][k] = *(const PG8_LAS bf16x8*)(lds + PG8_SA(b, h) + aoff + m * 2048 + k * 1024); } while (0)
; #define PG8_MMA(ai, bj, At, Bt) do { __builtin_amdgcn_s_setprio(1); _Pragma("unroll") for (int m = 0; m < 4; ++m) _Pragma("unroll") for (int n = 0; n < 2; ++n) _Pragma("unroll") for (int k = 0; k < 2; ++k) \
;         acc[ai][bj][m][n] = mma16<Epi::I8>(Bt[n][k], At[m][k], acc[ai][bj][m][n]); __builtin_amdgcn_s_setprio(0); } while (0)
; #define PG8_WAIT_V(n) asm volatile("s_waitcnt vmcnt(" #n ")" ::: "memory")
; #define PG8_WAIT_L(n) asm volatile("s_waitcnt lgkmcnt(" #n ")" ::: "memory")
; #define PG8_BAR __builtin_amdgcn_s_barrier()
; #define PG8_SCHED __builtin_amdgcn_sched_barrier(0)
; template <class Epi, class Sched, bool ALIGN_EPI = false, bool SP2 = false>
; __device__ __forceinline__ void gemm_phase(PG8_LAS unsigned char* lds, const Gemm g, const Sched& S, const Epi& E) {
;     ...
;         for (int t = 0; t < nt; t += 2) {
;     ...
;             PG8_LDA(At, 1, 1); PG8_STAGE(PG8_SB(1, 0), b3, voffB); PG8_STAGE(PG8_SB(1, 1), b3 + hstep, voffB); PG8_STAGE(PG8_SA(1, 0), a3, voffA);
;             PG8_WAIT_V(8); PG8_WAIT_L(0); PG8_BAR; PG8_MMA(1, 0, At, B0); PG8_MMA(1, 1, At, B1); PG8_BAR; PG8_SCHED;
	s_add_i32 s8, s66, s81
	v_lshl_add_u64 v[168:169], v[168:169], 0, s[92:93]
	s_mov_b32 m0, s8
	ds_read_b128 v[182:185], v177 offset:49152
	ds_read_b128 v[186:189], v177 offset:50176
	ds_read_b128 v[190:193], v177 offset:51200
	ds_read_b128 v[194:197], v177 offset:52224
	ds_read_b128 v[198:201], v177 offset:53248
	ds_read_b128 v[210:213], v177 offset:54272
	ds_read_b128 v[214:217], v177 offset:55296
	ds_read_b128 v[218:221], v177 offset:56320
	global_load_lds_dwordx4 v[168:169], off
	s_add_i32 m0, s8, 0x2000
	s_add_u32 s8, s96, 0x40080
	v_lshl_add_u64 v[168:169], v[206:207], 0, s[92:93]
	s_addc_u32 s9, s97, 0
	s_add_i32 s66, s70, s81
	global_load_lds_dwordx4 v[168:169], off
	v_lshl_add_u64 v[168:169], s[8:9], 0, v[0:1]
	s_mov_b32 m0, s66
	s_nop 0
	global_load_lds_dwordx4 v[168:169], off
	v_lshl_add_u64 v[168:169], s[8:9], 0, v[158:159]
	s_add_i32 m0, s66, 0x2000
	s_nop 0
	global_load_lds_dwordx4 v[168:169], off
	v_lshl_add_u64 v[168:169], v[222:223], 0, s[92:93]
	s_mov_b32 m0, s13
	s_nop 0
	global_load_lds_dwordx4 v[168:169], off
	v_lshl_add_u64 v[168:169], v[224:225], 0, s[92:93]
	s_mov_b32 m0, s12
	s_nop 0
	global_load_lds_dwordx4 v[168:169], off
	s_waitcnt vmcnt(8)
	s_waitcnt lgkmcnt(0)
	s_barrier
	s_waitcnt lgkmcnt(0)
	v_mfma_i32_16x16x64_i8 v[62:65], v[66:69], v[182:185], v[62:65]
	v_mfma_i32_16x16x64_i8 v[62:65], v[70:73], v[186:189], v[62:65]
	v_mfma_i32_16x16x64_i8 v[54:57], v[106:109], v[182:185], v[54:57]
	v_mfma_i32_16x16x64_i8 v[54:57], v[110:113], v[186:189], v[54:57]
	v_mfma_i32_16x16x64_i8 v[46:49], v[106:109], v[190:193], v[46:49]
	v_mfma_i32_16x16x64_i8 v[46:49], v[110:113], v[194:197], v[46:49]
	v_mfma_i32_16x16x64_i8 v[58:61], v[66:69], v[190:193], v[58:61]
	v_mfma_i32_16x16x64_i8 v[58:61], v[70:73], v[194:197], v[58:61]
	v_mfma_i32_16x16x64_i8 v[50:53], v[66:69], v[198:201], v[50:53]
	v_mfma_i32_16x16x64_i8 v[50:53], v[70:73], v[210:213], v[50:53]
	v_mfma_i32_16x16x64_i8 v[38:41], v[106:109], v[198:201], v[38:41]
	v_mfma_i32_16x16x64_i8 v[38:41], v[110:113], v[210:213], v[38:41]
	v_mfma_i32_16x16x64_i8 v[34:37], v[106:109], v[214:217], v[34:37]
	v_mfma_i32_16x16x64_i8 v[34:37], v[110:113], v[218:221], v[34:37]
	v_mfma_i32_16x16x64_i8 v[42:45], v[66:69], v[214:217], v[42:45]
	v_mfma_i32_16x16x64_i8 v[42:45], v[70:73], v[218:221], v[42:45]
	v_mfma_i32_16x16x64_i8 v[30:33], v[114:117], v[182:185], v[30:33]
	v_mfma_i32_16x16x64_i8 v[30:33], v[118:121], v[186:189], v[30:33]
	v_mfma_i32_16x16x64_i8 v[22:25], v[126:129], v[182:185], v[22:25]
	v_mfma_i32_16x16x64_i8 v[22:25], v[178:181], v[186:189], v[22:25]
	v_mfma_i32_16x16x64_i8 v[14:17], v[126:129], v[190:193], v[14:17]
	v_mfma_i32_16x16x64_i8 v[14:17], v[178:181], v[194:197], v[14:17]
	v_mfma_i32_16x16x64_i8 v[26:29], v[114:117], v[190:193], v[26:29]
	v_mfma_i32_16x16x64_i8 v[26:29], v[118:121], v[194:197], v[26:29]
	v_mfma_i32_16x16x64_i8 v[18:21], v[114:117], v[198:201], v[18:21]
	v_mfma_i32_16x16x64_i8 v[18:21], v[118:121], v[210:213], v[18:21]
	v_mfma_i32_16x16x64_i8 v[6:9], v[126:129], v[198:201], v[6:9]
	v_mfma_i32_16x16x64_i8 v[6:9], v[178:181], v[210:213], v[6:9]
	v_mfma_i32_16x16x64_i8 v[2:5], v[126:129], v[214:217], v[2:5]
	v_mfma_i32_16x16x64_i8 v[2:5], v[178:181], v[218:221], v[2:5]
	v_mfma_i32_16x16x64_i8 v[10:13], v[114:117], v[214:217], v[10:13]
	v_mfma_i32_16x16x64_i8 v[10:13], v[118:121], v[218:221], v[10:13]
	s_barrier
	s_add_i32 s10, s10, 2
	s_add_u32 s69, s69, 0x100
	s_addc_u32 s68, s68, 0
	s_cmp_gt_u32 s10, 13
	s_mov_b64 s[8:9], s[84:85]
	s_cbranch_scc0 .LBB0_291

; #define PG8_STAGE(bufoff, gbase, voff) do { _Pragma("unroll") for (int _i = 0; _i < 2; ++_i) \
;         __builtin_amdgcn_global_load_lds((const unsigned*)((const char*)(gbase) + (voff)[_i]), (PG8_LAS unsigned*)(lds + (bufoff) + ldsw + _i * 8192), 16, 0, 0); } while (0)
; #define PG8_LDA(dst, b, h) do { _Pragma("unroll") for (int m = 0; m < 4; ++m) _Pragma("unroll") for (int k = 0; k < 2; ++k) dst[m][k] = *(const PG8_LAS bf16x8*)(lds + PG8_SA(b, h) + aoff + m * 2048 + k * 1024); } while (0)
; #define PG8_LDB(dst, b, h) do { _Pragma("unroll") for (int n = 0; n < 2; ++n) _Pragma("unroll") for (int k = 0; k < 2; ++k) dst[n][k] = *(const PG8_LAS bf16x8*)(lds + PG8_SB(b, h) + boff + n * 2048 + k * 1024); } while (0)
; #define PG8_MMA(ai, bj, At, Bt) do { __builtin_amdgcn_s_setprio(1); _Pragma("unroll") for (int m = 0; m < 4; ++m) _Pragma("unroll") for (int n = 0; n < 2; ++n) _Pragma("unroll") for (int k = 0; k < 2; ++k) \
;         acc[ai][bj][m][n] = mma16<Epi::I8>(Bt[n][k], At[m][k], acc[ai][bj][m][n]); __builtin_amdgcn_s_setprio(0); } while (0)
; #define PG8_WAIT_V(n) asm volatile("s_waitcnt vmcnt(" #n ")" ::: "memory")
; #define PG8_WAIT_L(n) asm volatile("s_waitcnt lgkmcnt(" #n ")" ::: "memory")
; template <class Epi, class Sched, bool ALIGN_EPI = false, bool SP2 = false>
; __device__ __forceinline__ void gemm_phase(PG8_LAS unsigned char* lds, const Gemm g, const Sched& S, const Epi& E) {
;     ...
;         for (int t = 0; t < nt; t += 2) {
;             const bool last = (t == nt - 2);
;             const char* a1 = cA + (size_t)(t + 1) * kstep;
;             const char* a2 = last ? nA : cA + (size_t)(t + 2) * kstep; const char* b2 = last ? nB : cB + (size_t)(t + 2) * kstep;
;             const char* a3 = a2 + kstep; const char* b3 = b2 + kstep;
;             if (last && has_next) S.a_ready(nxt);
;             if constexpr (SP2) {
;             PG8_LDB(B0, 0, 0); PG8_LDB(B1, 0, 1); PG8_SCHED; PG8_LDA(At, 0, 0); PG8_STAGE(PG8_SA(1, 1), a1 + hstep, voffA);
;             PG8_WAIT_V(8); PG8_WAIT_L(0); PG8_BAR; PG8_MMA(0, 0, At, B0); PG8_MMA(0, 1, At, B1); PG8_BAR; PG8_SCHED;
;             PG8_LDA(At, 0, 1); PG8_STAGE(PG8_SB(0, 0), b2, voffB); PG8_STAGE(PG8_SB(0, 1), b2 + hstep, voffB); PG8_STAGE(PG8_SA(0, 0), a2, voffA);
;             PG8_WAIT_V(8); PG8_WAIT_L(0); PG8_BAR; PG8_MMA(1, 0, At, B0); PG8_MMA(1, 1, At, B1); PG8_BAR; PG8_SCHED;
.Lpeel327:
	s_add_u32 s68, s8, 0x100
	s_addc_u32 s69, s9, 0
	s_add_i32 s84, 0, 0x10000
	s_cmp_eq_u32 s4, 28
	s_cselect_b32 vcc_hi, s1, s69
	s_cselect_b32 vcc_lo, s5, s68
	v_add_u32_e32 v0, s84, v188
	s_cselect_b32 s71, s7, s96
	s_cselect_b32 s70, s85, s97
	s_add_i32 s10, 0, 0x14000
	ds_read_b128 v[52:55], v0
	ds_read_b128 v[56:59], v0 offset:1024
	ds_read_b128 v[76:79], v0 offset:2048
	ds_read_b128 v[80:83], v0 offset:3072
	v_add_u32_e32 v0, s10, v188
	ds_read_b128 v[116:119], v0
	ds_read_b128 v[120:123], v0 offset:1024
	ds_read_b128 v[168:171], v0 offset:2048
	ds_read_b128 v[172:175], v0 offset:3072
	v_lshl_add_u64 v[2:3], s[8:9], 0, v[164:165]
	s_add_i32 m0, s58, 0xc000
	ds_read_b128 v[176:179], v189
	ds_read_b128 v[180:183], v189 offset:1024
	ds_read_b128 v[190:193], v189 offset:2048
	ds_read_b128 v[194:197], v189 offset:3072
	ds_read_b128 v[198:201], v189 offset:4096
	ds_read_b128 v[210:213], v189 offset:5120
	ds_read_b128 v[214:217], v189 offset:6144
	ds_read_b128 v[218:221], v189 offset:7168
	global_load_lds_dwordx4 v[2:3], off
	v_lshl_add_u64 v[2:3], s[8:9], 0, v[166:167]
	s_add_i32 m0, s58, 0xe000
	s_nop 0
	global_load_lds_dwordx4 v[2:3], off
	s_waitcnt vmcnt(8)
	s_waitcnt lgkmcnt(0)
	s_barrier
	s_waitcnt lgkmcnt(0)
	v_mfma_f32_16x16x32_bf16 v[152:155], v[52:55], v[176:179], 0
	v_mfma_f32_16x16x32_bf16 v[152:155], v[56:59], v[180:183], v[152:155]
	v_mfma_f32_16x16x32_bf16 v[144:147], v[76:79], v[176:179], 0
	v_mfma_f32_16x16x32_bf16 v[144:147], v[80:83], v[180:183], v[144:147]
	v_mfma_f32_16x16x32_bf16 v[140:143], v[76:79], v[190:193], 0
	v_mfma_f32_16x16x32_bf16 v[140:143], v[80:83], v[194:197], v[140:143]
	v_mfma_f32_16x16x32_bf16 v[148:151], v[52:55], v[190:193], 0
	v_mfma_f32_16x16x32_bf16 v[148:151], v[56:59], v[194:197], v[148:151]
	v_mfma_f32_16x16x32_bf16 v[136:139], v[52:55], v[198:201], 0
	v_mfma_f32_16x16x32_bf16 v[136:139], v[56:59], v[210:213], v[136:139]
	v_mfma_f32_16x16x32_bf16 v[132:135], v[76:79], v[198:201], 0
	v_mfma_f32_16x16x32_bf16 v[132:135], v[80:83], v[210:213], v[132:135]
	v_mfma_f32_16x16x32_bf16 v[124:127], v[76:79], v[214:217], 0
	v_mfma_f32_16x16x32_bf16 v[124:127], v[80:83], v[218:221], v[124:127]
	v_mfma_f32_16x16x32_bf16 v[128:131], v[52:55], v[214:217], 0
	v_mfma_f32_16x16x32_bf16 v[128:131], v[56:59], v[218:221], v[128:131]
	v_mfma_f32_16x16x32_bf16 v[112:115], v[116:119], v[176:179], 0
	v_mfma_f32_16x16x32_bf16 v[112:115], v[120:123], v[180:183], v[112:115]
	v_mfma_f32_16x16x32_bf16 v[104:107], v[168:171], v[176:179], 0
	v_mfma_f32_16x16x32_bf16 v[104:107], v[172:175], v[180:183], v[104:107]
	v_mfma_f32_16x16x32_bf16 v[100:103], v[168:171], v[190:193], 0
	v_mfma_f32_16x16x32_bf16 v[100:103], v[172:175], v[194:197], v[100:103]
	v_mfma_f32_16x16x32_bf16 v[108:111], v[116:119], v[190:193], 0
	v_mfma_f32_16x16x32_bf16 v[108:111], v[120:123], v[194:197], v[108:111]
	v_mfma_f32_16x16x32_bf16 v[96:99], v[116:119], v[198:201], 0
	v_mfma_f32_16x16x32_bf16 v[96:99], v[120:123], v[210:213], v[96:99]
	v_mfma_f32_16x16x32_bf16 v[92:95], v[168:171], v[198:201], 0
	v_mfma_f32_16x16x32_bf16 v[92:95], v[172:175], v[210:213], v[92:95]
	v_mfma_f32_16x16x32_bf16 v[84:87], v[168:171], v[214:217], 0
	v_mfma_f32_16x16x32_bf16 v[84:87], v[172:175], v[218:221], v[84:87]
	v_mfma_f32_16x16x32_bf16 v[88:91], v[116:119], v[214:217], 0
	v_mfma_f32_16x16x32_bf16 v[88:91], v[120:123], v[218:221], v[88:91]
	s_barrier
	s_add_i32 s8, s84, s80
	v_lshl_add_u64 v[184:185], s[70:71], 0, v[158:159]
	s_mov_b32 m0, s8
	ds_read_b128 v[176:179], v189 offset:16384
	ds_read_b128 v[180:183], v189 offset:17408
	ds_read_b128 v[190:193], v189 offset:18432
	ds_read_b128 v[194:197], v189 offset:19456
	ds_read_b128 v[198:201], v189 offset:20480
	ds_read_b128 v[210:213], v189 offset:21504
	ds_read_b128 v[214:217], v189 offset:22528
	ds_read_b128 v[218:221], v189 offset:23552
	global_load_lds_dwordx4 v[184:185], off
	s_add_i32 m0, s8, 0x2000
	s_add_u32 s8, s70, 0x80000
	v_lshl_add_u64 v[206:207], s[70:71], 0, v[162:163]
	s_addc_u32 s9, s71, 0
	s_add_i32 s10, s10, s80
	global_load_lds_dwordx4 v[206:207], off
	v_lshl_add_u64 v[2:3], s[8:9], 0, v[158:159]
	s_mov_b32 m0, s10
	v_lshl_add_u64 v[222:223], vcc, 0, v[156:157]
	global_load_lds_dwordx4 v[2:3], off
	v_lshl_add_u64 v[2:3], s[8:9], 0, v[162:163]
	s_add_i32 m0, s10, 0x2000
	v_lshl_add_u64 v[224:225], vcc, 0, v[160:161]
	global_load_lds_dwordx4 v[2:3], off
	s_mov_b32 m0, s58
	s_nop 0
	global_load_lds_dwordx4 v[222:223], off
	s_mov_b32 m0, s12
	s_nop 0
	global_load_lds_dwordx4 v[224:225], off
	s_waitcnt vmcnt(8)
	s_waitcnt lgkmcnt(0)
	s_barrier
	s_waitcnt lgkmcnt(0)
	v_mfma_f32_16x16x32_bf16 v[72:75], v[52:55], v[176:179], 0
	v_mfma_f32_16x16x32_bf16 v[72:75], v[56:59], v[180:183], v[72:75]
	v_mfma_f32_16x16x32_bf16 v[64:67], v[76:79], v[176:179], 0
	v_mfma_f32_16x16x32_bf16 v[64:67], v[80:83], v[180:183], v[64:67]
	v_mfma_f32_16x16x32_bf16 v[60:63], v[76:79], v[190:193], 0
	v_mfma_f32_16x16x32_bf16 v[60:63], v[80:83], v[194:197], v[60:63]
	v_mfma_f32_16x16x32_bf16 v[68:71], v[52:55], v[190:193], 0
	v_mfma_f32_16x16x32_bf16 v[68:71], v[56:59], v[194:197], v[68:71]
	v_mfma_f32_16x16x32_bf16 v[48:51], v[52:55], v[198:201], 0
	v_mfma_f32_16x16x32_bf16 v[48:51], v[56:59], v[210:213], v[48:51]
	v_mfma_f32_16x16x32_bf16 v[44:47], v[76:79], v[198:201], 0
	v_mfma_f32_16x16x32_bf16 v[44:47], v[80:83], v[210:213], v[44:47]
	v_mfma_f32_16x16x32_bf16 v[36:39], v[76:79], v[214:217], 0
	v_mfma_f32_16x16x32_bf16 v[36:39], v[80:83], v[218:221], v[36:39]
	v_mfma_f32_16x16x32_bf16 v[40:43], v[52:55], v[214:217], 0
	v_mfma_f32_16x16x32_bf16 v[40:43], v[56:59], v[218:221], v[40:43]
	v_mfma_f32_16x16x32_bf16 v[32:35], v[116:119], v[176:179], 0
	v_mfma_f32_16x16x32_bf16 v[32:35], v[120:123], v[180:183], v[32:35]
	v_mfma_f32_16x16x32_bf16 v[24:27], v[168:171], v[176:179], 0
	v_mfma_f32_16x16x32_bf16 v[24:27], v[172:175], v[180:183], v[24:27]
	v_mfma_f32_16x16x32_bf16 v[20:23], v[168:171], v[190:193], 0
	v_mfma_f32_16x16x32_bf16 v[20:23], v[172:175], v[194:197], v[20:23]
	v_mfma_f32_16x16x32_bf16 v[28:31], v[116:119], v[190:193], 0
	v_mfma_f32_16x16x32_bf16 v[28:31], v[120:123], v[194:197], v[28:31]
	v_mfma_f32_16x16x32_bf16 v[16:19], v[116:119], v[198:201], 0
	v_mfma_f32_16x16x32_bf16 v[16:19], v[120:123], v[210:213], v[16:19]
	v_mfma_f32_16x16x32_bf16 v[12:15], v[168:171], v[198:201], 0
	v_mfma_f32_16x16x32_bf16 v[12:15], v[172:175], v[210:213], v[12:15]
	v_mfma_f32_16x16x32_bf16 v[2:5], v[168:171], v[214:217], 0
	v_mfma_f32_16x16x32_bf16 v[2:5], v[172:175], v[218:221], v[2:5]
	v_mfma_f32_16x16x32_bf16 v[8:11], v[116:119], v[214:217], 0
	v_mfma_f32_16x16x32_bf16 v[8:11], v[120:123], v[218:221], v[8:11]
	s_barrier
; #define PG8_STAGE(bufoff, gbase, voff) do { _Pragma("unroll") for (int _i = 0; _i < 2; ++_i) \
;         __builtin_amdgcn_global_load_lds((const unsigned*)((const char*)(gbase) + (voff)[_i]), (PG8_LAS unsigned*)(lds + (bufoff) + ldsw + _i * 8192), 16, 0, 0); } while (0)
; #define PG8_LDA(dst, b, h) do { _Pragma("unroll") for (int m = 0; m < 4; ++m) _Pragma("unroll") for (int k = 0; k < 2; ++k) dst[m][k] = *(const PG8_LAS bf16x8*)(lds + PG8_SA(b, h) + aoff + m * 2048 + k * 1024); } while (0)
; #define PG8_LDB(dst, b, h) do { _Pragma("unroll") for (int n = 0; n < 2; ++n) _Pragma("unroll") for (int k = 0; k < 2; ++k) dst[n][k] = *(const PG8_LAS bf16x8*)(lds + PG8_SB(b, h) + boff + n * 2048 + k * 1024); } while (0)
; #define PG8_MMA(ai, bj, At, Bt) do { __builtin_amdgcn_s_setprio(1); _Pragma("unroll") for (int m = 0; m < 4; ++m) _Pragma("unroll") for (int n = 0; n < 2; ++n) _Pragma("unroll") for (int k = 0; k < 2; ++k) \
;         acc[ai][bj][m][n] = mma16<Epi::I8>(Bt[n][k], At[m][k], acc[ai][bj][m][n]); __builtin_amdgcn_s_setprio(0); } while (0)
; #define PG8_WAIT_V(n) asm volatile("s_waitcnt vmcnt(" #n ")" ::: "memory")
; #define PG8_WAIT_L(n) asm volatile("s_waitcnt lgkmcnt(" #n ")" ::: "memory")
; #define PG8_BAR __builtin_amdgcn_s_barrier()
; #define PG8_SCHED __builtin_amdgcn_sched_barrier(0)
; template <class Epi, class Sched, bool ALIGN_EPI = false, bool SP2 = false>
; __device__ __forceinline__ void gemm_phase(PG8_LAS unsigned char* lds, const Gemm g, const Sched& S, const Epi& E) {
;     ...
;         for (int t = 0; t < nt; t += 2) {
;     ...
;             PG8_LDB(B0, 1, 0); PG8_LDB(B1, 1, 1); PG8_SCHED; PG8_LDA(At, 1, 0); PG8_STAGE(PG8_SA(0, 1), a2 + hstep, voffA);
;             PG8_WAIT_V(8); PG8_WAIT_L(0); PG8_BAR; PG8_MMA(0, 0, At, B0); PG8_MMA(0, 1, At, B1); PG8_BAR; PG8_SCHED;
;             PG8_LDA(At, 1, 1); PG8_STAGE(PG8_SB(1, 0), b3, voffB); PG8_STAGE(PG8_SB(1, 1), b3 + hstep, voffB); PG8_STAGE(PG8_SA(1, 0), a3, voffA);
;             PG8_WAIT_V(8); PG8_WAIT_L(0); PG8_BAR; PG8_MMA(1, 0, At, B0); PG8_MMA(1, 1, At, B1); PG8_BAR; PG8_SCHED;
	s_add_i32 s10, 0, 0x18000
	v_add_u32_e32 v0, s10, v188
	s_add_i32 s11, 0, 0x1c000
	ds_read_b128 v[52:55], v0
	ds_read_b128 v[56:59], v0 offset:1024
	ds_read_b128 v[76:79], v0 offset:2048
	ds_read_b128 v[80:83], v0 offset:3072
	v_add_u32_e32 v0, s11, v188
	ds_read_b128 v[116:119], v0
	ds_read_b128 v[120:123], v0 offset:1024
	ds_read_b128 v[168:171], v0 offset:2048
	ds_read_b128 v[172:175], v0 offset:3072
	s_add_u32 s8, vcc_lo, 0x80000
	s_addc_u32 s9, vcc_hi, 0
	s_mov_b32 m0, s13
	v_lshl_add_u64 v[6:7], s[8:9], 0, v[156:157]
	ds_read_b128 v[176:179], v189 offset:32768
	ds_read_b128 v[180:183], v189 offset:33792
	ds_read_b128 v[190:193], v189 offset:34816
	ds_read_b128 v[194:197], v189 offset:35840
	ds_read_b128 v[198:201], v189 offset:36864
	ds_read_b128 v[210:213], v189 offset:37888
	ds_read_b128 v[214:217], v189 offset:38912
	ds_read_b128 v[218:221], v189 offset:39936
	global_load_lds_dwordx4 v[6:7], off
	v_lshl_add_u64 v[6:7], s[8:9], 0, v[160:161]
	s_mov_b32 m0, s66
	s_nop 0
	global_load_lds_dwordx4 v[6:7], off
	s_waitcnt vmcnt(8)
	s_waitcnt lgkmcnt(0)
	s_barrier
	s_waitcnt lgkmcnt(0)
	v_mfma_f32_16x16x32_bf16 v[152:155], v[52:55], v[176:179], v[152:155]
	v_mfma_f32_16x16x32_bf16 v[152:155], v[56:59], v[180:183], v[152:155]
	v_mfma_f32_16x16x32_bf16 v[144:147], v[76:79], v[176:179], v[144:147]
	v_mfma_f32_16x16x32_bf16 v[144:147], v[80:83], v[180:183], v[144:147]
	v_mfma_f32_16x16x32_bf16 v[140:143], v[76:79], v[190:193], v[140:143]
	v_mfma_f32_16x16x32_bf16 v[140:143], v[80:83], v[194:197], v[140:143]
	v_mfma_f32_16x16x32_bf16 v[148:151], v[52:55], v[190:193], v[148:151]
	v_mfma_f32_16x16x32_bf16 v[148:151], v[56:59], v[194:197], v[148:151]
	v_mfma_f32_16x16x32_bf16 v[136:139], v[52:55], v[198:201], v[136:139]
	v_mfma_f32_16x16x32_bf16 v[136:139], v[56:59], v[210:213], v[136:139]
	v_mfma_f32_16x16x32_bf16 v[132:135], v[76:79], v[198:201], v[132:135]
	v_mfma_f32_16x16x32_bf16 v[132:135], v[80:83], v[210:213], v[132:135]
	v_mfma_f32_16x16x32_bf16 v[124:127], v[76:79], v[214:217], v[124:127]
	v_mfma_f32_16x16x32_bf16 v[124:127], v[80:83], v[218:221], v[124:127]
	v_mfma_f32_16x16x32_bf16 v[128:131], v[52:55], v[214:217], v[128:131]
	v_mfma_f32_16x16x32_bf16 v[128:131], v[56:59], v[218:221], v[128:131]
	v_mfma_f32_16x16x32_bf16 v[112:115], v[116:119], v[176:179], v[112:115]
	v_mfma_f32_16x16x32_bf16 v[112:115], v[120:123], v[180:183], v[112:115]
	v_mfma_f32_16x16x32_bf16 v[104:107], v[168:171], v[176:179], v[104:107]
	v_mfma_f32_16x16x32_bf16 v[104:107], v[172:175], v[180:183], v[104:107]
	v_mfma_f32_16x16x32_bf16 v[100:103], v[168:171], v[190:193], v[100:103]
	v_mfma_f32_16x16x32_bf16 v[100:103], v[172:175], v[194:197], v[100:103]
	v_mfma_f32_16x16x32_bf16 v[108:111], v[116:119], v[190:193], v[108:111]
	v_mfma_f32_16x16x32_bf16 v[108:111], v[120:123], v[194:197], v[108:111]
	v_mfma_f32_16x16x32_bf16 v[96:99], v[116:119], v[198:201], v[96:99]
	v_mfma_f32_16x16x32_bf16 v[96:99], v[120:123], v[210:213], v[96:99]
	v_mfma_f32_16x16x32_bf16 v[92:95], v[168:171], v[198:201], v[92:95]
	v_mfma_f32_16x16x32_bf16 v[92:95], v[172:175], v[210:213], v[92:95]
	v_mfma_f32_16x16x32_bf16 v[84:87], v[168:171], v[214:217], v[84:87]
	v_mfma_f32_16x16x32_bf16 v[84:87], v[172:175], v[218:221], v[84:87]
	v_mfma_f32_16x16x32_bf16 v[88:91], v[116:119], v[214:217], v[88:91]
	v_mfma_f32_16x16x32_bf16 v[88:91], v[120:123], v[218:221], v[88:91]
	s_barrier
	s_add_i32 s8, s10, s80
	v_lshl_add_u64 v[6:7], v[184:185], 0, s[92:93]
	s_mov_b32 m0, s8
	ds_read_b128 v[176:179], v189 offset:49152
	ds_read_b128 v[180:183], v189 offset:50176
	ds_read_b128 v[190:193], v189 offset:51200
	ds_read_b128 v[194:197], v189 offset:52224
	ds_read_b128 v[198:201], v189 offset:53248
	ds_read_b128 v[210:213], v189 offset:54272
	ds_read_b128 v[214:217], v189 offset:55296
	ds_read_b128 v[218:221], v189 offset:56320
	global_load_lds_dwordx4 v[6:7], off
	s_add_i32 m0, s8, 0x2000
	s_add_u32 s8, s70, 0x80080
	v_lshl_add_u64 v[6:7], v[206:207], 0, s[92:93]
	s_addc_u32 s9, s71, 0
	s_add_i32 s10, s11, s80
	global_load_lds_dwordx4 v[6:7], off
	v_lshl_add_u64 v[6:7], s[8:9], 0, v[158:159]
	s_mov_b32 m0, s10
	s_nop 0
	global_load_lds_dwordx4 v[6:7], off
	v_lshl_add_u64 v[6:7], s[8:9], 0, v[162:163]
	s_add_i32 m0, s10, 0x2000
	s_nop 0
	global_load_lds_dwordx4 v[6:7], off
	v_lshl_add_u64 v[6:7], v[222:223], 0, s[92:93]
	s_mov_b32 m0, s67
	s_nop 0
	global_load_lds_dwordx4 v[6:7], off
	v_lshl_add_u64 v[6:7], v[224:225], 0, s[92:93]
	s_mov_b32 m0, s81
	s_nop 0
	global_load_lds_dwordx4 v[6:7], off
	s_waitcnt vmcnt(8)
	s_waitcnt lgkmcnt(0)
	s_barrier
	s_waitcnt lgkmcnt(0)
	v_mfma_f32_16x16x32_bf16 v[72:75], v[52:55], v[176:179], v[72:75]
	v_mfma_f32_16x16x32_bf16 v[72:75], v[56:59], v[180:183], v[72:75]
	v_mfma_f32_16x16x32_bf16 v[64:67], v[76:79], v[176:179], v[64:67]
	v_mfma_f32_16x16x32_bf16 v[64:67], v[80:83], v[180:183], v[64:67]
	v_mfma_f32_16x16x32_bf16 v[60:63], v[76:79], v[190:193], v[60:63]
	v_mfma_f32_16x16x32_bf16 v[60:63], v[80:83], v[194:197], v[60:63]
	v_mfma_f32_16x16x32_bf16 v[68:71], v[52:55], v[190:193], v[68:71]
	v_mfma_f32_16x16x32_bf16 v[68:71], v[56:59], v[194:197], v[68:71]
	v_mfma_f32_16x16x32_bf16 v[48:51], v[52:55], v[198:201], v[48:51]
	v_mfma_f32_16x16x32_bf16 v[48:51], v[56:59], v[210:213], v[48:51]
	v_mfma_f32_16x16x32_bf16 v[44:47], v[76:79], v[198:201], v[44:47]
	v_mfma_f32_16x16x32_bf16 v[44:47], v[80:83], v[210:213], v[44:47]
	v_mfma_f32_16x16x32_bf16 v[36:39], v[76:79], v[214:217], v[36:39]
	v_mfma_f32_16x16x32_bf16 v[36:39], v[80:83], v[218:221], v[36:39]
	v_mfma_f32_16x16x32_bf16 v[40:43], v[52:55], v[214:217], v[40:43]
	v_mfma_f32_16x16x32_bf16 v[40:43], v[56:59], v[218:221], v[40:43]
	v_mfma_f32_16x16x32_bf16 v[32:35], v[116:119], v[176:179], v[32:35]
	v_mfma_f32_16x16x32_bf16 v[32:35], v[120:123], v[180:183], v[32:35]
	v_mfma_f32_16x16x32_bf16 v[24:27], v[168:171], v[176:179], v[24:27]
	v_mfma_f32_16x16x32_bf16 v[24:27], v[172:175], v[180:183], v[24:27]
	v_mfma_f32_16x16x32_bf16 v[20:23], v[168:171], v[190:193], v[20:23]
	v_mfma_f32_16x16x32_bf16 v[20:23], v[172:175], v[194:197], v[20:23]
	v_mfma_f32_16x16x32_bf16 v[28:31], v[116:119], v[190:193], v[28:31]
	v_mfma_f32_16x16x32_bf16 v[28:31], v[120:123], v[194:197], v[28:31]
	v_mfma_f32_16x16x32_bf16 v[16:19], v[116:119], v[198:201], v[16:19]
	v_mfma_f32_16x16x32_bf16 v[16:19], v[120:123], v[210:213], v[16:19]
	v_mfma_f32_16x16x32_bf16 v[12:15], v[168:171], v[198:201], v[12:15]
	v_mfma_f32_16x16x32_bf16 v[12:15], v[172:175], v[210:213], v[12:15]
	v_mfma_f32_16x16x32_bf16 v[2:5], v[168:171], v[214:217], v[2:5]
	v_mfma_f32_16x16x32_bf16 v[6:9], v[116:119], v[214:217], v[8:11]
	v_mfma_f32_16x16x32_bf16 v[8:11], v[120:123], v[218:221], v[6:9]
	v_mfma_f32_16x16x32_bf16 v[4:7], v[172:175], v[218:221], v[2:5]
	s_barrier
	s_add_i32 s4, s4, 2
	s_add_u32 s97, s97, 0x100
	s_addc_u32 s96, s96, 0
	s_cmp_gt_u32 s4, 29
	s_mov_b64 s[8:9], s[68:69]
	s_cbranch_scc0 .LBB0_327
	s_branch .Lpeelx327
; #define PG8_STAGE(bufoff, gbase, voff) do { _Pragma("unroll") for (int _i = 0; _i < 2; ++_i) \
;         __builtin_amdgcn_global_load_lds((const unsigned*)((const char*)(gbase) + (voff)[_i]), (PG8_LAS unsigned*)(lds + (bufoff) + ldsw + _i * 8192), 16, 0, 0); } while (0)
; #define PG8_LDA(dst, b, h) do { _Pragma("unroll") for (int m = 0; m < 4; ++m) _Pragma("unroll") for (int k = 0; k < 2; ++k) dst[m][k] = *(const PG8_LAS bf16x8*)(lds + PG8_SA(b, h) + aoff + m * 2048 + k * 1024); } while (0)
; #define PG8_LDB(dst, b, h) do { _Pragma("unroll") for (int n = 0; n < 2; ++n) _Pragma("unroll") for (int k = 0; k < 2; ++k) dst[n][k] = *(const PG8_LAS bf16x8*)(lds + PG8_SB(b, h) + boff + n * 2048 + k * 1024); } while (0)
; #define PG8_MMA(ai, bj, At, Bt) do { __builtin_amdgcn_s_setprio(1); _Pragma("unroll") for (int m = 0; m < 4; ++m) _Pragma("unroll") for (int n = 0; n < 2; ++n) _Pragma("unroll") for (int k = 0; k < 2; ++k) \
;         acc[ai][bj][m][n] = mma16<Epi::I8>(Bt[n][k], At[m][k], acc[ai][bj][m][n]); __builtin_amdgcn_s_setprio(0); } while (0)
; #define PG8_WAIT_V(n) asm volatile("s_waitcnt vmcnt(" #n ")" ::: "memory")
; template <class Epi, class Sched, bool ALIGN_EPI = false, bool SP2 = false>
; __device__ __forceinline__ void gemm_phase(PG8_LAS unsigned char* lds, const Gemm g, const Sched& S, const Epi& E) {
;     ...
;         const bool has_next = S.next(ui + 1, nxt);
;         const char* nA = has_next ? (const char*)g.A + (size_t)nxt.pm * tstep : cA; const char* nB = has_next ? (const char*)g.Bt + (size_t)nxt.pn * tstep : cB;
;         for (int t = 0; t < nt; t += 2) {
;             const bool last = (t == nt - 2);
;             const char* a1 = cA + (size_t)(t + 1) * kstep;
;             const char* a2 = last ? nA : cA + (size_t)(t + 2) * kstep; const char* b2 = last ? nB : cB + (size_t)(t + 2) * kstep;
;             const char* a3 = a2 + kstep; const char* b3 = b2 + kstep;
;             if (last && has_next) S.a_ready(nxt);
;             if constexpr (SP2) {
;             PG8_LDB(B0, 0, 0); PG8_LDB(B1, 0, 1); PG8_SCHED; PG8_LDA(At, 0, 0); PG8_STAGE(PG8_SA(1, 1), a1 + hstep, voffA);
;             PG8_WAIT_V(8); PG8_WAIT_L(0); PG8_BAR; PG8_MMA(0, 0, At, B0); PG8_MMA(0, 1, At, B1); PG8_BAR; PG8_SCHED;
;             PG8_LDA(At, 0, 1); PG8_STAGE(PG8_SB(0, 0), b2, voffB); PG8_STAGE(PG8_SB(0, 1), b2 + hstep, voffB); PG8_STAGE(PG8_SA(0, 0), a2, voffA);
.LBB0_327:
	s_add_u32 s68, s8, 0x100
	s_addc_u32 s69, s9, 0
	s_add_i32 s84, 0, 0x10000
	s_cmp_eq_u32 s4, 28
	s_cselect_b32 vcc_hi, s1, s69
	s_cselect_b32 vcc_lo, s5, s68
	v_add_u32_e32 v0, s84, v188
	s_cselect_b32 s71, s7, s96
	s_cselect_b32 s70, s85, s97
	s_add_i32 s10, 0, 0x14000
	ds_read_b128 v[52:55], v0
	ds_read_b128 v[56:59], v0 offset:1024
	ds_read_b128 v[76:79], v0 offset:2048
	ds_read_b128 v[80:83], v0 offset:3072
	v_add_u32_e32 v0, s10, v188
	ds_read_b128 v[116:119], v0
	ds_read_b128 v[120:123], v0 offset:1024
	ds_read_b128 v[168:171], v0 offset:2048
	ds_read_b128 v[172:175], v0 offset:3072
	v_lshl_add_u64 v[2:3], s[8:9], 0, v[164:165]
	s_add_i32 m0, s58, 0xc000
	ds_read_b128 v[176:179], v189
	ds_read_b128 v[180:183], v189 offset:1024
	ds_read_b128 v[190:193], v189 offset:2048
	ds_read_b128 v[194:197], v189 offset:3072
	ds_read_b128 v[198:201], v189 offset:4096
	ds_read_b128 v[210:213], v189 offset:5120
	ds_read_b128 v[214:217], v189 offset:6144
	ds_read_b128 v[218:221], v189 offset:7168
	global_load_lds_dwordx4 v[2:3], off
	v_lshl_add_u64 v[2:3], s[8:9], 0, v[166:167]
	s_add_i32 m0, s58, 0xe000
	s_nop 0
	global_load_lds_dwordx4 v[2:3], off
	s_waitcnt vmcnt(8)
	s_waitcnt lgkmcnt(0)
	s_barrier
	s_waitcnt lgkmcnt(0)
	v_mfma_f32_16x16x32_bf16 v[152:155], v[52:55], v[176:179], v[152:155]
	v_mfma_f32_16x16x32_bf16 v[152:155], v[56:59], v[180:183], v[152:155]
	v_mfma_f32_16x16x32_bf16 v[144:147], v[76:79], v[176:179], v[144:147]
	v_mfma_f32_16x16x32_bf16 v[144:147], v[80:83], v[180:183], v[144:147]
	v_mfma_f32_16x16x32_bf16 v[140:143], v[76:79], v[190:193], v[140:143]
	v_mfma_f32_16x16x32_bf16 v[140:143], v[80:83], v[194:197], v[140:143]
	v_mfma_f32_16x16x32_bf16 v[148:151], v[52:55], v[190:193], v[148:151]
	v_mfma_f32_16x16x32_bf16 v[148:151], v[56:59], v[194:197], v[148:151]
	v_mfma_f32_16x16x32_bf16 v[136:139], v[52:55], v[198:201], v[136:139]
	v_mfma_f32_16x16x32_bf16 v[136:139], v[56:59], v[210:213], v[136:139]
	v_mfma_f32_16x16x32_bf16 v[132:135], v[76:79], v[198:201], v[132:135]
	v_mfma_f32_16x16x32_bf16 v[132:135], v[80:83], v[210:213], v[132:135]
	v_mfma_f32_16x16x32_bf16 v[124:127], v[76:79], v[214:217], v[124:127]
	v_mfma_f32_16x16x32_bf16 v[124:127], v[80:83], v[218:221], v[124:127]
	v_mfma_f32_16x16x32_bf16 v[128:131], v[52:55], v[214:217], v[128:131]
	v_mfma_f32_16x16x32_bf16 v[128:131], v[56:59], v[218:221], v[128:131]
	v_mfma_f32_16x16x32_bf16 v[112:115], v[116:119], v[176:179], v[112:115]
	v_mfma_f32_16x16x32_bf16 v[112:115], v[120:123], v[180:183], v[112:115]
	v_mfma_f32_16x16x32_bf16 v[104:107], v[168:171], v[176:179], v[104:107]
	v_mfma_f32_16x16x32_bf16 v[104:107], v[172:175], v[180:183], v[104:107]
	v_mfma_f32_16x16x32_bf16 v[100:103], v[168:171], v[190:193], v[100:103]
	v_mfma_f32_16x16x32_bf16 v[100:103], v[172:175], v[194:197], v[100:103]
	v_mfma_f32_16x16x32_bf16 v[108:111], v[116:119], v[190:193], v[108:111]
	v_mfma_f32_16x16x32_bf16 v[108:111], v[120:123], v[194:197], v[108:111]
	v_mfma_f32_16x16x32_bf16 v[96:99], v[116:119], v[198:201], v[96:99]
	v_mfma_f32_16x16x32_bf16 v[96:99], v[120:123], v[210:213], v[96:99]
	v_mfma_f32_16x16x32_bf16 v[92:95], v[168:171], v[198:201], v[92:95]
	v_mfma_f32_16x16x32_bf16 v[92:95], v[172:175], v[210:213], v[92:95]
	v_mfma_f32_16x16x32_bf16 v[84:87], v[168:171], v[214:217], v[84:87]
	v_mfma_f32_16x16x32_bf16 v[84:87], v[172:175], v[218:221], v[84:87]
	v_mfma_f32_16x16x32_bf16 v[88:91], v[116:119], v[214:217], v[88:91]
	v_mfma_f32_16x16x32_bf16 v[88:91], v[120:123], v[218:221], v[88:91]
	s_barrier
	s_add_i32 s8, s84, s80
	v_lshl_add_u64 v[184:185], s[70:71], 0, v[158:159]
	s_mov_b32 m0, s8
	ds_read_b128 v[176:179], v189 offset:16384
	ds_read_b128 v[180:183], v189 offset:17408
	ds_read_b128 v[190:193], v189 offset:18432
	ds_read_b128 v[194:197], v189 offset:19456
	ds_read_b128 v[198:201], v189 offset:20480
	ds_read_b128 v[210:213], v189 offset:21504
	ds_read_b128 v[214:217], v189 offset:22528
	ds_read_b128 v[218:221], v189 offset:23552
	global_load_lds_dwordx4 v[184:185], off
	s_add_i32 m0, s8, 0x2000
	s_add_u32 s8, s70, 0x80000
	v_lshl_add_u64 v[206:207], s[70:71], 0, v[162:163]
	s_addc_u32 s9, s71, 0
	s_add_i32 s10, s10, s80
	global_load_lds_dwordx4 v[206:207], off
	v_lshl_add_u64 v[2:3], s[8:9], 0, v[158:159]
	s_mov_b32 m0, s10
	v_lshl_add_u64 v[222:223], vcc, 0, v[156:157]
	global_load_lds_dwordx4 v[2:3], off
	v_lshl_add_u64 v[2:3], s[8:9], 0, v[162:163]
	s_add_i32 m0, s10, 0x2000
	v_lshl_add_u64 v[224:225], vcc, 0, v[160:161]
	global_load_lds_dwordx4 v[2:3], off
	s_mov_b32 m0, s58
	s_nop 0
	global_load_lds_dwordx4 v[222:223], off
	s_mov_b32 m0, s12
	s_nop 0
	global_load_lds_dwordx4 v[224:225], off
	s_waitcnt vmcnt(8)
	s_waitcnt lgkmcnt(0)
	s_barrier
; #define PG8_STAGE(bufoff, gbase, voff) do { _Pragma("unroll") for (int _i = 0; _i < 2; ++_i) \
;         __builtin_amdgcn_global_load_lds((const unsigned*)((const char*)(gbase) + (voff)[_i]), (PG8_LAS unsigned*)(lds + (bufoff) + ldsw + _i * 8192), 16, 0, 0); } while (0)
; #define PG8_LDA(dst, b, h) do { _Pragma("unroll") for (int m = 0; m < 4; ++m) _Pragma("unroll") for (int k = 0; k < 2; ++k) dst[m][k] = *(const PG8_LAS bf16x8*)(lds + PG8_SA(b, h) + aoff + m * 2048 + k * 1024); } while (0)
; #define PG8_LDB(dst, b, h) do { _Pragma("unroll") for (int n = 0; n < 2; ++n) _Pragma("unroll") for (int k = 0; k < 2; ++k) dst[n][k] = *(const PG8_LAS bf16x8*)(lds + PG8_SB(b, h) + boff + n * 2048 + k * 1024); } while (0)
; #define PG8_MMA(ai, bj, At, Bt) do { __builtin_amdgcn_s_setprio(1); _Pragma("unroll") for (int m = 0; m < 4; ++m) _Pragma("unroll") for (int n = 0; n < 2; ++n) _Pragma("unroll") for (int k = 0; k < 2; ++k) \
;         acc[ai][bj][m][n] = mma16<Epi::I8>(Bt[n][k], At[m][k], acc[ai][bj][m][n]); __builtin_amdgcn_s_setprio(0); } while (0)
; #define PG8_WAIT_V(n) asm volatile("s_waitcnt vmcnt(" #n ")" ::: "memory")
; #define PG8_WAIT_L(n) asm volatile("s_waitcnt lgkmcnt(" #n ")" ::: "memory")
; #define PG8_BAR __builtin_amdgcn_s_barrier()
; #define PG8_SCHED __builtin_amdgcn_sched_barrier(0)
; template <class Epi, class Sched, bool ALIGN_EPI = false, bool SP2 = false>
; __device__ __forceinline__ void gemm_phase(PG8_LAS unsigned char* lds, const Gemm g, const Sched& S, const Epi& E) {
;     ...
;             PG8_WAIT_V(8); PG8_WAIT_L(0); PG8_BAR; PG8_MMA(1, 0, At, B0); PG8_MMA(1, 1, At, B1); PG8_BAR; PG8_SCHED;
;             PG8_LDB(B0, 1, 0); PG8_LDB(B1, 1, 1); PG8_SCHED; PG8_LDA(At, 1, 0); PG8_STAGE(PG8_SA(0, 1), a2 + hstep, voffA);
;             PG8_WAIT_V(8); PG8_WAIT_L(0); PG8_BAR; PG8_MMA(0, 0, At, B0); PG8_MMA(0, 1, At, B1); PG8_BAR; PG8_SCHED;
	s_waitcnt lgkmcnt(0)
	v_mfma_f32_16x16x32_bf16 v[72:75], v[52:55], v[176:179], v[72:75]
	v_mfma_f32_16x16x32_bf16 v[72:75], v[56:59], v[180:183], v[72:75]
	v_mfma_f32_16x16x32_bf16 v[64:67], v[76:79], v[176:179], v[64:67]
	v_mfma_f32_16x16x32_bf16 v[64:67], v[80:83], v[180:183], v[64:67]
	v_mfma_f32_16x16x32_bf16 v[60:63], v[76:79], v[190:193], v[60:63]
	v_mfma_f32_16x16x32_bf16 v[60:63], v[80:83], v[194:197], v[60:63]
	v_mfma_f32_16x16x32_bf16 v[68:71], v[52:55], v[190:193], v[68:71]
	v_mfma_f32_16x16x32_bf16 v[68:71], v[56:59], v[194:197], v[68:71]
	v_mfma_f32_16x16x32_bf16 v[48:51], v[52:55], v[198:201], v[48:51]
	v_mfma_f32_16x16x32_bf16 v[48:51], v[56:59], v[210:213], v[48:51]
	v_mfma_f32_16x16x32_bf16 v[44:47], v[76:79], v[198:201], v[44:47]
	v_mfma_f32_16x16x32_bf16 v[44:47], v[80:83], v[210:213], v[44:47]
	v_mfma_f32_16x16x32_bf16 v[36:39], v[76:79], v[214:217], v[36:39]
	v_mfma_f32_16x16x32_bf16 v[36:39], v[80:83], v[218:221], v[36:39]
	v_mfma_f32_16x16x32_bf16 v[40:43], v[52:55], v[214:217], v[40:43]
	v_mfma_f32_16x16x32_bf16 v[40:43], v[56:59], v[218:221], v[40:43]
	v_mfma_f32_16x16x32_bf16 v[32:35], v[116:119], v[176:179], v[32:35]
	v_mfma_f32_16x16x32_bf16 v[32:35], v[120:123], v[180:183], v[32:35]
	v_mfma_f32_16x16x32_bf16 v[24:27], v[168:171], v[176:179], v[24:27]
	v_mfma_f32_16x16x32_bf16 v[24:27], v[172:175], v[180:183], v[24:27]
	v_mfma_f32_16x16x32_bf16 v[20:23], v[168:171], v[190:193], v[20:23]
	v_mfma_f32_16x16x32_bf16 v[20:23], v[172:175], v[194:197], v[20:23]
	v_mfma_f32_16x16x32_bf16 v[28:31], v[116:119], v[190:193], v[28:31]
	v_mfma_f32_16x16x32_bf16 v[28:31], v[120:123], v[194:197], v[28:31]
	v_mfma_f32_16x16x32_bf16 v[16:19], v[116:119], v[198:201], v[16:19]
	v_mfma_f32_16x16x32_bf16 v[16:19], v[120:123], v[210:213], v[16:19]
	v_mfma_f32_16x16x32_bf16 v[12:15], v[168:171], v[198:201], v[12:15]
	v_mfma_f32_16x16x32_bf16 v[12:15], v[172:175], v[210:213], v[12:15]
	v_mfma_f32_16x16x32_bf16 v[2:5], v[168:171], v[214:217], v[4:7]
	v_mfma_f32_16x16x32_bf16 v[2:5], v[172:175], v[218:221], v[2:5]
	v_mfma_f32_16x16x32_bf16 v[8:11], v[116:119], v[214:217], v[8:11]
	v_mfma_f32_16x16x32_bf16 v[8:11], v[120:123], v[218:221], v[8:11]
	s_barrier
	s_add_i32 s10, 0, 0x18000
	v_add_u32_e32 v0, s10, v188
	s_add_i32 s11, 0, 0x1c000
	ds_read_b128 v[52:55], v0
	ds_read_b128 v[56:59], v0 offset:1024
	ds_read_b128 v[76:79], v0 offset:2048
	ds_read_b128 v[80:83], v0 offset:3072
	v_add_u32_e32 v0, s11, v188
	ds_read_b128 v[116:119], v0
	ds_read_b128 v[120:123], v0 offset:1024
	ds_read_b128 v[168:171], v0 offset:2048
	ds_read_b128 v[172:175], v0 offset:3072
	s_add_u32 s8, vcc_lo, 0x80000
	s_addc_u32 s9, vcc_hi, 0
	s_mov_b32 m0, s13
	v_lshl_add_u64 v[6:7], s[8:9], 0, v[156:157]
	ds_read_b128 v[176:179], v189 offset:32768
	ds_read_b128 v[180:183], v189 offset:33792
	ds_read_b128 v[190:193], v189 offset:34816
	ds_read_b128 v[194:197], v189 offset:35840
	ds_read_b128 v[198:201], v189 offset:36864
	ds_read_b128 v[210:213], v189 offset:37888
	ds_read_b128 v[214:217], v189 offset:38912
	ds_read_b128 v[218:221], v189 offset:39936
	global_load_lds_dwordx4 v[6:7], off
	v_lshl_add_u64 v[6:7], s[8:9], 0, v[160:161]
	s_mov_b32 m0, s66
	s_nop 0
	global_load_lds_dwordx4 v[6:7], off
	s_waitcnt vmcnt(8)
	s_waitcnt lgkmcnt(0)
	s_barrier
	s_waitcnt lgkmcnt(0)
	v_mfma_f32_16x16x32_bf16 v[152:155], v[52:55], v[176:179], v[152:155]
	v_mfma_f32_16x16x32_bf16 v[152:155], v[56:59], v[180:183], v[152:155]
	v_mfma_f32_16x16x32_bf16 v[144:147], v[76:79], v[176:179], v[144:147]
	v_mfma_f32_16x16x32_bf16 v[144:147], v[80:83], v[180:183], v[144:147]
	v_mfma_f32_16x16x32_bf16 v[140:143], v[76:79], v[190:193], v[140:143]
	v_mfma_f32_16x16x32_bf16 v[140:143], v[80:83], v[194:197], v[140:143]
	v_mfma_f32_16x16x32_bf16 v[148:151], v[52:55], v[190:193], v[148:151]
	v_mfma_f32_16x16x32_bf16 v[148:151], v[56:59], v[194:197], v[148:151]
	v_mfma_f32_16x16x32_bf16 v[136:139], v[52:55], v[198:201], v[136:139]
	v_mfma_f32_16x16x32_bf16 v[136:139], v[56:59], v[210:213], v[136:139]
	v_mfma_f32_16x16x32_bf16 v[132:135], v[76:79], v[198:201], v[132:135]
	v_mfma_f32_16x16x32_bf16 v[132:135], v[80:83], v[210:213], v[132:135]
	v_mfma_f32_16x16x32_bf16 v[124:127], v[76:79], v[214:217], v[124:127]
	v_mfma_f32_16x16x32_bf16 v[124:127], v[80:83], v[218:221], v[124:127]
	v_mfma_f32_16x16x32_bf16 v[128:131], v[52:55], v[214:217], v[128:131]
	v_mfma_f32_16x16x32_bf16 v[128:131], v[56:59], v[218:221], v[128:131]
	v_mfma_f32_16x16x32_bf16 v[112:115], v[116:119], v[176:179], v[112:115]
	v_mfma_f32_16x16x32_bf16 v[112:115], v[120:123], v[180:183], v[112:115]
	v_mfma_f32_16x16x32_bf16 v[104:107], v[168:171], v[176:179], v[104:107]
	v_mfma_f32_16x16x32_bf16 v[104:107], v[172:175], v[180:183], v[104:107]
	v_mfma_f32_16x16x32_bf16 v[100:103], v[168:171], v[190:193], v[100:103]
	v_mfma_f32_16x16x32_bf16 v[100:103], v[172:175], v[194:197], v[100:103]
	v_mfma_f32_16x16x32_bf16 v[108:111], v[116:119], v[190:193], v[108:111]
	v_mfma_f32_16x16x32_bf16 v[108:111], v[120:123], v[194:197], v[108:111]
	v_mfma_f32_16x16x32_bf16 v[96:99], v[116:119], v[198:201], v[96:99]
	v_mfma_f32_16x16x32_bf16 v[96:99], v[120:123], v[210:213], v[96:99]
	v_mfma_f32_16x16x32_bf16 v[92:95], v[168:171], v[198:201], v[92:95]
	v_mfma_f32_16x16x32_bf16 v[92:95], v[172:175], v[210:213], v[92:95]
	v_mfma_f32_16x16x32_bf16 v[84:87], v[168:171], v[214:217], v[84:87]
	v_mfma_f32_16x16x32_bf16 v[84:87], v[172:175], v[218:221], v[84:87]
	v_mfma_f32_16x16x32_bf16 v[88:91], v[116:119], v[214:217], v[88:91]
	v_mfma_f32_16x16x32_bf16 v[88:91], v[120:123], v[218:221], v[88:91]
	s_barrier
; #define PG8_STAGE(bufoff, gbase, voff) do { _Pragma("unroll") for (int _i = 0; _i < 2; ++_i) \
;         __builtin_amdgcn_global_load_lds((const unsigned*)((const char*)(gbase) + (voff)[_i]), (PG8_LAS unsigned*)(lds + (bufoff) + ldsw + _i * 8192), 16, 0, 0); } while (0)
; #define PG8_LDA(dst, b, h) do { _Pragma("unroll") for (int m = 0; m < 4; ++m) _Pragma("unroll") for (int k = 0; k < 2; ++k) dst[m][k] = *(const PG8_LAS bf16x8*)(lds + PG8_SA(b, h) + aoff + m * 2048 + k * 1024); } while (0)
; #define PG8_MMA(ai, bj, At, Bt) do { __builtin_amdgcn_s_setprio(1); _Pragma("unroll") for (int m = 0; m < 4; ++m) _Pragma("unroll") for (int n = 0; n < 2; ++n) _Pragma("unroll") for (int k = 0; k < 2; ++k) \
;         acc[ai][bj][m][n] = mma16<Epi::I8>(Bt[n][k], At[m][k], acc[ai][bj][m][n]); __builtin_amdgcn_s_setprio(0); } while (0)
; #define PG8_WAIT_V(n) asm volatile("s_waitcnt vmcnt(" #n ")" ::: "memory")
; #define PG8_WAIT_L(n) asm volatile("s_waitcnt lgkmcnt(" #n ")" ::: "memory")
; #define PG8_BAR __builtin_amdgcn_s_barrier()
; #define PG8_SCHED __builtin_amdgcn_sched_barrier(0)
; template <class Epi, class Sched, bool ALIGN_EPI = false, bool SP2 = false>
; __device__ __forceinline__ void gemm_phase(PG8_LAS unsigned char* lds, const Gemm g, const Sched& S, const Epi& E) {
;     ...
;         for (int t = 0; t < nt; t += 2) {
;     ...
;             PG8_LDA(At, 1, 1); PG8_STAGE(PG8_SB(1, 0), b3, voffB); PG8_STAGE(PG8_SB(1, 1), b3 + hstep, voffB); PG8_STAGE(PG8_SA(1, 0), a3, voffA);
;             PG8_WAIT_V(8); PG8_WAIT_L(0); PG8_BAR; PG8_MMA(1, 0, At, B0); PG8_MMA(1, 1, At, B1); PG8_BAR; PG8_SCHED;
	s_add_i32 s8, s10, s80
	v_lshl_add_u64 v[6:7], v[184:185], 0, s[92:93]
	s_mov_b32 m0, s8
	ds_read_b128 v[176:179], v189 offset:49152
	ds_read_b128 v[180:183], v189 offset:50176
	ds_read_b128 v[190:193], v189 offset:51200
	ds_read_b128 v[194:197], v189 offset:52224
	ds_read_b128 v[198:201], v189 offset:53248
	ds_read_b128 v[210:213], v189 offset:54272
	ds_read_b128 v[214:217], v189 offset:55296
	ds_read_b128 v[218:221], v189 offset:56320
	global_load_lds_dwordx4 v[6:7], off
	s_add_i32 m0, s8, 0x2000
	s_add_u32 s8, s70, 0x80080
	v_lshl_add_u64 v[6:7], v[206:207], 0, s[92:93]
	s_addc_u32 s9, s71, 0
	s_add_i32 s10, s11, s80
	global_load_lds_dwordx4 v[6:7], off
	v_lshl_add_u64 v[6:7], s[8:9], 0, v[158:159]
	s_mov_b32 m0, s10
	s_nop 0
	global_load_lds_dwordx4 v[6:7], off
	v_lshl_add_u64 v[6:7], s[8:9], 0, v[162:163]
	s_add_i32 m0, s10, 0x2000
	s_nop 0
	global_load_lds_dwordx4 v[6:7], off
	v_lshl_add_u64 v[6:7], v[222:223], 0, s[92:93]
	s_mov_b32 m0, s67
	s_nop 0
	global_load_lds_dwordx4 v[6:7], off
	v_lshl_add_u64 v[6:7], v[224:225], 0, s[92:93]
	s_mov_b32 m0, s81
	s_nop 0
	global_load_lds_dwordx4 v[6:7], off
	s_waitcnt vmcnt(8)
	s_waitcnt lgkmcnt(0)
	s_barrier
	s_waitcnt lgkmcnt(0)
	v_mfma_f32_16x16x32_bf16 v[72:75], v[52:55], v[176:179], v[72:75]
	v_mfma_f32_16x16x32_bf16 v[72:75], v[56:59], v[180:183], v[72:75]
	v_mfma_f32_16x16x32_bf16 v[64:67], v[76:79], v[176:179], v[64:67]
	v_mfma_f32_16x16x32_bf16 v[64:67], v[80:83], v[180:183], v[64:67]
	v_mfma_f32_16x16x32_bf16 v[60:63], v[76:79], v[190:193], v[60:63]
	v_mfma_f32_16x16x32_bf16 v[60:63], v[80:83], v[194:197], v[60:63]
	v_mfma_f32_16x16x32_bf16 v[68:71], v[52:55], v[190:193], v[68:71]
	v_mfma_f32_16x16x32_bf16 v[68:71], v[56:59], v[194:197], v[68:71]
	v_mfma_f32_16x16x32_bf16 v[48:51], v[52:55], v[198:201], v[48:51]
	v_mfma_f32_16x16x32_bf16 v[48:51], v[56:59], v[210:213], v[48:51]
	v_mfma_f32_16x16x32_bf16 v[44:47], v[76:79], v[198:201], v[44:47]
	v_mfma_f32_16x16x32_bf16 v[44:47], v[80:83], v[210:213], v[44:47]
	v_mfma_f32_16x16x32_bf16 v[36:39], v[76:79], v[214:217], v[36:39]
	v_mfma_f32_16x16x32_bf16 v[36:39], v[80:83], v[218:221], v[36:39]
	v_mfma_f32_16x16x32_bf16 v[40:43], v[52:55], v[214:217], v[40:43]
	v_mfma_f32_16x16x32_bf16 v[40:43], v[56:59], v[218:221], v[40:43]
	v_mfma_f32_16x16x32_bf16 v[32:35], v[116:119], v[176:179], v[32:35]
	v_mfma_f32_16x16x32_bf16 v[32:35], v[120:123], v[180:183], v[32:35]
	v_mfma_f32_16x16x32_bf16 v[24:27], v[168:171], v[176:179], v[24:27]
	v_mfma_f32_16x16x32_bf16 v[24:27], v[172:175], v[180:183], v[24:27]
	v_mfma_f32_16x16x32_bf16 v[20:23], v[168:171], v[190:193], v[20:23]
	v_mfma_f32_16x16x32_bf16 v[20:23], v[172:175], v[194:197], v[20:23]
	v_mfma_f32_16x16x32_bf16 v[28:31], v[116:119], v[190:193], v[28:31]
	v_mfma_f32_16x16x32_bf16 v[28:31], v[120:123], v[194:197], v[28:31]
	v_mfma_f32_16x16x32_bf16 v[16:19], v[116:119], v[198:201], v[16:19]
	v_mfma_f32_16x16x32_bf16 v[16:19], v[120:123], v[210:213], v[16:19]
	v_mfma_f32_16x16x32_bf16 v[12:15], v[168:171], v[198:201], v[12:15]
	v_mfma_f32_16x16x32_bf16 v[12:15], v[172:175], v[210:213], v[12:15]
	v_mfma_f32_16x16x32_bf16 v[2:5], v[168:171], v[214:217], v[2:5]
	v_mfma_f32_16x16x32_bf16 v[6:9], v[116:119], v[214:217], v[8:11]
	v_mfma_f32_16x16x32_bf16 v[8:11], v[120:123], v[218:221], v[6:9]
	v_mfma_f32_16x16x32_bf16 v[4:7], v[172:175], v[218:221], v[2:5]
	s_barrier
	s_add_i32 s4, s4, 2
	s_add_u32 s97, s97, 0x100
	s_addc_u32 s96, s96, 0
	s_cmp_gt_u32 s4, 29
	s_mov_b64 s[8:9], s[68:69]
	s_cbranch_scc0 .LBB0_327

; #define PG8_STAGE(bufoff, gbase, voff) do { _Pragma("unroll") for (int _i = 0; _i < 2; ++_i) \
;         __builtin_amdgcn_global_load_lds((const unsigned*)((const char*)(gbase) + (voff)[_i]), (PG8_LAS unsigned*)(lds + (bufoff) + ldsw + _i * 8192), 16, 0, 0); } while (0)
; #define PG8_LDA(dst, b, h) do { _Pragma("unroll") for (int m = 0; m < 4; ++m) _Pragma("unroll") for (int k = 0; k < 2; ++k) dst[m][k] = *(const PG8_LAS bf16x8*)(lds + PG8_SA(b, h) + aoff + m * 2048 + k * 1024); } while (0)
; #define PG8_LDB(dst, b, h) do { _Pragma("unroll") for (int n = 0; n < 2; ++n) _Pragma("unroll") for (int k = 0; k < 2; ++k) dst[n][k] = *(const PG8_LAS bf16x8*)(lds + PG8_SB(b, h) + boff + n * 2048 + k * 1024); } while (0)
; #define PG8_MMA(ai, bj, At, Bt) do { __builtin_amdgcn_s_setprio(1); _Pragma("unroll") for (int m = 0; m < 4; ++m) _Pragma("unroll") for (int n = 0; n < 2; ++n) _Pragma("unroll") for (int k = 0; k < 2; ++k) \
;         acc[ai][bj][m][n] = mma16<Epi::I8>(Bt[n][k], At[m][k], acc[ai][bj][m][n]); __builtin_amdgcn_s_setprio(0); } while (0)
; #define PG8_WAIT_V(n) asm volatile("s_waitcnt vmcnt(" #n ")" ::: "memory")
; #define PG8_WAIT_L(n) asm volatile("s_waitcnt lgkmcnt(" #n ")" ::: "memory")
; template <class Epi, class Sched, bool ALIGN_EPI = false, bool SP2 = false>
; __device__ __forceinline__ void gemm_phase(PG8_LAS unsigned char* lds, const Gemm g, const Sched& S, const Epi& E) {
;     ...
;         for (int t = 0; t < nt; t += 2) {
;             const bool last = (t == nt - 2);
;             const char* a1 = cA + (size_t)(t + 1) * kstep;
;             const char* a2 = last ? nA : cA + (size_t)(t + 2) * kstep; const char* b2 = last ? nB : cB + (size_t)(t + 2) * kstep;
;             const char* a3 = a2 + kstep; const char* b3 = b2 + kstep;
;             if (last && has_next) S.a_ready(nxt);
;             if constexpr (SP2) {
;             PG8_LDB(B0, 0, 0); PG8_LDB(B1, 0, 1); PG8_SCHED; PG8_LDA(At, 0, 0); PG8_STAGE(PG8_SA(1, 1), a1 + hstep, voffA);
;             PG8_WAIT_V(8); PG8_WAIT_L(0); PG8_BAR; PG8_MMA(0, 0, At, B0); PG8_MMA(0, 1, At, B1); PG8_BAR; PG8_SCHED;
;             PG8_LDA(At, 0, 1); PG8_STAGE(PG8_SB(0, 0), b2, voffB); PG8_STAGE(PG8_SB(0, 1), b2 + hstep, voffB); PG8_STAGE(PG8_SA(0, 0), a2, voffA);
;             PG8_WAIT_V(8); PG8_WAIT_L(0); PG8_BAR; PG8_MMA(1, 0, At, B0); PG8_MMA(1, 1, At, B1); PG8_BAR; PG8_SCHED;
.Lpeel385:
	s_add_u32 s70, s8, 0x100
	s_addc_u32 s71, s9, 0
	s_add_i32 s84, 0, 0x10000
	s_cmp_eq_u32 s5, 12
	s_cselect_b32 vcc_hi, s1, s71
	s_cselect_b32 vcc_lo, s7, s70
	v_add_u32_e32 v0, s84, v214
	s_cselect_b32 s83, s69, s68
	s_cselect_b32 s82, s81, s85
	s_add_i32 s10, 0, 0x14000
	ds_read_b128 v[44:47], v0
	ds_read_b128 v[52:55], v0 offset:1024
	ds_read_b128 v[60:63], v0 offset:2048
	ds_read_b128 v[64:67], v0 offset:3072
	v_add_u32_e32 v0, s10, v214
	ds_read_b128 v[84:87], v0
	ds_read_b128 v[88:91], v0 offset:1024
	ds_read_b128 v[92:95], v0 offset:2048
	ds_read_b128 v[100:103], v0 offset:3072
	v_lshl_add_u64 v[2:3], s[8:9], 0, v[184:185]
	s_add_i32 m0, s13, 0xc000
	ds_read_b128 v[124:127], v215
	ds_read_b128 v[128:131], v215 offset:1024
	ds_read_b128 v[140:143], v215 offset:2048
	ds_read_b128 v[188:191], v215 offset:3072
	ds_read_b128 v[192:195], v215 offset:4096
	ds_read_b128 v[196:199], v215 offset:5120
	ds_read_b128 v[216:219], v215 offset:6144
	ds_read_b128 v[220:223], v215 offset:7168
	global_load_lds_dwordx4 v[2:3], off
	v_lshl_add_u64 v[2:3], s[8:9], 0, v[186:187]
	s_add_i32 m0, s13, 0xe000
	s_nop 0
	global_load_lds_dwordx4 v[2:3], off
	s_waitcnt vmcnt(8)
	s_waitcnt lgkmcnt(0)
	s_barrier
	s_waitcnt lgkmcnt(0)
	v_mfma_i32_16x16x64_i8 v[172:175], v[44:47], v[124:127], 0
	v_mfma_i32_16x16x64_i8 v[172:175], v[52:55], v[128:131], v[172:175]
	v_mfma_i32_16x16x64_i8 v[164:167], v[60:63], v[124:127], 0
	v_mfma_i32_16x16x64_i8 v[164:167], v[64:67], v[128:131], v[164:167]
	v_mfma_i32_16x16x64_i8 v[160:163], v[60:63], v[140:143], 0
	v_mfma_i32_16x16x64_i8 v[160:163], v[64:67], v[188:191], v[160:163]
	v_mfma_i32_16x16x64_i8 v[168:171], v[44:47], v[140:143], 0
	v_mfma_i32_16x16x64_i8 v[168:171], v[52:55], v[188:191], v[168:171]
	v_mfma_i32_16x16x64_i8 v[156:159], v[44:47], v[192:195], 0
	v_mfma_i32_16x16x64_i8 v[156:159], v[52:55], v[196:199], v[156:159]
	v_mfma_i32_16x16x64_i8 v[152:155], v[60:63], v[192:195], 0
	v_mfma_i32_16x16x64_i8 v[152:155], v[64:67], v[196:199], v[152:155]
	v_mfma_i32_16x16x64_i8 v[144:147], v[60:63], v[216:219], 0
	v_mfma_i32_16x16x64_i8 v[144:147], v[64:67], v[220:223], v[144:147]
	v_mfma_i32_16x16x64_i8 v[148:151], v[44:47], v[216:219], 0
	v_mfma_i32_16x16x64_i8 v[148:151], v[52:55], v[220:223], v[148:151]
	v_mfma_i32_16x16x64_i8 v[136:139], v[84:87], v[124:127], 0
	v_mfma_i32_16x16x64_i8 v[136:139], v[88:91], v[128:131], v[136:139]
	v_mfma_i32_16x16x64_i8 v[120:123], v[92:95], v[124:127], 0
	v_mfma_i32_16x16x64_i8 v[120:123], v[100:103], v[128:131], v[120:123]
	v_mfma_i32_16x16x64_i8 v[116:119], v[92:95], v[140:143], 0
	v_mfma_i32_16x16x64_i8 v[116:119], v[100:103], v[188:191], v[116:119]
	v_mfma_i32_16x16x64_i8 v[108:111], v[92:95], v[192:195], 0
	v_mfma_i32_16x16x64_i8 v[108:111], v[100:103], v[196:199], v[108:111]
	v_mfma_i32_16x16x64_i8 v[112:115], v[84:87], v[192:195], 0
	v_mfma_i32_16x16x64_i8 v[112:115], v[88:91], v[196:199], v[112:115]
	v_mfma_i32_16x16x64_i8 v[104:107], v[84:87], v[216:219], 0
	v_mfma_i32_16x16x64_i8 v[104:107], v[88:91], v[220:223], v[104:107]
	v_mfma_i32_16x16x64_i8 v[96:99], v[92:95], v[216:219], 0
	v_mfma_i32_16x16x64_i8 v[96:99], v[100:103], v[220:223], v[96:99]
	v_mfma_i32_16x16x64_i8 v[124:127], v[84:87], v[140:143], 0
	v_mfma_i32_16x16x64_i8 v[124:127], v[88:91], v[188:191], v[124:127]
	s_barrier
	s_add_i32 s8, s84, s12
	v_lshl_add_u64 v[200:201], s[82:83], 0, v[178:179]
	s_mov_b32 m0, s8
	ds_read_b128 v[128:131], v215 offset:16384
	ds_read_b128 v[132:135], v215 offset:17408
	ds_read_b128 v[140:143], v215 offset:18432
	ds_read_b128 v[188:191], v215 offset:19456
	ds_read_b128 v[192:195], v215 offset:20480
	ds_read_b128 v[196:199], v215 offset:21504
	ds_read_b128 v[216:219], v215 offset:22528
	ds_read_b128 v[220:223], v215 offset:23552
	global_load_lds_dwordx4 v[200:201], off
	s_add_i32 m0, s8, 0x2000
	s_add_u32 s8, s82, 0x40000
	v_lshl_add_u64 v[206:207], s[82:83], 0, v[182:183]
	s_addc_u32 s9, s83, 0
	s_add_i32 s10, s10, s12
	global_load_lds_dwordx4 v[206:207], off
	v_lshl_add_u64 v[2:3], s[8:9], 0, v[178:179]
	s_mov_b32 m0, s10
	v_lshl_add_u64 v[210:211], vcc, 0, v[176:177]
	global_load_lds_dwordx4 v[2:3], off
	v_lshl_add_u64 v[2:3], s[8:9], 0, v[182:183]
	s_add_i32 m0, s10, 0x2000
	v_lshl_add_u64 v[224:225], vcc, 0, v[180:181]
	global_load_lds_dwordx4 v[2:3], off
	s_mov_b32 m0, s13
	s_nop 0
	global_load_lds_dwordx4 v[210:211], off
	s_mov_b32 m0, s66
	s_nop 0
	global_load_lds_dwordx4 v[224:225], off
	s_waitcnt vmcnt(8)
	s_waitcnt lgkmcnt(0)
	s_barrier
	s_waitcnt lgkmcnt(0)
	v_mfma_i32_16x16x64_i8 v[80:83], v[44:47], v[128:131], 0
	v_mfma_i32_16x16x64_i8 v[80:83], v[52:55], v[132:135], v[80:83]
	v_mfma_i32_16x16x64_i8 v[72:75], v[60:63], v[128:131], 0
	v_mfma_i32_16x16x64_i8 v[72:75], v[64:67], v[132:135], v[72:75]
	v_mfma_i32_16x16x64_i8 v[68:71], v[60:63], v[140:143], 0
	v_mfma_i32_16x16x64_i8 v[68:71], v[64:67], v[188:191], v[68:71]
	v_mfma_i32_16x16x64_i8 v[76:79], v[44:47], v[140:143], 0
	v_mfma_i32_16x16x64_i8 v[76:79], v[52:55], v[188:191], v[76:79]
	v_mfma_i32_16x16x64_i8 v[56:59], v[44:47], v[192:195], 0
	v_mfma_i32_16x16x64_i8 v[56:59], v[52:55], v[196:199], v[56:59]
	v_mfma_i32_16x16x64_i8 v[48:51], v[60:63], v[192:195], 0
	v_mfma_i32_16x16x64_i8 v[48:51], v[64:67], v[196:199], v[48:51]
	v_mfma_i32_16x16x64_i8 v[36:39], v[60:63], v[216:219], 0
	v_mfma_i32_16x16x64_i8 v[36:39], v[64:67], v[220:223], v[36:39]
	v_mfma_i32_16x16x64_i8 v[40:43], v[44:47], v[216:219], 0
	v_mfma_i32_16x16x64_i8 v[40:43], v[52:55], v[220:223], v[40:43]
	v_mfma_i32_16x16x64_i8 v[32:35], v[84:87], v[128:131], 0
	v_mfma_i32_16x16x64_i8 v[32:35], v[88:91], v[132:135], v[32:35]
	v_mfma_i32_16x16x64_i8 v[24:27], v[92:95], v[128:131], 0
	v_mfma_i32_16x16x64_i8 v[24:27], v[100:103], v[132:135], v[24:27]
	v_mfma_i32_16x16x64_i8 v[20:23], v[92:95], v[140:143], 0
	v_mfma_i32_16x16x64_i8 v[20:23], v[100:103], v[188:191], v[20:23]
	v_mfma_i32_16x16x64_i8 v[28:31], v[84:87], v[140:143], 0
	v_mfma_i32_16x16x64_i8 v[28:31], v[88:91], v[188:191], v[28:31]
	v_mfma_i32_16x16x64_i8 v[16:19], v[84:87], v[192:195], 0
	v_mfma_i32_16x16x64_i8 v[16:19], v[88:91], v[196:199], v[16:19]
	v_mfma_i32_16x16x64_i8 v[12:15], v[92:95], v[192:195], 0
	v_mfma_i32_16x16x64_i8 v[12:15], v[100:103], v[196:199], v[12:15]
	v_mfma_i32_16x16x64_i8 v[2:5], v[92:95], v[216:219], 0
	v_mfma_i32_16x16x64_i8 v[2:5], v[100:103], v[220:223], v[2:5]
	v_mfma_i32_16x16x64_i8 v[8:11], v[84:87], v[216:219], 0
	v_mfma_i32_16x16x64_i8 v[8:11], v[88:91], v[220:223], v[8:11]
	s_barrier
; #define PG8_STAGE(bufoff, gbase, voff) do { _Pragma("unroll") for (int _i = 0; _i < 2; ++_i) \
;         __builtin_amdgcn_global_load_lds((const unsigned*)((const char*)(gbase) + (voff)[_i]), (PG8_LAS unsigned*)(lds + (bufoff) + ldsw + _i * 8192), 16, 0, 0); } while (0)
; #define PG8_LDA(dst, b, h) do { _Pragma("unroll") for (int m = 0; m < 4; ++m) _Pragma("unroll") for (int k = 0; k < 2; ++k) dst[m][k] = *(const PG8_LAS bf16x8*)(lds + PG8_SA(b, h) + aoff + m * 2048 + k * 1024); } while (0)
; #define PG8_LDB(dst, b, h) do { _Pragma("unroll") for (int n = 0; n < 2; ++n) _Pragma("unroll") for (int k = 0; k < 2; ++k) dst[n][k] = *(const PG8_LAS bf16x8*)(lds + PG8_SB(b, h) + boff + n * 2048 + k * 1024); } while (0)
; #define PG8_MMA(ai, bj, At, Bt) do { __builtin_amdgcn_s_setprio(1); _Pragma("unroll") for (int m = 0; m < 4; ++m) _Pragma("unroll") for (int n = 0; n < 2; ++n) _Pragma("unroll") for (int k = 0; k < 2; ++k) \
;         acc[ai][bj][m][n] = mma16<Epi::I8>(Bt[n][k], At[m][k], acc[ai][bj][m][n]); __builtin_amdgcn_s_setprio(0); } while (0)
; #define PG8_WAIT_V(n) asm volatile("s_waitcnt vmcnt(" #n ")" ::: "memory")
; #define PG8_WAIT_L(n) asm volatile("s_waitcnt lgkmcnt(" #n ")" ::: "memory")
; #define PG8_BAR __builtin_amdgcn_s_barrier()
; #define PG8_SCHED __builtin_amdgcn_sched_barrier(0)
; template <class Epi, class Sched, bool ALIGN_EPI = false, bool SP2 = false>
; __device__ __forceinline__ void gemm_phase(PG8_LAS unsigned char* lds, const Gemm g, const Sched& S, const Epi& E) {
;     ...
;         for (int t = 0; t < nt; t += 2) {
;     ...
;             PG8_LDB(B0, 1, 0); PG8_LDB(B1, 1, 1); PG8_SCHED; PG8_LDA(At, 1, 0); PG8_STAGE(PG8_SA(0, 1), a2 + hstep, voffA);
;             PG8_WAIT_V(8); PG8_WAIT_L(0); PG8_BAR; PG8_MMA(0, 0, At, B0); PG8_MMA(0, 1, At, B1); PG8_BAR; PG8_SCHED;
;             PG8_LDA(At, 1, 1); PG8_STAGE(PG8_SB(1, 0), b3, voffB); PG8_STAGE(PG8_SB(1, 1), b3 + hstep, voffB); PG8_STAGE(PG8_SA(1, 0), a3, voffA);
;             PG8_WAIT_V(8); PG8_WAIT_L(0); PG8_BAR; PG8_MMA(1, 0, At, B0); PG8_MMA(1, 1, At, B1); PG8_BAR; PG8_SCHED;
	s_add_i32 s10, 0, 0x18000
	v_add_u32_e32 v0, s10, v214
	s_add_i32 s11, 0, 0x1c000
	ds_read_b128 v[44:47], v0
	ds_read_b128 v[52:55], v0 offset:1024
	ds_read_b128 v[60:63], v0 offset:2048
	ds_read_b128 v[64:67], v0 offset:3072
	v_add_u32_e32 v0, s11, v214
	ds_read_b128 v[84:87], v0
	ds_read_b128 v[88:91], v0 offset:1024
	ds_read_b128 v[92:95], v0 offset:2048
	ds_read_b128 v[100:103], v0 offset:3072
	s_add_u32 s8, vcc_lo, 0x40000
	s_addc_u32 s9, vcc_hi, 0
	s_mov_b32 m0, s67
	v_lshl_add_u64 v[6:7], s[8:9], 0, v[176:177]
	ds_read_b128 v[128:131], v215 offset:32768
	ds_read_b128 v[132:135], v215 offset:33792
	ds_read_b128 v[140:143], v215 offset:34816
	ds_read_b128 v[188:191], v215 offset:35840
	ds_read_b128 v[192:195], v215 offset:36864
	ds_read_b128 v[196:199], v215 offset:37888
	ds_read_b128 v[216:219], v215 offset:38912
	ds_read_b128 v[220:223], v215 offset:39936
	global_load_lds_dwordx4 v[6:7], off
	v_lshl_add_u64 v[6:7], s[8:9], 0, v[180:181]
	s_mov_b32 m0, s80
	s_nop 0
	global_load_lds_dwordx4 v[6:7], off
	s_waitcnt vmcnt(8)
	s_waitcnt lgkmcnt(0)
	s_barrier
	s_waitcnt lgkmcnt(0)
	v_mfma_i32_16x16x64_i8 v[172:175], v[44:47], v[128:131], v[172:175]
	v_mfma_i32_16x16x64_i8 v[172:175], v[52:55], v[132:135], v[172:175]
	v_mfma_i32_16x16x64_i8 v[164:167], v[60:63], v[128:131], v[164:167]
	v_mfma_i32_16x16x64_i8 v[164:167], v[64:67], v[132:135], v[164:167]
	v_mfma_i32_16x16x64_i8 v[160:163], v[60:63], v[140:143], v[160:163]
	v_mfma_i32_16x16x64_i8 v[160:163], v[64:67], v[188:191], v[160:163]
	v_mfma_i32_16x16x64_i8 v[168:171], v[44:47], v[140:143], v[168:171]
	v_mfma_i32_16x16x64_i8 v[168:171], v[52:55], v[188:191], v[168:171]
	v_mfma_i32_16x16x64_i8 v[156:159], v[44:47], v[192:195], v[156:159]
	v_mfma_i32_16x16x64_i8 v[156:159], v[52:55], v[196:199], v[156:159]
	v_mfma_i32_16x16x64_i8 v[152:155], v[60:63], v[192:195], v[152:155]
	v_mfma_i32_16x16x64_i8 v[152:155], v[64:67], v[196:199], v[152:155]
	v_mfma_i32_16x16x64_i8 v[144:147], v[60:63], v[216:219], v[144:147]
	v_mfma_i32_16x16x64_i8 v[144:147], v[64:67], v[220:223], v[144:147]
	v_mfma_i32_16x16x64_i8 v[148:151], v[44:47], v[216:219], v[148:151]
	v_mfma_i32_16x16x64_i8 v[148:151], v[52:55], v[220:223], v[148:151]
	v_mfma_i32_16x16x64_i8 v[136:139], v[84:87], v[128:131], v[136:139]
	v_mfma_i32_16x16x64_i8 v[136:139], v[88:91], v[132:135], v[136:139]
	v_mfma_i32_16x16x64_i8 v[120:123], v[92:95], v[128:131], v[120:123]
	v_mfma_i32_16x16x64_i8 v[120:123], v[100:103], v[132:135], v[120:123]
	v_mfma_i32_16x16x64_i8 v[116:119], v[92:95], v[140:143], v[116:119]
	v_mfma_i32_16x16x64_i8 v[116:119], v[100:103], v[188:191], v[116:119]
	v_mfma_i32_16x16x64_i8 v[124:127], v[84:87], v[140:143], v[124:127]
	v_mfma_i32_16x16x64_i8 v[132:135], v[88:91], v[188:191], v[124:127]
	v_mfma_i32_16x16x64_i8 v[112:115], v[84:87], v[192:195], v[112:115]
	v_mfma_i32_16x16x64_i8 v[112:115], v[88:91], v[196:199], v[112:115]
	v_mfma_i32_16x16x64_i8 v[108:111], v[92:95], v[192:195], v[108:111]
	v_mfma_i32_16x16x64_i8 v[108:111], v[100:103], v[196:199], v[108:111]
	v_mfma_i32_16x16x64_i8 v[96:99], v[92:95], v[216:219], v[96:99]
	v_mfma_i32_16x16x64_i8 v[96:99], v[100:103], v[220:223], v[96:99]
	v_mfma_i32_16x16x64_i8 v[104:107], v[84:87], v[216:219], v[104:107]
	v_mfma_i32_16x16x64_i8 v[104:107], v[88:91], v[220:223], v[104:107]
	s_barrier
	s_add_i32 s8, s10, s12
	v_lshl_add_u64 v[6:7], v[200:201], 0, s[92:93]
	s_mov_b32 m0, s8
	ds_read_b128 v[124:127], v215 offset:49152
	ds_read_b128 v[128:131], v215 offset:50176
	ds_read_b128 v[140:143], v215 offset:51200
	ds_read_b128 v[188:191], v215 offset:52224
	ds_read_b128 v[192:195], v215 offset:53248
	ds_read_b128 v[196:199], v215 offset:54272
	ds_read_b128 v[216:219], v215 offset:55296
	ds_read_b128 v[220:223], v215 offset:56320
	global_load_lds_dwordx4 v[6:7], off
	s_add_i32 m0, s8, 0x2000
	s_add_u32 s8, s82, 0x40080
	v_lshl_add_u64 v[6:7], v[206:207], 0, s[92:93]
	s_addc_u32 s9, s83, 0
	s_add_i32 s10, s11, s12
	global_load_lds_dwordx4 v[6:7], off
	v_lshl_add_u64 v[6:7], s[8:9], 0, v[178:179]
	s_mov_b32 m0, s10
	s_nop 0
	global_load_lds_dwordx4 v[6:7], off
	v_lshl_add_u64 v[6:7], s[8:9], 0, v[182:183]
	s_add_i32 m0, s10, 0x2000
	s_nop 0
	global_load_lds_dwordx4 v[6:7], off
	v_lshl_add_u64 v[6:7], v[210:211], 0, s[92:93]
	s_mov_b32 m0, s58
	s_nop 0
	global_load_lds_dwordx4 v[6:7], off
	v_lshl_add_u64 v[6:7], v[224:225], 0, s[92:93]
	s_mov_b32 m0, s4
	s_nop 0
	global_load_lds_dwordx4 v[6:7], off
	s_waitcnt vmcnt(8)
	s_waitcnt lgkmcnt(0)
	s_barrier
	s_waitcnt lgkmcnt(0)
	v_mfma_i32_16x16x64_i8 v[80:83], v[44:47], v[124:127], v[80:83]
	v_mfma_i32_16x16x64_i8 v[80:83], v[52:55], v[128:131], v[80:83]
	v_mfma_i32_16x16x64_i8 v[72:75], v[60:63], v[124:127], v[72:75]
	v_mfma_i32_16x16x64_i8 v[72:75], v[64:67], v[128:131], v[72:75]
	v_mfma_i32_16x16x64_i8 v[68:71], v[60:63], v[140:143], v[68:71]
	v_mfma_i32_16x16x64_i8 v[68:71], v[64:67], v[188:191], v[68:71]
	v_mfma_i32_16x16x64_i8 v[76:79], v[44:47], v[140:143], v[76:79]
	v_mfma_i32_16x16x64_i8 v[76:79], v[52:55], v[188:191], v[76:79]
	v_mfma_i32_16x16x64_i8 v[56:59], v[44:47], v[192:195], v[56:59]
	v_mfma_i32_16x16x64_i8 v[56:59], v[52:55], v[196:199], v[56:59]
	v_mfma_i32_16x16x64_i8 v[48:51], v[60:63], v[192:195], v[48:51]
	v_mfma_i32_16x16x64_i8 v[48:51], v[64:67], v[196:199], v[48:51]
	v_mfma_i32_16x16x64_i8 v[36:39], v[60:63], v[216:219], v[36:39]
	v_mfma_i32_16x16x64_i8 v[36:39], v[64:67], v[220:223], v[36:39]
	v_mfma_i32_16x16x64_i8 v[40:43], v[44:47], v[216:219], v[40:43]
	v_mfma_i32_16x16x64_i8 v[40:43], v[52:55], v[220:223], v[40:43]
	v_mfma_i32_16x16x64_i8 v[32:35], v[84:87], v[124:127], v[32:35]
	v_mfma_i32_16x16x64_i8 v[32:35], v[88:91], v[128:131], v[32:35]
	v_mfma_i32_16x16x64_i8 v[24:27], v[92:95], v[124:127], v[24:27]
	v_mfma_i32_16x16x64_i8 v[24:27], v[100:103], v[128:131], v[24:27]
	v_mfma_i32_16x16x64_i8 v[20:23], v[92:95], v[140:143], v[20:23]
	v_mfma_i32_16x16x64_i8 v[20:23], v[100:103], v[188:191], v[20:23]
	v_mfma_i32_16x16x64_i8 v[28:31], v[84:87], v[140:143], v[28:31]
	v_mfma_i32_16x16x64_i8 v[28:31], v[88:91], v[188:191], v[28:31]
	v_mfma_i32_16x16x64_i8 v[16:19], v[84:87], v[192:195], v[16:19]
	v_mfma_i32_16x16x64_i8 v[16:19], v[88:91], v[196:199], v[16:19]
	v_mfma_i32_16x16x64_i8 v[12:15], v[92:95], v[192:195], v[12:15]
	v_mfma_i32_16x16x64_i8 v[12:15], v[100:103], v[196:199], v[12:15]
	v_mfma_i32_16x16x64_i8 v[2:5], v[92:95], v[216:219], v[2:5]
	v_mfma_i32_16x16x64_i8 v[6:9], v[84:87], v[216:219], v[8:11]
	v_mfma_i32_16x16x64_i8 v[8:11], v[88:91], v[220:223], v[6:9]
	v_mfma_i32_16x16x64_i8 v[4:7], v[100:103], v[220:223], v[2:5]
	s_barrier
	s_add_i32 s5, s5, 2
	s_add_u32 s85, s85, 0x100
	s_addc_u32 s68, s68, 0
	s_cmp_gt_u32 s5, 13
	s_mov_b64 s[8:9], s[70:71]
	s_cbranch_scc0 .LBB0_385
	s_branch .Lpeelx385
; #define PG8_STAGE(bufoff, gbase, voff) do { _Pragma("unroll") for (int _i = 0; _i < 2; ++_i) \
;         __builtin_amdgcn_global_load_lds((const unsigned*)((const char*)(gbase) + (voff)[_i]), (PG8_LAS unsigned*)(lds + (bufoff) + ldsw + _i * 8192), 16, 0, 0); } while (0)
; #define PG8_LDA(dst, b, h) do { _Pragma("unroll") for (int m = 0; m < 4; ++m) _Pragma("unroll") for (int k = 0; k < 2; ++k) dst[m][k] = *(const PG8_LAS bf16x8*)(lds + PG8_SA(b, h) + aoff + m * 2048 + k * 1024); } while (0)
; #define PG8_LDB(dst, b, h) do { _Pragma("unroll") for (int n = 0; n < 2; ++n) _Pragma("unroll") for (int k = 0; k < 2; ++k) dst[n][k] = *(const PG8_LAS bf16x8*)(lds + PG8_SB(b, h) + boff + n * 2048 + k * 1024); } while (0)
; #define PG8_MMA(ai, bj, At, Bt) do { __builtin_amdgcn_s_setprio(1); _Pragma("unroll") for (int m = 0; m < 4; ++m) _Pragma("unroll") for (int n = 0; n < 2; ++n) _Pragma("unroll") for (int k = 0; k < 2; ++k) \
;         acc[ai][bj][m][n] = mma16<Epi::I8>(Bt[n][k], At[m][k], acc[ai][bj][m][n]); __builtin_amdgcn_s_setprio(0); } while (0)
; #define PG8_WAIT_V(n) asm volatile("s_waitcnt vmcnt(" #n ")" ::: "memory")
; template <class Epi, class Sched, bool ALIGN_EPI = false, bool SP2 = false>
; __device__ __forceinline__ void gemm_phase(PG8_LAS unsigned char* lds, const Gemm g, const Sched& S, const Epi& E) {
;     ...
;         const bool has_next = S.next(ui + 1, nxt);
;         const char* nA = has_next ? (const char*)g.A + (size_t)nxt.pm * tstep : cA; const char* nB = has_next ? (const char*)g.Bt + (size_t)nxt.pn * tstep : cB;
;         for (int t = 0; t < nt; t += 2) {
;             const bool last = (t == nt - 2);
;             const char* a1 = cA + (size_t)(t + 1) * kstep;
;             const char* a2 = last ? nA : cA + (size_t)(t + 2) * kstep; const char* b2 = last ? nB : cB + (size_t)(t + 2) * kstep;
;             const char* a3 = a2 + kstep; const char* b3 = b2 + kstep;
;             if (last && has_next) S.a_ready(nxt);
;             if constexpr (SP2) {
;             PG8_LDB(B0, 0, 0); PG8_LDB(B1, 0, 1); PG8_SCHED; PG8_LDA(At, 0, 0); PG8_STAGE(PG8_SA(1, 1), a1 + hstep, voffA);
;             PG8_WAIT_V(8); PG8_WAIT_L(0); PG8_BAR; PG8_MMA(0, 0, At, B0); PG8_MMA(0, 1, At, B1); PG8_BAR; PG8_SCHED;
;             PG8_LDA(At, 0, 1); PG8_STAGE(PG8_SB(0, 0), b2, voffB); PG8_STAGE(PG8_SB(0, 1), b2 + hstep, voffB); PG8_STAGE(PG8_SA(0, 0), a2, voffA);
.LBB0_385:
	s_add_u32 s70, s8, 0x100
	s_addc_u32 s71, s9, 0
	s_add_i32 s84, 0, 0x10000
	s_cmp_eq_u32 s5, 12
	s_cselect_b32 vcc_hi, s1, s71
	s_cselect_b32 vcc_lo, s7, s70
	v_add_u32_e32 v0, s84, v214
	s_cselect_b32 s83, s69, s68
	s_cselect_b32 s82, s81, s85
	s_add_i32 s10, 0, 0x14000
	ds_read_b128 v[44:47], v0
	ds_read_b128 v[52:55], v0 offset:1024
	ds_read_b128 v[60:63], v0 offset:2048
	ds_read_b128 v[64:67], v0 offset:3072
	v_add_u32_e32 v0, s10, v214
	ds_read_b128 v[84:87], v0
	ds_read_b128 v[88:91], v0 offset:1024
	ds_read_b128 v[92:95], v0 offset:2048
	ds_read_b128 v[100:103], v0 offset:3072
	v_lshl_add_u64 v[2:3], s[8:9], 0, v[184:185]
	s_add_i32 m0, s13, 0xc000
	ds_read_b128 v[124:127], v215
	ds_read_b128 v[128:131], v215 offset:1024
	ds_read_b128 v[140:143], v215 offset:2048
	ds_read_b128 v[188:191], v215 offset:3072
	ds_read_b128 v[192:195], v215 offset:4096
	ds_read_b128 v[196:199], v215 offset:5120
	ds_read_b128 v[216:219], v215 offset:6144
	ds_read_b128 v[220:223], v215 offset:7168
	global_load_lds_dwordx4 v[2:3], off
	v_lshl_add_u64 v[2:3], s[8:9], 0, v[186:187]
	s_add_i32 m0, s13, 0xe000
	s_nop 0
	global_load_lds_dwordx4 v[2:3], off
	s_waitcnt vmcnt(8)
	s_waitcnt lgkmcnt(0)
	s_barrier
	s_waitcnt lgkmcnt(0)
	v_mfma_i32_16x16x64_i8 v[172:175], v[44:47], v[124:127], v[172:175]
	v_mfma_i32_16x16x64_i8 v[172:175], v[52:55], v[128:131], v[172:175]
	v_mfma_i32_16x16x64_i8 v[164:167], v[60:63], v[124:127], v[164:167]
	v_mfma_i32_16x16x64_i8 v[164:167], v[64:67], v[128:131], v[164:167]
	v_mfma_i32_16x16x64_i8 v[160:163], v[60:63], v[140:143], v[160:163]
	v_mfma_i32_16x16x64_i8 v[160:163], v[64:67], v[188:191], v[160:163]
	v_mfma_i32_16x16x64_i8 v[168:171], v[44:47], v[140:143], v[168:171]
	v_mfma_i32_16x16x64_i8 v[168:171], v[52:55], v[188:191], v[168:171]
	v_mfma_i32_16x16x64_i8 v[156:159], v[44:47], v[192:195], v[156:159]
	v_mfma_i32_16x16x64_i8 v[156:159], v[52:55], v[196:199], v[156:159]
	v_mfma_i32_16x16x64_i8 v[152:155], v[60:63], v[192:195], v[152:155]
	v_mfma_i32_16x16x64_i8 v[152:155], v[64:67], v[196:199], v[152:155]
	v_mfma_i32_16x16x64_i8 v[144:147], v[60:63], v[216:219], v[144:147]
	v_mfma_i32_16x16x64_i8 v[144:147], v[64:67], v[220:223], v[144:147]
	v_mfma_i32_16x16x64_i8 v[148:151], v[44:47], v[216:219], v[148:151]
	v_mfma_i32_16x16x64_i8 v[148:151], v[52:55], v[220:223], v[148:151]
	v_mfma_i32_16x16x64_i8 v[136:139], v[84:87], v[124:127], v[136:139]
	v_mfma_i32_16x16x64_i8 v[136:139], v[88:91], v[128:131], v[136:139]
	v_mfma_i32_16x16x64_i8 v[120:123], v[92:95], v[124:127], v[120:123]
	v_mfma_i32_16x16x64_i8 v[120:123], v[100:103], v[128:131], v[120:123]
	v_mfma_i32_16x16x64_i8 v[116:119], v[92:95], v[140:143], v[116:119]
	v_mfma_i32_16x16x64_i8 v[116:119], v[100:103], v[188:191], v[116:119]
	v_mfma_i32_16x16x64_i8 v[108:111], v[92:95], v[192:195], v[108:111]
	v_mfma_i32_16x16x64_i8 v[108:111], v[100:103], v[196:199], v[108:111]
	v_mfma_i32_16x16x64_i8 v[112:115], v[84:87], v[192:195], v[112:115]
	v_mfma_i32_16x16x64_i8 v[112:115], v[88:91], v[196:199], v[112:115]
	v_mfma_i32_16x16x64_i8 v[104:107], v[84:87], v[216:219], v[104:107]
	v_mfma_i32_16x16x64_i8 v[104:107], v[88:91], v[220:223], v[104:107]
	v_mfma_i32_16x16x64_i8 v[96:99], v[92:95], v[216:219], v[96:99]
	v_mfma_i32_16x16x64_i8 v[96:99], v[100:103], v[220:223], v[96:99]
	v_mfma_i32_16x16x64_i8 v[124:127], v[84:87], v[140:143], v[132:135]
	v_mfma_i32_16x16x64_i8 v[124:127], v[88:91], v[188:191], v[124:127]
	s_barrier
	s_add_i32 s8, s84, s12
	v_lshl_add_u64 v[200:201], s[82:83], 0, v[178:179]
	s_mov_b32 m0, s8
	ds_read_b128 v[128:131], v215 offset:16384
	ds_read_b128 v[132:135], v215 offset:17408
	ds_read_b128 v[140:143], v215 offset:18432
	ds_read_b128 v[188:191], v215 offset:19456
	ds_read_b128 v[192:195], v215 offset:20480
	ds_read_b128 v[196:199], v215 offset:21504
	ds_read_b128 v[216:219], v215 offset:22528
	ds_read_b128 v[220:223], v215 offset:23552
	global_load_lds_dwordx4 v[200:201], off
	s_add_i32 m0, s8, 0x2000
	s_add_u32 s8, s82, 0x40000
	v_lshl_add_u64 v[206:207], s[82:83], 0, v[182:183]
	s_addc_u32 s9, s83, 0
	s_add_i32 s10, s10, s12
	global_load_lds_dwordx4 v[206:207], off
	v_lshl_add_u64 v[2:3], s[8:9], 0, v[178:179]
	s_mov_b32 m0, s10
	v_lshl_add_u64 v[210:211], vcc, 0, v[176:177]
	global_load_lds_dwordx4 v[2:3], off
	v_lshl_add_u64 v[2:3], s[8:9], 0, v[182:183]
	s_add_i32 m0, s10, 0x2000
	v_lshl_add_u64 v[224:225], vcc, 0, v[180:181]
	global_load_lds_dwordx4 v[2:3], off
	s_mov_b32 m0, s13
	s_nop 0
	global_load_lds_dwordx4 v[210:211], off
	s_mov_b32 m0, s66
	s_nop 0
	global_load_lds_dwordx4 v[224:225], off
	s_waitcnt vmcnt(8)
	s_waitcnt lgkmcnt(0)
	s_barrier
; #define PG8_STAGE(bufoff, gbase, voff) do { _Pragma("unroll") for (int _i = 0; _i < 2; ++_i) \
;         __builtin_amdgcn_global_load_lds((const unsigned*)((const char*)(gbase) + (voff)[_i]), (PG8_LAS unsigned*)(lds + (bufoff) + ldsw + _i * 8192), 16, 0, 0); } while (0)
; #define PG8_LDA(dst, b, h) do { _Pragma("unroll") for (int m = 0; m < 4; ++m) _Pragma("unroll") for (int k = 0; k < 2; ++k) dst[m][k] = *(const PG8_LAS bf16x8*)(lds + PG8_SA(b, h) + aoff + m * 2048 + k * 1024); } while (0)
; #define PG8_LDB(dst, b, h) do { _Pragma("unroll") for (int n = 0; n < 2; ++n) _Pragma("unroll") for (int k = 0; k < 2; ++k) dst[n][k] = *(const PG8_LAS bf16x8*)(lds + PG8_SB(b, h) + boff + n * 2048 + k * 1024); } while (0)
; #define PG8_MMA(ai, bj, At, Bt) do { __builtin_amdgcn_s_setprio(1); _Pragma("unroll") for (int m = 0; m < 4; ++m) _Pragma("unroll") for (int n = 0; n < 2; ++n) _Pragma("unroll") for (int k = 0; k < 2; ++k) \
;         acc[ai][bj][m][n] = mma16<Epi::I8>(Bt[n][k], At[m][k], acc[ai][bj][m][n]); __builtin_amdgcn_s_setprio(0); } while (0)
; #define PG8_WAIT_V(n) asm volatile("s_waitcnt vmcnt(" #n ")" ::: "memory")
; #define PG8_WAIT_L(n) asm volatile("s_waitcnt lgkmcnt(" #n ")" ::: "memory")
; #define PG8_BAR __builtin_amdgcn_s_barrier()
; #define PG8_SCHED __builtin_amdgcn_sched_barrier(0)
; template <class Epi, class Sched, bool ALIGN_EPI = false, bool SP2 = false>
; __device__ __forceinline__ void gemm_phase(PG8_LAS unsigned char* lds, const Gemm g, const Sched& S, const Epi& E) {
;     ...
;             PG8_WAIT_V(8); PG8_WAIT_L(0); PG8_BAR; PG8_MMA(1, 0, At, B0); PG8_MMA(1, 1, At, B1); PG8_BAR; PG8_SCHED;
;             PG8_LDB(B0, 1, 0); PG8_LDB(B1, 1, 1); PG8_SCHED; PG8_LDA(At, 1, 0); PG8_STAGE(PG8_SA(0, 1), a2 + hstep, voffA);
;             PG8_WAIT_V(8); PG8_WAIT_L(0); PG8_BAR; PG8_MMA(0, 0, At, B0); PG8_MMA(0, 1, At, B1); PG8_BAR; PG8_SCHED;
	s_waitcnt lgkmcnt(0)
	v_mfma_i32_16x16x64_i8 v[80:83], v[44:47], v[128:131], v[80:83]
	v_mfma_i32_16x16x64_i8 v[80:83], v[52:55], v[132:135], v[80:83]
	v_mfma_i32_16x16x64_i8 v[72:75], v[60:63], v[128:131], v[72:75]
	v_mfma_i32_16x16x64_i8 v[72:75], v[64:67], v[132:135], v[72:75]
	v_mfma_i32_16x16x64_i8 v[68:71], v[60:63], v[140:143], v[68:71]
	v_mfma_i32_16x16x64_i8 v[68:71], v[64:67], v[188:191], v[68:71]
	v_mfma_i32_16x16x64_i8 v[76:79], v[44:47], v[140:143], v[76:79]
	v_mfma_i32_16x16x64_i8 v[76:79], v[52:55], v[188:191], v[76:79]
	v_mfma_i32_16x16x64_i8 v[56:59], v[44:47], v[192:195], v[56:59]
	v_mfma_i32_16x16x64_i8 v[56:59], v[52:55], v[196:199], v[56:59]
	v_mfma_i32_16x16x64_i8 v[48:51], v[60:63], v[192:195], v[48:51]
	v_mfma_i32_16x16x64_i8 v[48:51], v[64:67], v[196:199], v[48:51]
	v_mfma_i32_16x16x64_i8 v[36:39], v[60:63], v[216:219], v[36:39]
	v_mfma_i32_16x16x64_i8 v[36:39], v[64:67], v[220:223], v[36:39]
	v_mfma_i32_16x16x64_i8 v[40:43], v[44:47], v[216:219], v[40:43]
	v_mfma_i32_16x16x64_i8 v[40:43], v[52:55], v[220:223], v[40:43]
	v_mfma_i32_16x16x64_i8 v[32:35], v[84:87], v[128:131], v[32:35]
	v_mfma_i32_16x16x64_i8 v[32:35], v[88:91], v[132:135], v[32:35]
	v_mfma_i32_16x16x64_i8 v[24:27], v[92:95], v[128:131], v[24:27]
	v_mfma_i32_16x16x64_i8 v[24:27], v[100:103], v[132:135], v[24:27]
	v_mfma_i32_16x16x64_i8 v[20:23], v[92:95], v[140:143], v[20:23]
	v_mfma_i32_16x16x64_i8 v[20:23], v[100:103], v[188:191], v[20:23]
	v_mfma_i32_16x16x64_i8 v[28:31], v[84:87], v[140:143], v[28:31]
	v_mfma_i32_16x16x64_i8 v[28:31], v[88:91], v[188:191], v[28:31]
	v_mfma_i32_16x16x64_i8 v[16:19], v[84:87], v[192:195], v[16:19]
	v_mfma_i32_16x16x64_i8 v[16:19], v[88:91], v[196:199], v[16:19]
	v_mfma_i32_16x16x64_i8 v[12:15], v[92:95], v[192:195], v[12:15]
	v_mfma_i32_16x16x64_i8 v[12:15], v[100:103], v[196:199], v[12:15]
	v_mfma_i32_16x16x64_i8 v[2:5], v[92:95], v[216:219], v[4:7]
	v_mfma_i32_16x16x64_i8 v[2:5], v[100:103], v[220:223], v[2:5]
	v_mfma_i32_16x16x64_i8 v[8:11], v[84:87], v[216:219], v[8:11]
	v_mfma_i32_16x16x64_i8 v[8:11], v[88:91], v[220:223], v[8:11]
	s_barrier
	s_add_i32 s10, 0, 0x18000
	v_add_u32_e32 v0, s10, v214
	s_add_i32 s11, 0, 0x1c000
	ds_read_b128 v[44:47], v0
	ds_read_b128 v[52:55], v0 offset:1024
	ds_read_b128 v[60:63], v0 offset:2048
	ds_read_b128 v[64:67], v0 offset:3072
	v_add_u32_e32 v0, s11, v214
	ds_read_b128 v[84:87], v0
	ds_read_b128 v[88:91], v0 offset:1024
	ds_read_b128 v[92:95], v0 offset:2048
	ds_read_b128 v[100:103], v0 offset:3072
	s_add_u32 s8, vcc_lo, 0x40000
	s_addc_u32 s9, vcc_hi, 0
	s_mov_b32 m0, s67
	v_lshl_add_u64 v[6:7], s[8:9], 0, v[176:177]
	ds_read_b128 v[128:131], v215 offset:32768
	ds_read_b128 v[132:135], v215 offset:33792
	ds_read_b128 v[140:143], v215 offset:34816
	ds_read_b128 v[188:191], v215 offset:35840
	ds_read_b128 v[192:195], v215 offset:36864
	ds_read_b128 v[196:199], v215 offset:37888
	ds_read_b128 v[216:219], v215 offset:38912
	ds_read_b128 v[220:223], v215 offset:39936
	global_load_lds_dwordx4 v[6:7], off
	v_lshl_add_u64 v[6:7], s[8:9], 0, v[180:181]
	s_mov_b32 m0, s80
	s_nop 0
	global_load_lds_dwordx4 v[6:7], off
	s_waitcnt vmcnt(8)
	s_waitcnt lgkmcnt(0)
	s_barrier
	s_waitcnt lgkmcnt(0)
	v_mfma_i32_16x16x64_i8 v[172:175], v[44:47], v[128:131], v[172:175]
	v_mfma_i32_16x16x64_i8 v[172:175], v[52:55], v[132:135], v[172:175]
	v_mfma_i32_16x16x64_i8 v[164:167], v[60:63], v[128:131], v[164:167]
	v_mfma_i32_16x16x64_i8 v[164:167], v[64:67], v[132:135], v[164:167]
	v_mfma_i32_16x16x64_i8 v[160:163], v[60:63], v[140:143], v[160:163]
	v_mfma_i32_16x16x64_i8 v[160:163], v[64:67], v[188:191], v[160:163]
	v_mfma_i32_16x16x64_i8 v[168:171], v[44:47], v[140:143], v[168:171]
	v_mfma_i32_16x16x64_i8 v[168:171], v[52:55], v[188:191], v[168:171]
	v_mfma_i32_16x16x64_i8 v[156:159], v[44:47], v[192:195], v[156:159]
	v_mfma_i32_16x16x64_i8 v[156:159], v[52:55], v[196:199], v[156:159]
	v_mfma_i32_16x16x64_i8 v[152:155], v[60:63], v[192:195], v[152:155]
	v_mfma_i32_16x16x64_i8 v[152:155], v[64:67], v[196:199], v[152:155]
	v_mfma_i32_16x16x64_i8 v[144:147], v[60:63], v[216:219], v[144:147]
	v_mfma_i32_16x16x64_i8 v[144:147], v[64:67], v[220:223], v[144:147]
	v_mfma_i32_16x16x64_i8 v[148:151], v[44:47], v[216:219], v[148:151]
	v_mfma_i32_16x16x64_i8 v[148:151], v[52:55], v[220:223], v[148:151]
	v_mfma_i32_16x16x64_i8 v[136:139], v[84:87], v[128:131], v[136:139]
	v_mfma_i32_16x16x64_i8 v[136:139], v[88:91], v[132:135], v[136:139]
	v_mfma_i32_16x16x64_i8 v[120:123], v[92:95], v[128:131], v[120:123]
	v_mfma_i32_16x16x64_i8 v[120:123], v[100:103], v[132:135], v[120:123]
	v_mfma_i32_16x16x64_i8 v[116:119], v[92:95], v[140:143], v[116:119]
	v_mfma_i32_16x16x64_i8 v[116:119], v[100:103], v[188:191], v[116:119]
	v_mfma_i32_16x16x64_i8 v[124:127], v[84:87], v[140:143], v[124:127]
	v_mfma_i32_16x16x64_i8 v[132:135], v[88:91], v[188:191], v[124:127]
	v_mfma_i32_16x16x64_i8 v[112:115], v[84:87], v[192:195], v[112:115]
	v_mfma_i32_16x16x64_i8 v[112:115], v[88:91], v[196:199], v[112:115]
	v_mfma_i32_16x16x64_i8 v[108:111], v[92:95], v[192:195], v[108:111]
	v_mfma_i32_16x16x64_i8 v[108:111], v[100:103], v[196:199], v[108:111]
	v_mfma_i32_16x16x64_i8 v[96:99], v[92:95], v[216:219], v[96:99]
	v_mfma_i32_16x16x64_i8 v[96:99], v[100:103], v[220:223], v[96:99]
	v_mfma_i32_16x16x64_i8 v[104:107], v[84:87], v[216:219], v[104:107]
	v_mfma_i32_16x16x64_i8 v[104:107], v[88:91], v[220:223], v[104:107]
	s_barrier
; #define PG8_STAGE(bufoff, gbase, voff) do { _Pragma("unroll") for (int _i = 0; _i < 2; ++_i) \
;         __builtin_amdgcn_global_load_lds((const unsigned*)((const char*)(gbase) + (voff)[_i]), (PG8_LAS unsigned*)(lds + (bufoff) + ldsw + _i * 8192), 16, 0, 0); } while (0)
; #define PG8_LDA(dst, b, h) do { _Pragma("unroll") for (int m = 0; m < 4; ++m) _Pragma("unroll") for (int k = 0; k < 2; ++k) dst[m][k] = *(const PG8_LAS bf16x8*)(lds + PG8_SA(b, h) + aoff + m * 2048 + k * 1024); } while (0)
; #define PG8_MMA(ai, bj, At, Bt) do { __builtin_amdgcn_s_setprio(1); _Pragma("unroll") for (int m = 0; m < 4; ++m) _Pragma("unroll") for (int n = 0; n < 2; ++n) _Pragma("unroll") for (int k = 0; k < 2; ++k) \
;         acc[ai][bj][m][n] = mma16<Epi::I8>(Bt[n][k], At[m][k], acc[ai][bj][m][n]); __builtin_amdgcn_s_setprio(0); } while (0)
; #define PG8_WAIT_V(n) asm volatile("s_waitcnt vmcnt(" #n ")" ::: "memory")
; #define PG8_WAIT_L(n) asm volatile("s_waitcnt lgkmcnt(" #n ")" ::: "memory")
; #define PG8_BAR __builtin_amdgcn_s_barrier()
; #define PG8_SCHED __builtin_amdgcn_sched_barrier(0)
; template <class Epi, class Sched, bool ALIGN_EPI = false, bool SP2 = false>
; __device__ __forceinline__ void gemm_phase(PG8_LAS unsigned char* lds, const Gemm g, const Sched& S, const Epi& E) {
;     ...
;         for (int t = 0; t < nt; t += 2) {
;     ...
;             PG8_LDA(At, 1, 1); PG8_STAGE(PG8_SB(1, 0), b3, voffB); PG8_STAGE(PG8_SB(1, 1), b3 + hstep, voffB); PG8_STAGE(PG8_SA(1, 0), a3, voffA);
;             PG8_WAIT_V(8); PG8_WAIT_L(0); PG8_BAR; PG8_MMA(1, 0, At, B0); PG8_MMA(1, 1, At, B1); PG8_BAR; PG8_SCHED;
	s_add_i32 s8, s10, s12
	v_lshl_add_u64 v[6:7], v[200:201], 0, s[92:93]
	s_mov_b32 m0, s8
	ds_read_b128 v[124:127], v215 offset:49152
	ds_read_b128 v[128:131], v215 offset:50176
	ds_read_b128 v[140:143], v215 offset:51200
	ds_read_b128 v[188:191], v215 offset:52224
	ds_read_b128 v[192:195], v215 offset:53248
	ds_read_b128 v[196:199], v215 offset:54272
	ds_read_b128 v[216:219], v215 offset:55296
	ds_read_b128 v[220:223], v215 offset:56320
	global_load_lds_dwordx4 v[6:7], off
	s_add_i32 m0, s8, 0x2000
	s_add_u32 s8, s82, 0x40080
	v_lshl_add_u64 v[6:7], v[206:207], 0, s[92:93]
	s_addc_u32 s9, s83, 0
	s_add_i32 s10, s11, s12
	global_load_lds_dwordx4 v[6:7], off
	v_lshl_add_u64 v[6:7], s[8:9], 0, v[178:179]
	s_mov_b32 m0, s10
	s_nop 0
	global_load_lds_dwordx4 v[6:7], off
	v_lshl_add_u64 v[6:7], s[8:9], 0, v[182:183]
	s_add_i32 m0, s10, 0x2000
	s_nop 0
	global_load_lds_dwordx4 v[6:7], off
	v_lshl_add_u64 v[6:7], v[210:211], 0, s[92:93]
	s_mov_b32 m0, s58
	s_nop 0
	global_load_lds_dwordx4 v[6:7], off
	v_lshl_add_u64 v[6:7], v[224:225], 0, s[92:93]
	s_mov_b32 m0, s4
	s_nop 0
	global_load_lds_dwordx4 v[6:7], off
	s_waitcnt vmcnt(8)
	s_waitcnt lgkmcnt(0)
	s_barrier
	s_waitcnt lgkmcnt(0)
	v_mfma_i32_16x16x64_i8 v[80:83], v[44:47], v[124:127], v[80:83]
	v_mfma_i32_16x16x64_i8 v[80:83], v[52:55], v[128:131], v[80:83]
	v_mfma_i32_16x16x64_i8 v[72:75], v[60:63], v[124:127], v[72:75]
	v_mfma_i32_16x16x64_i8 v[72:75], v[64:67], v[128:131], v[72:75]
	v_mfma_i32_16x16x64_i8 v[68:71], v[60:63], v[140:143], v[68:71]
	v_mfma_i32_16x16x64_i8 v[68:71], v[64:67], v[188:191], v[68:71]
	v_mfma_i32_16x16x64_i8 v[76:79], v[44:47], v[140:143], v[76:79]
	v_mfma_i32_16x16x64_i8 v[76:79], v[52:55], v[188:191], v[76:79]
	v_mfma_i32_16x16x64_i8 v[56:59], v[44:47], v[192:195], v[56:59]
	v_mfma_i32_16x16x64_i8 v[56:59], v[52:55], v[196:199], v[56:59]
	v_mfma_i32_16x16x64_i8 v[48:51], v[60:63], v[192:195], v[48:51]
	v_mfma_i32_16x16x64_i8 v[48:51], v[64:67], v[196:199], v[48:51]
	v_mfma_i32_16x16x64_i8 v[36:39], v[60:63], v[216:219], v[36:39]
	v_mfma_i32_16x16x64_i8 v[36:39], v[64:67], v[220:223], v[36:39]
	v_mfma_i32_16x16x64_i8 v[40:43], v[44:47], v[216:219], v[40:43]
	v_mfma_i32_16x16x64_i8 v[40:43], v[52:55], v[220:223], v[40:43]
	v_mfma_i32_16x16x64_i8 v[32:35], v[84:87], v[124:127], v[32:35]
	v_mfma_i32_16x16x64_i8 v[32:35], v[88:91], v[128:131], v[32:35]
	v_mfma_i32_16x16x64_i8 v[24:27], v[92:95], v[124:127], v[24:27]
	v_mfma_i32_16x16x64_i8 v[24:27], v[100:103], v[128:131], v[24:27]
	v_mfma_i32_16x16x64_i8 v[20:23], v[92:95], v[140:143], v[20:23]
	v_mfma_i32_16x16x64_i8 v[20:23], v[100:103], v[188:191], v[20:23]
	v_mfma_i32_16x16x64_i8 v[28:31], v[84:87], v[140:143], v[28:31]
	v_mfma_i32_16x16x64_i8 v[28:31], v[88:91], v[188:191], v[28:31]
	v_mfma_i32_16x16x64_i8 v[16:19], v[84:87], v[192:195], v[16:19]
	v_mfma_i32_16x16x64_i8 v[16:19], v[88:91], v[196:199], v[16:19]
	v_mfma_i32_16x16x64_i8 v[12:15], v[92:95], v[192:195], v[12:15]
	v_mfma_i32_16x16x64_i8 v[12:15], v[100:103], v[196:199], v[12:15]
	v_mfma_i32_16x16x64_i8 v[2:5], v[92:95], v[216:219], v[2:5]
	v_mfma_i32_16x16x64_i8 v[6:9], v[84:87], v[216:219], v[8:11]
	v_mfma_i32_16x16x64_i8 v[8:11], v[88:91], v[220:223], v[6:9]
	v_mfma_i32_16x16x64_i8 v[4:7], v[100:103], v[220:223], v[2:5]
	s_barrier
	s_add_i32 s5, s5, 2
	s_add_u32 s85, s85, 0x100
	s_addc_u32 s68, s68, 0
	s_cmp_gt_u32 s5, 13
	s_mov_b64 s[8:9], s[70:71]
	s_cbranch_scc0 .LBB0_385
